# v16
# speedup vs baseline: 1.0282x; 1.0052x over previous
; #define WAIT_V(n) asm volatile("s_waitcnt vmcnt(" #n ")" ::: "memory")
; #define WAIT_L(n) asm volatile("s_waitcnt lgkmcnt(" #n ")" ::: "memory")
; #define BAR __builtin_amdgcn_s_barrier()
; #define SCHED __builtin_amdgcn_sched_barrier(0)
; __device__ __forceinline__ void mainloop_8phase(const u16* __restrict__ A, const u16* __restrict__ Bt, int K,
;                                                 f32x4 (&acc)[2][2][4][2], int wid_s, int ld) {
;     ...
;     LDB(B0, 0, 0); SCHED; LDA(At, 0, 0); STAGE(SA(1, 1), A, brow + G_HALF, t + 1);
;     WAIT_L(8); BAR; WAIT_L(0); MMA(0, 0, At, B0); BAR; SCHED;
;     LDB(B1, 0, 1); STAGE(SB(0, 0), Bt, bcol, t + 2);
;     BAR; WAIT_L(0); MMA(0, 1, At, B1); BAR;
;     LDA(At, 0, 1); STAGE(SA(0, 0), A, brow, t + 2);
;     BAR; WAIT_L(0); MMA(1, 0, At, B0); BAR; SCHED;
;     STAGE(SB(0, 1), Bt, bcol + G_HALF, t + 2);
;     WAIT_V(6); BAR; MMA(1, 1, At, B1); BAR;
.LBB0_58:
	ds_read_b128 v[156:159], v155
	ds_read_b128 v[160:163], v155 offset:1024
	ds_read_b128 v[164:167], v155 offset:2048
	ds_read_b128 v[168:171], v155 offset:3072
	s_add_i32 s6, s1, 0xffffff00
	s_add_i32 m0, s100, 0xc000
	ds_read_b128 v[172:175], v133
	ds_read_b128 v[176:179], v133 offset:1024
	ds_read_b128 v[180:183], v132
	ds_read_b128 v[184:187], v132 offset:1024
	ds_read_b128 v[188:191], v131
	ds_read_b128 v[192:195], v131 offset:1024
	ds_read_b128 v[196:199], v130
	buffer_load_dwordx4 v137, s[88:91], s6 offen lds
	s_add_i32 m0, s100, 0xe000
	ds_read_b128 v[200:203], v130 offset:1024
	buffer_load_dwordx4 v136, s[88:91], s6 offen lds
	s_waitcnt lgkmcnt(8)
	s_barrier
	s_waitcnt lgkmcnt(1)
	v_mfma_f32_16x16x32_bf16 v[126:129], v[172:175], v[156:159], v[126:129]
	v_mfma_f32_16x16x32_bf16 v[122:125], v[172:175], v[164:167], v[122:125]
	v_mfma_f32_16x16x32_bf16 v[118:121], v[180:183], v[156:159], v[118:121]
	v_mfma_f32_16x16x32_bf16 v[114:117], v[180:183], v[164:167], v[114:117]
	v_mfma_f32_16x16x32_bf16 v[110:113], v[188:191], v[156:159], v[110:113]
	v_mfma_f32_16x16x32_bf16 v[106:109], v[188:191], v[164:167], v[106:109]
	v_mfma_f32_16x16x32_bf16 v[102:105], v[196:199], v[156:159], v[102:105]
	v_mfma_f32_16x16x32_bf16 v[98:101], v[196:199], v[164:167], v[98:101]
	v_mfma_f32_16x16x32_bf16 v[126:129], v[176:179], v[160:163], v[126:129]
	v_mfma_f32_16x16x32_bf16 v[122:125], v[176:179], v[168:171], v[122:125]
	v_mfma_f32_16x16x32_bf16 v[118:121], v[184:187], v[160:163], v[118:121]
	v_mfma_f32_16x16x32_bf16 v[114:117], v[184:187], v[168:171], v[114:117]
	v_mfma_f32_16x16x32_bf16 v[110:113], v[192:195], v[160:163], v[110:113]
	v_mfma_f32_16x16x32_bf16 v[106:109], v[192:195], v[168:171], v[106:109]
	s_waitcnt lgkmcnt(0)
	v_mfma_f32_16x16x32_bf16 v[102:105], v[200:203], v[160:163], v[102:105]
	v_mfma_f32_16x16x32_bf16 v[98:101], v[200:203], v[168:171], v[98:101]
	s_barrier
	s_add_i32 s15, s1, 0xfff7ff80
	s_mov_b32 s6, s90
	s_add_i32 m0, s100, 0x10000
	ds_read_b128 v[204:207], v147
	ds_read_b128 v[208:211], v147 offset:1024
	ds_read_b128 v[212:215], v147 offset:2048
	buffer_load_dwordx4 v137, s[4:7], s15 offen lds
	s_add_i32 m0, s100, 0x12000
	ds_read_b128 v[216:219], v147 offset:3072
	buffer_load_dwordx4 v136, s[4:7], s15 offen lds
	s_barrier
	s_waitcnt lgkmcnt(1)
	v_mfma_f32_16x16x32_bf16 v[94:97], v[172:175], v[204:207], v[94:97]
	v_mfma_f32_16x16x32_bf16 v[90:93], v[172:175], v[212:215], v[90:93]
	v_mfma_f32_16x16x32_bf16 v[86:89], v[180:183], v[204:207], v[86:89]
	v_mfma_f32_16x16x32_bf16 v[82:85], v[180:183], v[212:215], v[82:85]
	v_mfma_f32_16x16x32_bf16 v[78:81], v[188:191], v[204:207], v[78:81]
	v_mfma_f32_16x16x32_bf16 v[74:77], v[188:191], v[212:215], v[74:77]
	v_mfma_f32_16x16x32_bf16 v[70:73], v[196:199], v[204:207], v[70:73]
	v_mfma_f32_16x16x32_bf16 v[66:69], v[196:199], v[212:215], v[66:69]
	v_mfma_f32_16x16x32_bf16 v[94:97], v[176:179], v[208:211], v[94:97]
	s_waitcnt lgkmcnt(0)
	v_mfma_f32_16x16x32_bf16 v[90:93], v[176:179], v[216:219], v[90:93]
	v_mfma_f32_16x16x32_bf16 v[86:89], v[184:187], v[208:211], v[86:89]
	v_mfma_f32_16x16x32_bf16 v[82:85], v[184:187], v[216:219], v[82:85]
	v_mfma_f32_16x16x32_bf16 v[78:81], v[192:195], v[208:211], v[78:81]
	v_mfma_f32_16x16x32_bf16 v[74:77], v[192:195], v[216:219], v[74:77]
	v_mfma_f32_16x16x32_bf16 v[70:73], v[200:203], v[208:211], v[70:73]
	v_mfma_f32_16x16x32_bf16 v[66:69], v[200:203], v[216:219], v[66:69]
	s_mov_b32 m0, s100
	s_barrier
	ds_read_b128 v[172:175], v133 offset:16384
	ds_read_b128 v[176:179], v133 offset:17408
	ds_read_b128 v[180:183], v132 offset:16384
	ds_read_b128 v[184:187], v132 offset:17408
	ds_read_b128 v[188:191], v131 offset:16384
	ds_read_b128 v[192:195], v131 offset:17408
	ds_read_b128 v[196:199], v130 offset:16384
	buffer_load_dwordx4 v137, s[88:91], s15 offen lds
	s_add_i32 m0, s100, 0x2000
	ds_read_b128 v[200:203], v130 offset:17408
	buffer_load_dwordx4 v136, s[88:91], s15 offen lds
	s_barrier
	s_waitcnt lgkmcnt(1)
	v_mfma_f32_16x16x32_bf16 v[62:65], v[172:175], v[156:159], v[62:65]
	v_mfma_f32_16x16x32_bf16 v[58:61], v[172:175], v[164:167], v[58:61]
	v_mfma_f32_16x16x32_bf16 v[54:57], v[180:183], v[156:159], v[54:57]
	v_mfma_f32_16x16x32_bf16 v[50:53], v[180:183], v[164:167], v[50:53]
	v_mfma_f32_16x16x32_bf16 v[46:49], v[188:191], v[156:159], v[46:49]
	v_mfma_f32_16x16x32_bf16 v[42:45], v[188:191], v[164:167], v[42:45]
	v_mfma_f32_16x16x32_bf16 v[38:41], v[196:199], v[156:159], v[38:41]
	v_mfma_f32_16x16x32_bf16 v[34:37], v[196:199], v[164:167], v[34:37]
	v_mfma_f32_16x16x32_bf16 v[62:65], v[176:179], v[160:163], v[62:65]
	v_mfma_f32_16x16x32_bf16 v[58:61], v[176:179], v[168:171], v[58:61]
	v_mfma_f32_16x16x32_bf16 v[54:57], v[184:187], v[160:163], v[54:57]
	v_mfma_f32_16x16x32_bf16 v[50:53], v[184:187], v[168:171], v[50:53]
	v_mfma_f32_16x16x32_bf16 v[46:49], v[192:195], v[160:163], v[46:49]
	v_mfma_f32_16x16x32_bf16 v[42:45], v[192:195], v[168:171], v[42:45]
	s_waitcnt lgkmcnt(0)
	v_mfma_f32_16x16x32_bf16 v[38:41], v[200:203], v[160:163], v[38:41]
	v_mfma_f32_16x16x32_bf16 v[34:37], v[200:203], v[168:171], v[34:37]
	s_barrier
	s_add_i32 s15, s1, 0xffffff80
	s_add_i32 m0, s100, 0x14000
	buffer_load_dwordx4 v137, s[4:7], s15 offen lds
	s_add_i32 m0, s100, 0x16000
	s_nop 0
	buffer_load_dwordx4 v136, s[4:7], s15 offen lds
	s_waitcnt vmcnt(6)
	s_barrier
; #define WAIT_V(n) asm volatile("s_waitcnt vmcnt(" #n ")" ::: "memory")
; #define WAIT_L(n) asm volatile("s_waitcnt lgkmcnt(" #n ")" ::: "memory")
; #define BAR __builtin_amdgcn_s_barrier()
; #define SCHED __builtin_amdgcn_sched_barrier(0)
; __device__ __forceinline__ void mainloop_8phase(const u16* __restrict__ A, const u16* __restrict__ Bt, int K,
;                                                 f32x4 (&acc)[2][2][4][2], int wid_s, int ld) {
;     ...
;     LDB(B0, 1, 0); SCHED; LDA(At, 1, 0); STAGE(SA(0, 1), A, brow + G_HALF, t + 2);
;     WAIT_L(8); BAR; WAIT_L(0); MMA(0, 0, At, B0); BAR; SCHED;
;     LDB(B1, 1, 1); STAGE(SB(1, 0), Bt, bcol, t + 3);
;     BAR; WAIT_L(0); MMA(0, 1, At, B1); BAR;
;     LDA(At, 1, 1); STAGE(SA(1, 0), A, brow, t + 3);
;     BAR; WAIT_L(0); MMA(1, 0, At, B0); BAR; SCHED;
;     STAGE(SB(1, 1), Bt, bcol + G_HALF, t + 3);
;     WAIT_V(6); BAR; MMA(1, 1, At, B1); BAR;
	v_mfma_f32_16x16x32_bf16 v[30:33], v[172:175], v[204:207], v[30:33]
	v_mfma_f32_16x16x32_bf16 v[26:29], v[172:175], v[212:215], v[26:29]
	v_mfma_f32_16x16x32_bf16 v[22:25], v[180:183], v[204:207], v[22:25]
	v_mfma_f32_16x16x32_bf16 v[18:21], v[180:183], v[212:215], v[18:21]
	v_mfma_f32_16x16x32_bf16 v[14:17], v[188:191], v[204:207], v[14:17]
	v_mfma_f32_16x16x32_bf16 v[10:13], v[188:191], v[212:215], v[10:13]
	v_mfma_f32_16x16x32_bf16 v[6:9], v[196:199], v[204:207], v[6:9]
	v_mfma_f32_16x16x32_bf16 v[2:5], v[196:199], v[212:215], v[2:5]
	v_mfma_f32_16x16x32_bf16 v[30:33], v[176:179], v[208:211], v[30:33]
	v_mfma_f32_16x16x32_bf16 v[26:29], v[176:179], v[216:219], v[26:29]
	v_mfma_f32_16x16x32_bf16 v[22:25], v[184:187], v[208:211], v[22:25]
	v_mfma_f32_16x16x32_bf16 v[18:21], v[184:187], v[216:219], v[18:21]
	v_mfma_f32_16x16x32_bf16 v[14:17], v[192:195], v[208:211], v[14:17]
	v_mfma_f32_16x16x32_bf16 v[10:13], v[192:195], v[216:219], v[10:13]
	v_mfma_f32_16x16x32_bf16 v[6:9], v[200:203], v[208:211], v[6:9]
	v_mfma_f32_16x16x32_bf16 v[2:5], v[200:203], v[216:219], v[2:5]
	s_barrier
	ds_read_b128 v[156:159], v135
	ds_read_b128 v[160:163], v135 offset:1024
	ds_read_b128 v[164:167], v135 offset:2048
	ds_read_b128 v[168:171], v135 offset:3072
	s_add_i32 m0, s100, 0x4000
	ds_read_b128 v[172:175], v133 offset:32768
	ds_read_b128 v[176:179], v133 offset:33792
	ds_read_b128 v[180:183], v132 offset:32768
	ds_read_b128 v[184:187], v132 offset:33792
	ds_read_b128 v[188:191], v131 offset:32768
	ds_read_b128 v[192:195], v131 offset:33792
	ds_read_b128 v[196:199], v130 offset:32768
	buffer_load_dwordx4 v137, s[88:91], s15 offen lds
	s_add_i32 m0, s100, 0x6000
	ds_read_b128 v[200:203], v130 offset:33792
	buffer_load_dwordx4 v136, s[88:91], s15 offen lds
	s_waitcnt lgkmcnt(8)
	s_barrier
	s_waitcnt lgkmcnt(1)
	v_mfma_f32_16x16x32_bf16 v[126:129], v[172:175], v[156:159], v[126:129]
	v_mfma_f32_16x16x32_bf16 v[122:125], v[172:175], v[164:167], v[122:125]
	v_mfma_f32_16x16x32_bf16 v[118:121], v[180:183], v[156:159], v[118:121]
	v_mfma_f32_16x16x32_bf16 v[114:117], v[180:183], v[164:167], v[114:117]
	v_mfma_f32_16x16x32_bf16 v[110:113], v[188:191], v[156:159], v[110:113]
	v_mfma_f32_16x16x32_bf16 v[106:109], v[188:191], v[164:167], v[106:109]
	v_mfma_f32_16x16x32_bf16 v[102:105], v[196:199], v[156:159], v[102:105]
	v_mfma_f32_16x16x32_bf16 v[98:101], v[196:199], v[164:167], v[98:101]
	v_mfma_f32_16x16x32_bf16 v[126:129], v[176:179], v[160:163], v[126:129]
	v_mfma_f32_16x16x32_bf16 v[122:125], v[176:179], v[168:171], v[122:125]
	v_mfma_f32_16x16x32_bf16 v[118:121], v[184:187], v[160:163], v[118:121]
	v_mfma_f32_16x16x32_bf16 v[114:117], v[184:187], v[168:171], v[114:117]
	v_mfma_f32_16x16x32_bf16 v[110:113], v[192:195], v[160:163], v[110:113]
	v_mfma_f32_16x16x32_bf16 v[106:109], v[192:195], v[168:171], v[106:109]
	s_waitcnt lgkmcnt(0)
	v_mfma_f32_16x16x32_bf16 v[102:105], v[200:203], v[160:163], v[102:105]
	v_mfma_f32_16x16x32_bf16 v[98:101], v[200:203], v[168:171], v[98:101]
	s_barrier
	s_add_i32 s15, s1, 0xfff80000
	s_add_i32 m0, s100, 0x18000
	ds_read_b128 v[204:207], v134
	ds_read_b128 v[208:211], v134 offset:1024
	ds_read_b128 v[212:215], v134 offset:2048
	buffer_load_dwordx4 v137, s[4:7], s15 offen lds
	s_add_i32 m0, s100, 0x1a000
	ds_read_b128 v[216:219], v134 offset:3072
	buffer_load_dwordx4 v136, s[4:7], s15 offen lds
	s_barrier
	s_waitcnt lgkmcnt(1)
	v_mfma_f32_16x16x32_bf16 v[94:97], v[172:175], v[204:207], v[94:97]
	v_mfma_f32_16x16x32_bf16 v[90:93], v[172:175], v[212:215], v[90:93]
	v_mfma_f32_16x16x32_bf16 v[86:89], v[180:183], v[204:207], v[86:89]
	v_mfma_f32_16x16x32_bf16 v[82:85], v[180:183], v[212:215], v[82:85]
	v_mfma_f32_16x16x32_bf16 v[78:81], v[188:191], v[204:207], v[78:81]
	v_mfma_f32_16x16x32_bf16 v[74:77], v[188:191], v[212:215], v[74:77]
	v_mfma_f32_16x16x32_bf16 v[70:73], v[196:199], v[204:207], v[70:73]
	v_mfma_f32_16x16x32_bf16 v[66:69], v[196:199], v[212:215], v[66:69]
	v_mfma_f32_16x16x32_bf16 v[94:97], v[176:179], v[208:211], v[94:97]
	s_waitcnt lgkmcnt(0)
	v_mfma_f32_16x16x32_bf16 v[90:93], v[176:179], v[216:219], v[90:93]
	v_mfma_f32_16x16x32_bf16 v[86:89], v[184:187], v[208:211], v[86:89]
	v_mfma_f32_16x16x32_bf16 v[82:85], v[184:187], v[216:219], v[82:85]
	v_mfma_f32_16x16x32_bf16 v[78:81], v[192:195], v[208:211], v[78:81]
	v_mfma_f32_16x16x32_bf16 v[74:77], v[192:195], v[216:219], v[74:77]
	v_mfma_f32_16x16x32_bf16 v[70:73], v[200:203], v[208:211], v[70:73]
	v_mfma_f32_16x16x32_bf16 v[66:69], v[200:203], v[216:219], v[66:69]
	s_add_i32 m0, s100, 0x8000
	s_barrier
	ds_read_b128 v[172:175], v133 offset:49152
	ds_read_b128 v[176:179], v133 offset:50176
	ds_read_b128 v[180:183], v132 offset:49152
	ds_read_b128 v[184:187], v132 offset:50176
	ds_read_b128 v[188:191], v131 offset:49152
	ds_read_b128 v[192:195], v131 offset:50176
	ds_read_b128 v[196:199], v130 offset:49152
	buffer_load_dwordx4 v137, s[88:91], s15 offen lds
	s_add_i32 m0, s100, 0xa000
	ds_read_b128 v[200:203], v130 offset:50176
	buffer_load_dwordx4 v136, s[88:91], s15 offen lds
	s_barrier
	s_waitcnt lgkmcnt(1)
	v_mfma_f32_16x16x32_bf16 v[62:65], v[172:175], v[156:159], v[62:65]
	v_mfma_f32_16x16x32_bf16 v[58:61], v[172:175], v[164:167], v[58:61]
	v_mfma_f32_16x16x32_bf16 v[54:57], v[180:183], v[156:159], v[54:57]
	v_mfma_f32_16x16x32_bf16 v[50:53], v[180:183], v[164:167], v[50:53]
	v_mfma_f32_16x16x32_bf16 v[46:49], v[188:191], v[156:159], v[46:49]
	v_mfma_f32_16x16x32_bf16 v[42:45], v[188:191], v[164:167], v[42:45]
	v_mfma_f32_16x16x32_bf16 v[38:41], v[196:199], v[156:159], v[38:41]
	v_mfma_f32_16x16x32_bf16 v[34:37], v[196:199], v[164:167], v[34:37]
	v_mfma_f32_16x16x32_bf16 v[62:65], v[176:179], v[160:163], v[62:65]
	v_mfma_f32_16x16x32_bf16 v[58:61], v[176:179], v[168:171], v[58:61]
	v_mfma_f32_16x16x32_bf16 v[54:57], v[184:187], v[160:163], v[54:57]
	v_mfma_f32_16x16x32_bf16 v[50:53], v[184:187], v[168:171], v[50:53]
	v_mfma_f32_16x16x32_bf16 v[46:49], v[192:195], v[160:163], v[46:49]
	v_mfma_f32_16x16x32_bf16 v[42:45], v[192:195], v[168:171], v[42:45]
	s_waitcnt lgkmcnt(0)
	v_mfma_f32_16x16x32_bf16 v[38:41], v[200:203], v[160:163], v[38:41]
	v_mfma_f32_16x16x32_bf16 v[34:37], v[200:203], v[168:171], v[34:37]
	s_barrier
; #define WAIT_V(n) asm volatile("s_waitcnt vmcnt(" #n ")" ::: "memory")
; #define WAIT_L(n) asm volatile("s_waitcnt lgkmcnt(" #n ")" ::: "memory")
; #define BAR __builtin_amdgcn_s_barrier()
; __device__ __forceinline__ void mainloop_8phase(const u16* __restrict__ A, const u16* __restrict__ Bt, int K,
;                                                 f32x4 (&acc)[2][2][4][2], int wid_s, int ld) {
;     ...
;     WAIT_V(6); BAR; MMA(1, 1, At, B1); BAR;
;   }
;   { LDB(B0, 0, 0); LDA(At, 0, 0); STAGE(SA(1, 1), A, brow + G_HALF, nt - 1);
;     BAR; WAIT_L(0); MMA(0, 0, At, B0); BAR;
;     LDB(B1, 0, 1); BAR; WAIT_L(0); MMA(0, 1, At, B1); BAR;
;     LDA(At, 0, 1); WAIT_V(4); BAR; WAIT_L(0); MMA(1, 0, At, B0); MMA(1, 1, At, B1); BAR; }
	s_add_i32 m0, s100, 0x1c000
	buffer_load_dwordx4 v137, s[4:7], s1 offen lds
	s_add_i32 m0, s100, 0x1e000
	s_nop 0
	buffer_load_dwordx4 v136, s[4:7], s1 offen lds
	s_waitcnt vmcnt(6)
	s_barrier
	v_mfma_f32_16x16x32_bf16 v[30:33], v[172:175], v[204:207], v[30:33]
	v_mfma_f32_16x16x32_bf16 v[26:29], v[172:175], v[212:215], v[26:29]
	v_mfma_f32_16x16x32_bf16 v[22:25], v[180:183], v[204:207], v[22:25]
	v_mfma_f32_16x16x32_bf16 v[18:21], v[180:183], v[212:215], v[18:21]
	v_mfma_f32_16x16x32_bf16 v[14:17], v[188:191], v[204:207], v[14:17]
	v_mfma_f32_16x16x32_bf16 v[10:13], v[188:191], v[212:215], v[10:13]
	v_mfma_f32_16x16x32_bf16 v[6:9], v[196:199], v[204:207], v[6:9]
	v_mfma_f32_16x16x32_bf16 v[2:5], v[196:199], v[212:215], v[2:5]
	v_mfma_f32_16x16x32_bf16 v[30:33], v[176:179], v[208:211], v[30:33]
	v_mfma_f32_16x16x32_bf16 v[26:29], v[176:179], v[216:219], v[26:29]
	v_mfma_f32_16x16x32_bf16 v[22:25], v[184:187], v[208:211], v[22:25]
	v_mfma_f32_16x16x32_bf16 v[18:21], v[184:187], v[216:219], v[18:21]
	v_mfma_f32_16x16x32_bf16 v[14:17], v[192:195], v[208:211], v[14:17]
	v_mfma_f32_16x16x32_bf16 v[10:13], v[192:195], v[216:219], v[10:13]
	v_mfma_f32_16x16x32_bf16 v[6:9], v[200:203], v[208:211], v[6:9]
	v_mfma_f32_16x16x32_bf16 v[2:5], v[200:203], v[216:219], v[2:5]
	s_add_i32 s0, s0, 2
	s_addk_i32 s1, 0x100
	s_cmp_lt_u32 s0, 28
	s_barrier
	s_cbranch_scc1 .LBB0_58
	v_readfirstlane_b32 s0, v145
	s_mov_b32 m0, s0
	s_mov_b32 s1, 0x80f80
	v_readfirstlane_b32 s0, v144
	ds_read_b128 v[138:141], v155
	ds_read_b128 v[148:151], v155 offset:1024
	ds_read_b128 v[156:159], v155 offset:2048
	ds_read_b128 v[152:155], v155 offset:3072
	ds_read_b128 v[160:163], v133
	ds_read_b128 v[164:167], v133 offset:1024
	ds_read_b128 v[168:171], v132
	ds_read_b128 v[172:175], v132 offset:1024
	ds_read_b128 v[176:179], v131
	ds_read_b128 v[180:183], v131 offset:1024
	ds_read_b128 v[184:187], v130
	ds_read_b128 v[188:191], v130 offset:1024
	buffer_load_dwordx4 v137, s[88:91], s1 offen lds
	s_mov_b32 m0, s0
	s_nop 0
	buffer_load_dwordx4 v136, s[88:91], s1 offen lds
	s_barrier
	s_waitcnt lgkmcnt(0)
	v_mfma_f32_16x16x32_bf16 v[126:129], v[160:163], v[138:141], v[126:129]
	v_mfma_f32_16x16x32_bf16 v[122:125], v[160:163], v[156:159], v[122:125]
	v_mfma_f32_16x16x32_bf16 v[118:121], v[168:171], v[138:141], v[118:121]
	v_mfma_f32_16x16x32_bf16 v[114:117], v[168:171], v[156:159], v[114:117]
	v_mfma_f32_16x16x32_bf16 v[102:105], v[184:187], v[138:141], v[102:105]
	v_mfma_f32_16x16x32_bf16 v[98:101], v[184:187], v[156:159], v[98:101]
	v_mfma_f32_16x16x32_bf16 v[126:129], v[164:167], v[148:151], v[126:129]
	v_mfma_f32_16x16x32_bf16 v[122:125], v[164:167], v[152:155], v[122:125]
	v_mfma_f32_16x16x32_bf16 v[118:121], v[172:175], v[148:151], v[118:121]
	v_mfma_f32_16x16x32_bf16 v[114:117], v[172:175], v[152:155], v[114:117]
	v_mfma_f32_16x16x32_bf16 v[110:113], v[176:179], v[138:141], v[110:113]
	v_mfma_f32_16x16x32_bf16 v[106:109], v[176:179], v[156:159], v[106:109]
	v_mfma_f32_16x16x32_bf16 v[102:105], v[188:191], v[148:151], v[102:105]
	v_mfma_f32_16x16x32_bf16 v[98:101], v[188:191], v[152:155], v[98:101]
	v_mfma_f32_16x16x32_bf16 v[142:145], v[180:183], v[148:151], v[110:113]
	v_mfma_f32_16x16x32_bf16 v[192:195], v[180:183], v[152:155], v[106:109]
	s_barrier
	s_nop 0
	ds_read_b128 v[106:109], v147
	ds_read_b128 v[110:113], v147 offset:1024
	ds_read_b128 v[196:199], v147 offset:2048
	ds_read_b128 v[200:203], v147 offset:3072
	s_barrier
	s_waitcnt lgkmcnt(0)
	v_mfma_f32_16x16x32_bf16 v[86:89], v[168:171], v[106:109], v[86:89]
	v_mfma_f32_16x16x32_bf16 v[82:85], v[168:171], v[196:199], v[82:85]
	v_mfma_f32_16x16x32_bf16 v[70:73], v[184:187], v[106:109], v[70:73]
	v_mfma_f32_16x16x32_bf16 v[66:69], v[184:187], v[196:199], v[66:69]
	v_mfma_f32_16x16x32_bf16 v[94:97], v[160:163], v[106:109], v[94:97]
	v_mfma_f32_16x16x32_bf16 v[90:93], v[160:163], v[196:199], v[90:93]
	v_mfma_f32_16x16x32_bf16 v[86:89], v[172:175], v[110:113], v[86:89]
	v_mfma_f32_16x16x32_bf16 v[82:85], v[172:175], v[200:203], v[82:85]
	v_mfma_f32_16x16x32_bf16 v[78:81], v[176:179], v[106:109], v[78:81]
	v_mfma_f32_16x16x32_bf16 v[74:77], v[176:179], v[196:199], v[74:77]
	v_mfma_f32_16x16x32_bf16 v[70:73], v[188:191], v[110:113], v[70:73]
	v_mfma_f32_16x16x32_bf16 v[66:69], v[188:191], v[200:203], v[66:69]
	v_mfma_f32_16x16x32_bf16 v[204:207], v[164:167], v[110:113], v[94:97]
	v_mfma_f32_16x16x32_bf16 v[160:163], v[164:167], v[200:203], v[90:93]
	v_mfma_f32_16x16x32_bf16 v[164:167], v[180:183], v[110:113], v[78:81]
	v_mfma_f32_16x16x32_bf16 v[168:171], v[180:183], v[200:203], v[74:77]
	s_barrier
	s_nop 0
	ds_read_b128 v[74:77], v133 offset:16384
	ds_read_b128 v[78:81], v133 offset:17408
	ds_read_b128 v[90:93], v132 offset:16384
	ds_read_b128 v[94:97], v132 offset:17408
	ds_read_b128 v[172:175], v131 offset:16384
	ds_read_b128 v[176:179], v131 offset:17408
	ds_read_b128 v[180:183], v130 offset:16384
	ds_read_b128 v[184:187], v130 offset:17408
	s_waitcnt vmcnt(4)
	s_barrier
; #define WAIT_V(n) asm volatile("s_waitcnt vmcnt(" #n ")" ::: "memory")
; #define WAIT_L(n) asm volatile("s_waitcnt lgkmcnt(" #n ")" ::: "memory")
; #define BAR __builtin_amdgcn_s_barrier()
; __device__ __forceinline__ void mainloop_8phase(const u16* __restrict__ A, const u16* __restrict__ Bt, int K,
;                                                 f32x4 (&acc)[2][2][4][2], int wid_s, int ld) {
;     ...
;     LDA(At, 0, 1); WAIT_V(4); BAR; WAIT_L(0); MMA(1, 0, At, B0); MMA(1, 1, At, B1); BAR; }
;   { LDB(B0, 1, 0); LDA(At, 1, 0); WAIT_V(2); BAR; WAIT_L(0); MMA(0, 0, At, B0); BAR;
	s_waitcnt lgkmcnt(0)
	v_mfma_f32_16x16x32_bf16 v[62:65], v[74:77], v[138:141], v[62:65]
	v_mfma_f32_16x16x32_bf16 v[58:61], v[74:77], v[156:159], v[58:61]
	v_mfma_f32_16x16x32_bf16 v[54:57], v[90:93], v[138:141], v[54:57]
	v_mfma_f32_16x16x32_bf16 v[50:53], v[90:93], v[156:159], v[50:53]
	v_mfma_f32_16x16x32_bf16 v[38:41], v[180:183], v[138:141], v[38:41]
	v_mfma_f32_16x16x32_bf16 v[34:37], v[180:183], v[156:159], v[34:37]
	v_mfma_f32_16x16x32_bf16 v[62:65], v[78:81], v[148:151], v[62:65]
	v_mfma_f32_16x16x32_bf16 v[58:61], v[78:81], v[152:155], v[58:61]
	v_mfma_f32_16x16x32_bf16 v[54:57], v[94:97], v[148:151], v[54:57]
	v_mfma_f32_16x16x32_bf16 v[50:53], v[94:97], v[152:155], v[50:53]
	v_mfma_f32_16x16x32_bf16 v[46:49], v[172:175], v[138:141], v[46:49]
	v_mfma_f32_16x16x32_bf16 v[42:45], v[172:175], v[156:159], v[42:45]
	v_mfma_f32_16x16x32_bf16 v[38:41], v[184:187], v[148:151], v[38:41]
	v_mfma_f32_16x16x32_bf16 v[34:37], v[184:187], v[152:155], v[34:37]
	v_mfma_f32_16x16x32_bf16 v[188:191], v[176:179], v[148:151], v[46:49]
	v_mfma_f32_16x16x32_bf16 v[208:211], v[176:179], v[152:155], v[42:45]
	v_mfma_f32_16x16x32_bf16 v[22:25], v[90:93], v[106:109], v[22:25]
	v_mfma_f32_16x16x32_bf16 v[18:21], v[90:93], v[196:199], v[18:21]
	v_mfma_f32_16x16x32_bf16 v[6:9], v[180:183], v[106:109], v[6:9]
	v_mfma_f32_16x16x32_bf16 v[2:5], v[180:183], v[196:199], v[2:5]
	v_mfma_f32_16x16x32_bf16 v[30:33], v[74:77], v[106:109], v[30:33]
	v_mfma_f32_16x16x32_bf16 v[26:29], v[74:77], v[196:199], v[26:29]
	v_mfma_f32_16x16x32_bf16 v[22:25], v[94:97], v[110:113], v[22:25]
	v_mfma_f32_16x16x32_bf16 v[18:21], v[94:97], v[200:203], v[18:21]
	v_mfma_f32_16x16x32_bf16 v[14:17], v[172:175], v[106:109], v[14:17]
	v_mfma_f32_16x16x32_bf16 v[10:13], v[172:175], v[196:199], v[10:13]
	v_mfma_f32_16x16x32_bf16 v[6:9], v[184:187], v[110:113], v[6:9]
	v_mfma_f32_16x16x32_bf16 v[2:5], v[184:187], v[200:203], v[2:5]
	v_mfma_f32_16x16x32_bf16 v[136:139], v[78:81], v[110:113], v[30:33]
	v_mfma_f32_16x16x32_bf16 v[146:149], v[78:81], v[200:203], v[26:29]
	v_mfma_f32_16x16x32_bf16 v[150:153], v[176:179], v[110:113], v[14:17]
	v_mfma_f32_16x16x32_bf16 v[154:157], v[176:179], v[200:203], v[10:13]
	s_barrier
	s_nop 0
	ds_read_b128 v[10:13], v135
	ds_read_b128 v[14:17], v135 offset:1024
	ds_read_b128 v[172:175], v135 offset:2048
	ds_read_b128 v[176:179], v135 offset:3072
	ds_read_b128 v[26:29], v133 offset:32768
	ds_read_b128 v[30:33], v133 offset:33792
	ds_read_b128 v[42:45], v132 offset:32768
	ds_read_b128 v[46:49], v132 offset:33792
	ds_read_b128 v[180:183], v131 offset:32768
	ds_read_b128 v[184:187], v131 offset:33792
	ds_read_b128 v[196:199], v130 offset:32768
	ds_read_b128 v[200:203], v130 offset:33792
	s_waitcnt vmcnt(2)
	s_barrier
	s_waitcnt lgkmcnt(0)
	v_mfma_f32_16x16x32_bf16 v[74:77], v[26:29], v[10:13], v[126:129]
	v_mfma_f32_16x16x32_bf16 v[126:129], v[30:33], v[14:17], v[74:77]
	v_mfma_f32_16x16x32_bf16 v[74:77], v[26:29], v[172:175], v[122:125]
	v_mfma_f32_16x16x32_bf16 v[122:125], v[30:33], v[176:179], v[74:77]
	v_mfma_f32_16x16x32_bf16 v[74:77], v[42:45], v[10:13], v[118:121]
	v_mfma_f32_16x16x32_bf16 v[110:113], v[46:49], v[14:17], v[74:77]
	v_mfma_f32_16x16x32_bf16 v[74:77], v[42:45], v[172:175], v[114:117]
	v_mfma_f32_16x16x32_bf16 v[106:109], v[46:49], v[176:179], v[74:77]
	v_mfma_f32_16x16x32_bf16 v[74:77], v[180:183], v[10:13], v[142:145]
	v_mfma_f32_16x16x32_bf16 v[94:97], v[184:187], v[14:17], v[74:77]
	v_mfma_f32_16x16x32_bf16 v[74:77], v[180:183], v[172:175], v[192:195]
	v_mfma_f32_16x16x32_bf16 v[90:93], v[184:187], v[176:179], v[74:77]
	v_mfma_f32_16x16x32_bf16 v[74:77], v[196:199], v[10:13], v[102:105]
	v_mfma_f32_16x16x32_bf16 v[78:81], v[200:203], v[14:17], v[74:77]
	v_mfma_f32_16x16x32_bf16 v[74:77], v[196:199], v[172:175], v[98:101]
	v_mfma_f32_16x16x32_bf16 v[74:77], v[200:203], v[176:179], v[74:77]
	s_barrier
; #define WAIT_V(n) asm volatile("s_waitcnt vmcnt(" #n ")" ::: "memory")
; #define WAIT_L(n) asm volatile("s_waitcnt lgkmcnt(" #n ")" ::: "memory")
; #define BAR __builtin_amdgcn_s_barrier()
; __device__ __forceinline__ void mainloop_8phase(const u16* __restrict__ A, const u16* __restrict__ Bt, int K,
;                                                 f32x4 (&acc)[2][2][4][2], int wid_s, int ld) {
;     ...
;   { LDB(B0, 1, 0); LDA(At, 1, 0); WAIT_V(2); BAR; WAIT_L(0); MMA(0, 0, At, B0); BAR;
;     LDB(B1, 1, 1); WAIT_V(0); BAR; WAIT_L(0); MMA(0, 1, At, B1); BAR;
;     LDA(At, 1, 1); BAR; WAIT_L(0); MMA(1, 0, At, B0); MMA(1, 1, At, B1); BAR; }
;   if (wr == 0) BAR;
	ds_read_b128 v[140:143], v134
	ds_read_b128 v[192:195], v134 offset:1024
	ds_read_b128 v[212:215], v134 offset:2048
	ds_read_b128 v[216:219], v134 offset:3072
	s_waitcnt vmcnt(0)
	s_barrier
	s_waitcnt lgkmcnt(0)
	v_mfma_f32_16x16x32_bf16 v[98:101], v[26:29], v[140:143], v[204:207]
	v_mfma_f32_16x16x32_bf16 v[26:29], v[26:29], v[212:215], v[160:163]
	v_mfma_f32_16x16x32_bf16 v[114:117], v[30:33], v[216:219], v[26:29]
	v_mfma_f32_16x16x32_bf16 v[26:29], v[42:45], v[140:143], v[86:89]
	v_mfma_f32_16x16x32_bf16 v[102:105], v[46:49], v[192:195], v[26:29]
	v_mfma_f32_16x16x32_bf16 v[26:29], v[42:45], v[212:215], v[82:85]
	v_mfma_f32_16x16x32_bf16 v[118:121], v[30:33], v[192:195], v[98:101]
	v_mfma_f32_16x16x32_bf16 v[98:101], v[46:49], v[216:219], v[26:29]
	v_mfma_f32_16x16x32_bf16 v[26:29], v[180:183], v[140:143], v[164:167]
	v_mfma_f32_16x16x32_bf16 v[86:89], v[184:187], v[192:195], v[26:29]
	v_mfma_f32_16x16x32_bf16 v[26:29], v[180:183], v[212:215], v[168:171]
	v_mfma_f32_16x16x32_bf16 v[82:85], v[184:187], v[216:219], v[26:29]
	v_mfma_f32_16x16x32_bf16 v[26:29], v[196:199], v[140:143], v[70:73]
	v_mfma_f32_16x16x32_bf16 v[70:73], v[200:203], v[192:195], v[26:29]
	v_mfma_f32_16x16x32_bf16 v[26:29], v[196:199], v[212:215], v[66:69]
	v_mfma_f32_16x16x32_bf16 v[66:69], v[200:203], v[216:219], v[26:29]
	s_barrier
	ds_read_b128 v[158:161], v133 offset:49152
	ds_read_b128 v[162:165], v133 offset:50176
	ds_read_b128 v[166:169], v132 offset:49152
	ds_read_b128 v[132:135], v132 offset:50176
	ds_read_b128 v[180:183], v131 offset:49152
	ds_read_b128 v[184:187], v131 offset:50176
	ds_read_b128 v[196:199], v130 offset:49152
	ds_read_b128 v[200:203], v130 offset:50176
	s_barrier
	s_waitcnt lgkmcnt(0)
	v_mfma_f32_16x16x32_bf16 v[26:29], v[158:161], v[10:13], v[62:65]
	v_mfma_f32_16x16x32_bf16 v[62:65], v[162:165], v[14:17], v[26:29]
	v_mfma_f32_16x16x32_bf16 v[26:29], v[158:161], v[172:175], v[58:61]
	v_mfma_f32_16x16x32_bf16 v[58:61], v[162:165], v[176:179], v[26:29]
	v_mfma_f32_16x16x32_bf16 v[26:29], v[166:169], v[10:13], v[54:57]
	v_mfma_f32_16x16x32_bf16 v[46:49], v[132:135], v[14:17], v[26:29]
	v_mfma_f32_16x16x32_bf16 v[26:29], v[166:169], v[172:175], v[50:53]
	v_mfma_f32_16x16x32_bf16 v[42:45], v[132:135], v[176:179], v[26:29]
	v_mfma_f32_16x16x32_bf16 v[26:29], v[180:183], v[10:13], v[188:191]
	v_mfma_f32_16x16x32_bf16 v[10:13], v[196:199], v[10:13], v[38:41]
	v_mfma_f32_16x16x32_bf16 v[30:33], v[184:187], v[14:17], v[26:29]
	v_mfma_f32_16x16x32_bf16 v[26:29], v[180:183], v[172:175], v[208:211]
	v_mfma_f32_16x16x32_bf16 v[14:17], v[200:203], v[14:17], v[10:13]
	v_mfma_f32_16x16x32_bf16 v[10:13], v[196:199], v[172:175], v[34:37]
	v_mfma_f32_16x16x32_bf16 v[26:29], v[184:187], v[176:179], v[26:29]
	v_mfma_f32_16x16x32_bf16 v[10:13], v[200:203], v[176:179], v[10:13]
	v_mfma_f32_16x16x32_bf16 v[34:37], v[158:161], v[140:143], v[136:139]
	v_mfma_f32_16x16x32_bf16 v[54:57], v[162:165], v[192:195], v[34:37]
	v_mfma_f32_16x16x32_bf16 v[34:37], v[158:161], v[212:215], v[146:149]
	v_mfma_f32_16x16x32_bf16 v[18:21], v[166:169], v[212:215], v[18:21]
	v_mfma_f32_16x16x32_bf16 v[50:53], v[162:165], v[216:219], v[34:37]
	v_mfma_f32_16x16x32_bf16 v[22:25], v[166:169], v[140:143], v[22:25]
	v_mfma_f32_16x16x32_bf16 v[34:37], v[132:135], v[216:219], v[18:21]
	v_mfma_f32_16x16x32_bf16 v[18:21], v[180:183], v[140:143], v[150:153]
	v_mfma_f32_16x16x32_bf16 v[38:41], v[132:135], v[192:195], v[22:25]
	v_mfma_f32_16x16x32_bf16 v[22:25], v[184:187], v[192:195], v[18:21]
	v_mfma_f32_16x16x32_bf16 v[18:21], v[180:183], v[212:215], v[154:157]
	v_mfma_f32_16x16x32_bf16 v[6:9], v[196:199], v[140:143], v[6:9]
	v_mfma_f32_16x16x32_bf16 v[2:5], v[196:199], v[212:215], v[2:5]
	v_mfma_f32_16x16x32_bf16 v[18:21], v[184:187], v[216:219], v[18:21]
	v_mfma_f32_16x16x32_bf16 v[6:9], v[200:203], v[192:195], v[6:9]
	v_mfma_f32_16x16x32_bf16 v[2:5], v[200:203], v[216:219], v[2:5]
	s_movk_i32 s0, 0x100
	v_cmp_gt_u32_e32 vcc, s0, v0
	s_barrier
	s_and_saveexec_b64 s[0:1], vcc
	s_cbranch_execz .LBB0_61
	s_barrier

; #define WAIT_V(n) asm volatile("s_waitcnt vmcnt(" #n ")" ::: "memory")
; #define WAIT_L(n) asm volatile("s_waitcnt lgkmcnt(" #n ")" ::: "memory")
; #define BAR __builtin_amdgcn_s_barrier()
; #define SCHED __builtin_amdgcn_sched_barrier(0)
; __device__ __forceinline__ void mainloop_8phase(const u16* __restrict__ A, const u16* __restrict__ Bt, int K,
;                                                 f32x4 (&acc)[2][2][4][2], int wid_s, int ld) {
;     ...
;     LDB(B0, 0, 0); SCHED; LDA(At, 0, 0); STAGE(SA(1, 1), A, brow + G_HALF, t + 1);
;     WAIT_L(8); BAR; WAIT_L(0); MMA(0, 0, At, B0); BAR; SCHED;
;     LDB(B1, 0, 1); STAGE(SB(0, 0), Bt, bcol, t + 2);
;     BAR; WAIT_L(0); MMA(0, 1, At, B1); BAR;
;     LDA(At, 0, 1); STAGE(SA(0, 0), A, brow, t + 2);
;     BAR; WAIT_L(0); MMA(1, 0, At, B0); BAR; SCHED;
;     STAGE(SB(0, 1), Bt, bcol + G_HALF, t + 2);
;     WAIT_V(6); BAR; MMA(1, 1, At, B1); BAR;
.LBB0_162:
	ds_read_b128 v[156:159], v148
	ds_read_b128 v[160:163], v148 offset:1024
	ds_read_b128 v[164:167], v148 offset:2048
	ds_read_b128 v[168:171], v148 offset:3072
	s_add_i32 s6, s3, 0xffffff00
	s_add_i32 m0, s100, 0xc000
	ds_read_b128 v[172:175], v133
	ds_read_b128 v[176:179], v133 offset:1024
	ds_read_b128 v[180:183], v132
	ds_read_b128 v[184:187], v132 offset:1024
	ds_read_b128 v[188:191], v131
	ds_read_b128 v[192:195], v131 offset:1024
	ds_read_b128 v[196:199], v130
	buffer_load_dwordx4 v137, s[88:91], s6 offen lds
	s_add_i32 m0, s100, 0xe000
	ds_read_b128 v[200:203], v130 offset:1024
	buffer_load_dwordx4 v136, s[88:91], s6 offen lds
	s_waitcnt lgkmcnt(8)
	s_barrier
	s_waitcnt lgkmcnt(1)
	v_mfma_f32_16x16x32_bf16 v[126:129], v[172:175], v[156:159], v[126:129]
	v_mfma_f32_16x16x32_bf16 v[122:125], v[172:175], v[164:167], v[122:125]
	v_mfma_f32_16x16x32_bf16 v[118:121], v[180:183], v[156:159], v[118:121]
	v_mfma_f32_16x16x32_bf16 v[114:117], v[180:183], v[164:167], v[114:117]
	v_mfma_f32_16x16x32_bf16 v[110:113], v[188:191], v[156:159], v[110:113]
	v_mfma_f32_16x16x32_bf16 v[106:109], v[188:191], v[164:167], v[106:109]
	v_mfma_f32_16x16x32_bf16 v[102:105], v[196:199], v[156:159], v[102:105]
	v_mfma_f32_16x16x32_bf16 v[98:101], v[196:199], v[164:167], v[98:101]
	v_mfma_f32_16x16x32_bf16 v[126:129], v[176:179], v[160:163], v[126:129]
	v_mfma_f32_16x16x32_bf16 v[122:125], v[176:179], v[168:171], v[122:125]
	v_mfma_f32_16x16x32_bf16 v[118:121], v[184:187], v[160:163], v[118:121]
	v_mfma_f32_16x16x32_bf16 v[114:117], v[184:187], v[168:171], v[114:117]
	v_mfma_f32_16x16x32_bf16 v[110:113], v[192:195], v[160:163], v[110:113]
	v_mfma_f32_16x16x32_bf16 v[106:109], v[192:195], v[168:171], v[106:109]
	s_waitcnt lgkmcnt(0)
	v_mfma_f32_16x16x32_bf16 v[102:105], v[200:203], v[160:163], v[102:105]
	v_mfma_f32_16x16x32_bf16 v[98:101], v[200:203], v[168:171], v[98:101]
	s_barrier
	s_add_i32 s15, s3, 0xfff7ff80
	s_mov_b32 s6, s90
	s_add_i32 m0, s100, 0x10000
	ds_read_b128 v[204:207], v145
	ds_read_b128 v[208:211], v145 offset:1024
	ds_read_b128 v[212:215], v145 offset:2048
	buffer_load_dwordx4 v137, s[4:7], s15 offen lds
	s_add_i32 m0, s100, 0x12000
	ds_read_b128 v[216:219], v145 offset:3072
	buffer_load_dwordx4 v136, s[4:7], s15 offen lds
	s_barrier
	s_waitcnt lgkmcnt(1)
	v_mfma_f32_16x16x32_bf16 v[94:97], v[172:175], v[204:207], v[94:97]
	v_mfma_f32_16x16x32_bf16 v[90:93], v[172:175], v[212:215], v[90:93]
	v_mfma_f32_16x16x32_bf16 v[86:89], v[180:183], v[204:207], v[86:89]
	v_mfma_f32_16x16x32_bf16 v[82:85], v[180:183], v[212:215], v[82:85]
	v_mfma_f32_16x16x32_bf16 v[78:81], v[188:191], v[204:207], v[78:81]
	v_mfma_f32_16x16x32_bf16 v[74:77], v[188:191], v[212:215], v[74:77]
	v_mfma_f32_16x16x32_bf16 v[70:73], v[196:199], v[204:207], v[70:73]
	v_mfma_f32_16x16x32_bf16 v[66:69], v[196:199], v[212:215], v[66:69]
	v_mfma_f32_16x16x32_bf16 v[94:97], v[176:179], v[208:211], v[94:97]
	s_waitcnt lgkmcnt(0)
	v_mfma_f32_16x16x32_bf16 v[90:93], v[176:179], v[216:219], v[90:93]
	v_mfma_f32_16x16x32_bf16 v[86:89], v[184:187], v[208:211], v[86:89]
	v_mfma_f32_16x16x32_bf16 v[82:85], v[184:187], v[216:219], v[82:85]
	v_mfma_f32_16x16x32_bf16 v[78:81], v[192:195], v[208:211], v[78:81]
	v_mfma_f32_16x16x32_bf16 v[74:77], v[192:195], v[216:219], v[74:77]
	v_mfma_f32_16x16x32_bf16 v[70:73], v[200:203], v[208:211], v[70:73]
	v_mfma_f32_16x16x32_bf16 v[66:69], v[200:203], v[216:219], v[66:69]
	s_mov_b32 m0, s100
	s_barrier
	ds_read_b128 v[172:175], v133 offset:16384
	ds_read_b128 v[176:179], v133 offset:17408
	ds_read_b128 v[180:183], v132 offset:16384
	ds_read_b128 v[184:187], v132 offset:17408
	ds_read_b128 v[188:191], v131 offset:16384
	ds_read_b128 v[192:195], v131 offset:17408
	ds_read_b128 v[196:199], v130 offset:16384
	buffer_load_dwordx4 v137, s[88:91], s15 offen lds
	s_add_i32 m0, s100, 0x2000
	ds_read_b128 v[200:203], v130 offset:17408
	buffer_load_dwordx4 v136, s[88:91], s15 offen lds
	s_barrier
	s_waitcnt lgkmcnt(1)
	v_mfma_f32_16x16x32_bf16 v[62:65], v[172:175], v[156:159], v[62:65]
	v_mfma_f32_16x16x32_bf16 v[58:61], v[172:175], v[164:167], v[58:61]
	v_mfma_f32_16x16x32_bf16 v[54:57], v[180:183], v[156:159], v[54:57]
	v_mfma_f32_16x16x32_bf16 v[50:53], v[180:183], v[164:167], v[50:53]
	v_mfma_f32_16x16x32_bf16 v[46:49], v[188:191], v[156:159], v[46:49]
	v_mfma_f32_16x16x32_bf16 v[42:45], v[188:191], v[164:167], v[42:45]
	v_mfma_f32_16x16x32_bf16 v[38:41], v[196:199], v[156:159], v[38:41]
	v_mfma_f32_16x16x32_bf16 v[34:37], v[196:199], v[164:167], v[34:37]
	v_mfma_f32_16x16x32_bf16 v[62:65], v[176:179], v[160:163], v[62:65]
	v_mfma_f32_16x16x32_bf16 v[58:61], v[176:179], v[168:171], v[58:61]
	v_mfma_f32_16x16x32_bf16 v[54:57], v[184:187], v[160:163], v[54:57]
	v_mfma_f32_16x16x32_bf16 v[50:53], v[184:187], v[168:171], v[50:53]
	v_mfma_f32_16x16x32_bf16 v[46:49], v[192:195], v[160:163], v[46:49]
	v_mfma_f32_16x16x32_bf16 v[42:45], v[192:195], v[168:171], v[42:45]
	s_waitcnt lgkmcnt(0)
	v_mfma_f32_16x16x32_bf16 v[38:41], v[200:203], v[160:163], v[38:41]
	v_mfma_f32_16x16x32_bf16 v[34:37], v[200:203], v[168:171], v[34:37]
	s_barrier
	s_add_i32 s15, s3, 0xffffff80
	s_add_i32 m0, s100, 0x14000
	buffer_load_dwordx4 v137, s[4:7], s15 offen lds
	s_add_i32 m0, s100, 0x16000
	s_nop 0
	buffer_load_dwordx4 v136, s[4:7], s15 offen lds
	s_waitcnt vmcnt(6)
	s_barrier
; #define WAIT_V(n) asm volatile("s_waitcnt vmcnt(" #n ")" ::: "memory")
; #define WAIT_L(n) asm volatile("s_waitcnt lgkmcnt(" #n ")" ::: "memory")
; #define BAR __builtin_amdgcn_s_barrier()
; #define SCHED __builtin_amdgcn_sched_barrier(0)
; __device__ __forceinline__ void mainloop_8phase(const u16* __restrict__ A, const u16* __restrict__ Bt, int K,
;                                                 f32x4 (&acc)[2][2][4][2], int wid_s, int ld) {
;     ...
;     LDB(B0, 1, 0); SCHED; LDA(At, 1, 0); STAGE(SA(0, 1), A, brow + G_HALF, t + 2);
;     WAIT_L(8); BAR; WAIT_L(0); MMA(0, 0, At, B0); BAR; SCHED;
;     LDB(B1, 1, 1); STAGE(SB(1, 0), Bt, bcol, t + 3);
;     BAR; WAIT_L(0); MMA(0, 1, At, B1); BAR;
;     LDA(At, 1, 1); STAGE(SA(1, 0), A, brow, t + 3);
;     BAR; WAIT_L(0); MMA(1, 0, At, B0); BAR; SCHED;
;     STAGE(SB(1, 1), Bt, bcol + G_HALF, t + 3);
;     WAIT_V(6); BAR; MMA(1, 1, At, B1); BAR;
	v_mfma_f32_16x16x32_bf16 v[30:33], v[172:175], v[204:207], v[30:33]
	v_mfma_f32_16x16x32_bf16 v[26:29], v[172:175], v[212:215], v[26:29]
	v_mfma_f32_16x16x32_bf16 v[22:25], v[180:183], v[204:207], v[22:25]
	v_mfma_f32_16x16x32_bf16 v[18:21], v[180:183], v[212:215], v[18:21]
	v_mfma_f32_16x16x32_bf16 v[14:17], v[188:191], v[204:207], v[14:17]
	v_mfma_f32_16x16x32_bf16 v[10:13], v[188:191], v[212:215], v[10:13]
	v_mfma_f32_16x16x32_bf16 v[6:9], v[196:199], v[204:207], v[6:9]
	v_mfma_f32_16x16x32_bf16 v[2:5], v[196:199], v[212:215], v[2:5]
	v_mfma_f32_16x16x32_bf16 v[30:33], v[176:179], v[208:211], v[30:33]
	v_mfma_f32_16x16x32_bf16 v[26:29], v[176:179], v[216:219], v[26:29]
	v_mfma_f32_16x16x32_bf16 v[22:25], v[184:187], v[208:211], v[22:25]
	v_mfma_f32_16x16x32_bf16 v[18:21], v[184:187], v[216:219], v[18:21]
	v_mfma_f32_16x16x32_bf16 v[14:17], v[192:195], v[208:211], v[14:17]
	v_mfma_f32_16x16x32_bf16 v[10:13], v[192:195], v[216:219], v[10:13]
	v_mfma_f32_16x16x32_bf16 v[6:9], v[200:203], v[208:211], v[6:9]
	v_mfma_f32_16x16x32_bf16 v[2:5], v[200:203], v[216:219], v[2:5]
	s_barrier
	ds_read_b128 v[156:159], v135
	ds_read_b128 v[160:163], v135 offset:1024
	ds_read_b128 v[164:167], v135 offset:2048
	ds_read_b128 v[168:171], v135 offset:3072
	s_add_i32 m0, s100, 0x4000
	ds_read_b128 v[172:175], v133 offset:32768
	ds_read_b128 v[176:179], v133 offset:33792
	ds_read_b128 v[180:183], v132 offset:32768
	ds_read_b128 v[184:187], v132 offset:33792
	ds_read_b128 v[188:191], v131 offset:32768
	ds_read_b128 v[192:195], v131 offset:33792
	ds_read_b128 v[196:199], v130 offset:32768
	buffer_load_dwordx4 v137, s[88:91], s15 offen lds
	s_add_i32 m0, s100, 0x6000
	ds_read_b128 v[200:203], v130 offset:33792
	buffer_load_dwordx4 v136, s[88:91], s15 offen lds
	s_waitcnt lgkmcnt(8)
	s_barrier
	s_waitcnt lgkmcnt(1)
	v_mfma_f32_16x16x32_bf16 v[126:129], v[172:175], v[156:159], v[126:129]
	v_mfma_f32_16x16x32_bf16 v[122:125], v[172:175], v[164:167], v[122:125]
	v_mfma_f32_16x16x32_bf16 v[118:121], v[180:183], v[156:159], v[118:121]
	v_mfma_f32_16x16x32_bf16 v[114:117], v[180:183], v[164:167], v[114:117]
	v_mfma_f32_16x16x32_bf16 v[110:113], v[188:191], v[156:159], v[110:113]
	v_mfma_f32_16x16x32_bf16 v[106:109], v[188:191], v[164:167], v[106:109]
	v_mfma_f32_16x16x32_bf16 v[102:105], v[196:199], v[156:159], v[102:105]
	v_mfma_f32_16x16x32_bf16 v[98:101], v[196:199], v[164:167], v[98:101]
	v_mfma_f32_16x16x32_bf16 v[126:129], v[176:179], v[160:163], v[126:129]
	v_mfma_f32_16x16x32_bf16 v[122:125], v[176:179], v[168:171], v[122:125]
	v_mfma_f32_16x16x32_bf16 v[118:121], v[184:187], v[160:163], v[118:121]
	v_mfma_f32_16x16x32_bf16 v[114:117], v[184:187], v[168:171], v[114:117]
	v_mfma_f32_16x16x32_bf16 v[110:113], v[192:195], v[160:163], v[110:113]
	v_mfma_f32_16x16x32_bf16 v[106:109], v[192:195], v[168:171], v[106:109]
	s_waitcnt lgkmcnt(0)
	v_mfma_f32_16x16x32_bf16 v[102:105], v[200:203], v[160:163], v[102:105]
	v_mfma_f32_16x16x32_bf16 v[98:101], v[200:203], v[168:171], v[98:101]
	s_barrier
	s_add_i32 s15, s3, 0xfff80000
	s_add_i32 m0, s100, 0x18000
	ds_read_b128 v[204:207], v134
	ds_read_b128 v[208:211], v134 offset:1024
	ds_read_b128 v[212:215], v134 offset:2048
	buffer_load_dwordx4 v137, s[4:7], s15 offen lds
	s_add_i32 m0, s100, 0x1a000
	ds_read_b128 v[216:219], v134 offset:3072
	buffer_load_dwordx4 v136, s[4:7], s15 offen lds
	s_barrier
	s_waitcnt lgkmcnt(1)
	v_mfma_f32_16x16x32_bf16 v[94:97], v[172:175], v[204:207], v[94:97]
	v_mfma_f32_16x16x32_bf16 v[90:93], v[172:175], v[212:215], v[90:93]
	v_mfma_f32_16x16x32_bf16 v[86:89], v[180:183], v[204:207], v[86:89]
	v_mfma_f32_16x16x32_bf16 v[82:85], v[180:183], v[212:215], v[82:85]
	v_mfma_f32_16x16x32_bf16 v[78:81], v[188:191], v[204:207], v[78:81]
	v_mfma_f32_16x16x32_bf16 v[74:77], v[188:191], v[212:215], v[74:77]
	v_mfma_f32_16x16x32_bf16 v[70:73], v[196:199], v[204:207], v[70:73]
	v_mfma_f32_16x16x32_bf16 v[66:69], v[196:199], v[212:215], v[66:69]
	v_mfma_f32_16x16x32_bf16 v[94:97], v[176:179], v[208:211], v[94:97]
	s_waitcnt lgkmcnt(0)
	v_mfma_f32_16x16x32_bf16 v[90:93], v[176:179], v[216:219], v[90:93]
	v_mfma_f32_16x16x32_bf16 v[86:89], v[184:187], v[208:211], v[86:89]
	v_mfma_f32_16x16x32_bf16 v[82:85], v[184:187], v[216:219], v[82:85]
	v_mfma_f32_16x16x32_bf16 v[78:81], v[192:195], v[208:211], v[78:81]
	v_mfma_f32_16x16x32_bf16 v[74:77], v[192:195], v[216:219], v[74:77]
	v_mfma_f32_16x16x32_bf16 v[70:73], v[200:203], v[208:211], v[70:73]
	v_mfma_f32_16x16x32_bf16 v[66:69], v[200:203], v[216:219], v[66:69]
	s_add_i32 m0, s100, 0x8000
	s_barrier
	ds_read_b128 v[172:175], v133 offset:49152
	ds_read_b128 v[176:179], v133 offset:50176
	ds_read_b128 v[180:183], v132 offset:49152
	ds_read_b128 v[184:187], v132 offset:50176
	ds_read_b128 v[188:191], v131 offset:49152
	ds_read_b128 v[192:195], v131 offset:50176
	ds_read_b128 v[196:199], v130 offset:49152
	buffer_load_dwordx4 v137, s[88:91], s15 offen lds
	s_add_i32 m0, s100, 0xa000
	ds_read_b128 v[200:203], v130 offset:50176
	buffer_load_dwordx4 v136, s[88:91], s15 offen lds
	s_barrier
	s_waitcnt lgkmcnt(1)
	v_mfma_f32_16x16x32_bf16 v[62:65], v[172:175], v[156:159], v[62:65]
	v_mfma_f32_16x16x32_bf16 v[58:61], v[172:175], v[164:167], v[58:61]
	v_mfma_f32_16x16x32_bf16 v[54:57], v[180:183], v[156:159], v[54:57]
	v_mfma_f32_16x16x32_bf16 v[50:53], v[180:183], v[164:167], v[50:53]
	v_mfma_f32_16x16x32_bf16 v[46:49], v[188:191], v[156:159], v[46:49]
	v_mfma_f32_16x16x32_bf16 v[42:45], v[188:191], v[164:167], v[42:45]
	v_mfma_f32_16x16x32_bf16 v[38:41], v[196:199], v[156:159], v[38:41]
	v_mfma_f32_16x16x32_bf16 v[34:37], v[196:199], v[164:167], v[34:37]
	v_mfma_f32_16x16x32_bf16 v[62:65], v[176:179], v[160:163], v[62:65]
	v_mfma_f32_16x16x32_bf16 v[58:61], v[176:179], v[168:171], v[58:61]
	v_mfma_f32_16x16x32_bf16 v[54:57], v[184:187], v[160:163], v[54:57]
	v_mfma_f32_16x16x32_bf16 v[50:53], v[184:187], v[168:171], v[50:53]
	v_mfma_f32_16x16x32_bf16 v[46:49], v[192:195], v[160:163], v[46:49]
	v_mfma_f32_16x16x32_bf16 v[42:45], v[192:195], v[168:171], v[42:45]
	s_waitcnt lgkmcnt(0)
	v_mfma_f32_16x16x32_bf16 v[38:41], v[200:203], v[160:163], v[38:41]
	v_mfma_f32_16x16x32_bf16 v[34:37], v[200:203], v[168:171], v[34:37]
	s_barrier
; #define WAIT_V(n) asm volatile("s_waitcnt vmcnt(" #n ")" ::: "memory")
; #define WAIT_L(n) asm volatile("s_waitcnt lgkmcnt(" #n ")" ::: "memory")
; #define BAR __builtin_amdgcn_s_barrier()
; __device__ __forceinline__ void mainloop_8phase(const u16* __restrict__ A, const u16* __restrict__ Bt, int K,
;                                                 f32x4 (&acc)[2][2][4][2], int wid_s, int ld) {
;     ...
;     WAIT_V(6); BAR; MMA(1, 1, At, B1); BAR;
;   }
;   { LDB(B0, 0, 0); LDA(At, 0, 0); STAGE(SA(1, 1), A, brow + G_HALF, nt - 1);
;     BAR; WAIT_L(0); MMA(0, 0, At, B0); BAR;
;     LDB(B1, 0, 1); BAR; WAIT_L(0); MMA(0, 1, At, B1); BAR;
;     LDA(At, 0, 1); WAIT_V(4); BAR; WAIT_L(0); MMA(1, 0, At, B0); MMA(1, 1, At, B1); BAR; }
	s_add_i32 m0, s100, 0x1c000
	buffer_load_dwordx4 v137, s[4:7], s3 offen lds
	s_add_i32 m0, s100, 0x1e000
	s_nop 0
	buffer_load_dwordx4 v136, s[4:7], s3 offen lds
	s_waitcnt vmcnt(6)
	s_barrier
	v_mfma_f32_16x16x32_bf16 v[30:33], v[172:175], v[204:207], v[30:33]
	v_mfma_f32_16x16x32_bf16 v[26:29], v[172:175], v[212:215], v[26:29]
	v_mfma_f32_16x16x32_bf16 v[22:25], v[180:183], v[204:207], v[22:25]
	v_mfma_f32_16x16x32_bf16 v[18:21], v[180:183], v[212:215], v[18:21]
	v_mfma_f32_16x16x32_bf16 v[14:17], v[188:191], v[204:207], v[14:17]
	v_mfma_f32_16x16x32_bf16 v[10:13], v[188:191], v[212:215], v[10:13]
	v_mfma_f32_16x16x32_bf16 v[6:9], v[196:199], v[204:207], v[6:9]
	v_mfma_f32_16x16x32_bf16 v[2:5], v[196:199], v[212:215], v[2:5]
	v_mfma_f32_16x16x32_bf16 v[30:33], v[176:179], v[208:211], v[30:33]
	v_mfma_f32_16x16x32_bf16 v[26:29], v[176:179], v[216:219], v[26:29]
	v_mfma_f32_16x16x32_bf16 v[22:25], v[184:187], v[208:211], v[22:25]
	v_mfma_f32_16x16x32_bf16 v[18:21], v[184:187], v[216:219], v[18:21]
	v_mfma_f32_16x16x32_bf16 v[14:17], v[192:195], v[208:211], v[14:17]
	v_mfma_f32_16x16x32_bf16 v[10:13], v[192:195], v[216:219], v[10:13]
	v_mfma_f32_16x16x32_bf16 v[6:9], v[200:203], v[208:211], v[6:9]
	v_mfma_f32_16x16x32_bf16 v[2:5], v[200:203], v[216:219], v[2:5]
	s_add_i32 s2, s2, 2
	s_addk_i32 s3, 0x100
	s_cmp_lt_u32 s2, 28
	s_barrier
	s_cbranch_scc1 .LBB0_162
	v_readfirstlane_b32 s2, v150
	s_mov_b32 m0, s2
	s_mov_b32 s3, 0x80f80
	v_readfirstlane_b32 s2, v149
	ds_read_b128 v[138:141], v148
	ds_read_b128 v[152:155], v148 offset:1024
	ds_read_b128 v[156:159], v148 offset:2048
	ds_read_b128 v[160:163], v148 offset:3072
	ds_read_b128 v[164:167], v133
	ds_read_b128 v[168:171], v133 offset:1024
	ds_read_b128 v[172:175], v132
	ds_read_b128 v[176:179], v132 offset:1024
	ds_read_b128 v[180:183], v131
	ds_read_b128 v[184:187], v131 offset:1024
	ds_read_b128 v[188:191], v130
	ds_read_b128 v[192:195], v130 offset:1024
	buffer_load_dwordx4 v137, s[88:91], s3 offen lds
	s_mov_b32 m0, s2
	s_nop 0
	buffer_load_dwordx4 v136, s[88:91], s3 offen lds
	s_barrier
	s_waitcnt lgkmcnt(0)
	v_mfma_f32_16x16x32_bf16 v[126:129], v[164:167], v[138:141], v[126:129]
	v_mfma_f32_16x16x32_bf16 v[118:121], v[172:175], v[138:141], v[118:121]
	v_mfma_f32_16x16x32_bf16 v[110:113], v[180:183], v[138:141], v[110:113]
	v_mfma_f32_16x16x32_bf16 v[102:105], v[188:191], v[138:141], v[102:105]
	v_mfma_f32_16x16x32_bf16 v[126:129], v[168:171], v[152:155], v[126:129]
	v_mfma_f32_16x16x32_bf16 v[122:125], v[164:167], v[156:159], v[122:125]
	v_mfma_f32_16x16x32_bf16 v[118:121], v[176:179], v[152:155], v[118:121]
	v_mfma_f32_16x16x32_bf16 v[114:117], v[172:175], v[156:159], v[114:117]
	v_mfma_f32_16x16x32_bf16 v[110:113], v[184:187], v[152:155], v[110:113]
	v_mfma_f32_16x16x32_bf16 v[106:109], v[180:183], v[156:159], v[106:109]
	v_mfma_f32_16x16x32_bf16 v[102:105], v[192:195], v[152:155], v[102:105]
	v_mfma_f32_16x16x32_bf16 v[98:101], v[188:191], v[156:159], v[98:101]
	v_mfma_f32_16x16x32_bf16 v[146:149], v[168:171], v[160:163], v[122:125]
	v_mfma_f32_16x16x32_bf16 v[196:199], v[176:179], v[160:163], v[114:117]
	v_mfma_f32_16x16x32_bf16 v[200:203], v[184:187], v[160:163], v[106:109]
	v_mfma_f32_16x16x32_bf16 v[204:207], v[192:195], v[160:163], v[98:101]
	s_barrier
	s_nop 1
	ds_read_b128 v[98:101], v145
	ds_read_b128 v[106:109], v145 offset:1024
	ds_read_b128 v[114:117], v145 offset:2048
	ds_read_b128 v[122:125], v145 offset:3072
	s_barrier
	s_waitcnt lgkmcnt(0)
	v_mfma_f32_16x16x32_bf16 v[94:97], v[164:167], v[98:101], v[94:97]
	v_mfma_f32_16x16x32_bf16 v[90:93], v[164:167], v[114:117], v[90:93]
	v_mfma_f32_16x16x32_bf16 v[86:89], v[172:175], v[98:101], v[86:89]
	v_mfma_f32_16x16x32_bf16 v[82:85], v[172:175], v[114:117], v[82:85]
	v_mfma_f32_16x16x32_bf16 v[78:81], v[180:183], v[98:101], v[78:81]
	v_mfma_f32_16x16x32_bf16 v[74:77], v[180:183], v[114:117], v[74:77]
	v_mfma_f32_16x16x32_bf16 v[70:73], v[188:191], v[98:101], v[70:73]
	v_mfma_f32_16x16x32_bf16 v[66:69], v[188:191], v[114:117], v[66:69]
	v_mfma_f32_16x16x32_bf16 v[94:97], v[168:171], v[106:109], v[94:97]
	v_mfma_f32_16x16x32_bf16 v[90:93], v[168:171], v[122:125], v[90:93]
	v_mfma_f32_16x16x32_bf16 v[86:89], v[176:179], v[106:109], v[86:89]
	v_mfma_f32_16x16x32_bf16 v[82:85], v[176:179], v[122:125], v[82:85]
	v_mfma_f32_16x16x32_bf16 v[78:81], v[184:187], v[106:109], v[78:81]
	v_mfma_f32_16x16x32_bf16 v[74:77], v[184:187], v[122:125], v[74:77]
	v_mfma_f32_16x16x32_bf16 v[70:73], v[192:195], v[106:109], v[70:73]
	v_mfma_f32_16x16x32_bf16 v[66:69], v[192:195], v[122:125], v[66:69]
	s_barrier
	ds_read_b128 v[142:145], v133 offset:16384
	ds_read_b128 v[164:167], v133 offset:17408
	ds_read_b128 v[168:171], v132 offset:16384
	ds_read_b128 v[172:175], v132 offset:17408
	ds_read_b128 v[176:179], v131 offset:16384
	ds_read_b128 v[180:183], v131 offset:17408
	ds_read_b128 v[184:187], v130 offset:16384
	ds_read_b128 v[188:191], v130 offset:17408
	s_waitcnt vmcnt(4)
	s_barrier
; #define WAIT_V(n) asm volatile("s_waitcnt vmcnt(" #n ")" ::: "memory")
; #define WAIT_L(n) asm volatile("s_waitcnt lgkmcnt(" #n ")" ::: "memory")
; #define BAR __builtin_amdgcn_s_barrier()
; __device__ __forceinline__ void mainloop_8phase(const u16* __restrict__ A, const u16* __restrict__ Bt, int K,
;                                                 f32x4 (&acc)[2][2][4][2], int wid_s, int ld) {
;     ...
;     LDA(At, 0, 1); WAIT_V(4); BAR; WAIT_L(0); MMA(1, 0, At, B0); MMA(1, 1, At, B1); BAR; }
;   { LDB(B0, 1, 0); LDA(At, 1, 0); WAIT_V(2); BAR; WAIT_L(0); MMA(0, 0, At, B0); BAR;
	s_waitcnt lgkmcnt(0)
	v_mfma_f32_16x16x32_bf16 v[62:65], v[142:145], v[138:141], v[62:65]
	v_mfma_f32_16x16x32_bf16 v[58:61], v[142:145], v[156:159], v[58:61]
	v_mfma_f32_16x16x32_bf16 v[54:57], v[168:171], v[138:141], v[54:57]
	v_mfma_f32_16x16x32_bf16 v[50:53], v[168:171], v[156:159], v[50:53]
	v_mfma_f32_16x16x32_bf16 v[46:49], v[176:179], v[138:141], v[46:49]
	v_mfma_f32_16x16x32_bf16 v[42:45], v[176:179], v[156:159], v[42:45]
	v_mfma_f32_16x16x32_bf16 v[38:41], v[184:187], v[138:141], v[38:41]
	v_mfma_f32_16x16x32_bf16 v[34:37], v[184:187], v[156:159], v[34:37]
	v_mfma_f32_16x16x32_bf16 v[192:195], v[164:167], v[152:155], v[62:65]
	v_mfma_f32_16x16x32_bf16 v[208:211], v[164:167], v[160:163], v[58:61]
	v_mfma_f32_16x16x32_bf16 v[212:215], v[172:175], v[152:155], v[54:57]
	v_mfma_f32_16x16x32_bf16 v[216:219], v[172:175], v[160:163], v[50:53]
	v_mfma_f32_16x16x32_bf16 v[220:223], v[180:183], v[152:155], v[46:49]
	v_mfma_f32_16x16x32_bf16 v[224:227], v[180:183], v[160:163], v[42:45]
	v_mfma_f32_16x16x32_bf16 v[136:139], v[188:191], v[152:155], v[38:41]
	v_mfma_f32_16x16x32_bf16 v[150:153], v[188:191], v[160:163], v[34:37]
	v_mfma_f32_16x16x32_bf16 v[30:33], v[142:145], v[98:101], v[30:33]
	v_mfma_f32_16x16x32_bf16 v[22:25], v[168:171], v[98:101], v[22:25]
	v_mfma_f32_16x16x32_bf16 v[14:17], v[176:179], v[98:101], v[14:17]
	v_mfma_f32_16x16x32_bf16 v[6:9], v[184:187], v[98:101], v[6:9]
	v_mfma_f32_16x16x32_bf16 v[30:33], v[164:167], v[106:109], v[30:33]
	v_mfma_f32_16x16x32_bf16 v[26:29], v[142:145], v[114:117], v[26:29]
	v_mfma_f32_16x16x32_bf16 v[22:25], v[172:175], v[106:109], v[22:25]
	v_mfma_f32_16x16x32_bf16 v[18:21], v[168:171], v[114:117], v[18:21]
	v_mfma_f32_16x16x32_bf16 v[14:17], v[180:183], v[106:109], v[14:17]
	v_mfma_f32_16x16x32_bf16 v[10:13], v[176:179], v[114:117], v[10:13]
	v_mfma_f32_16x16x32_bf16 v[6:9], v[188:191], v[106:109], v[6:9]
	v_mfma_f32_16x16x32_bf16 v[2:5], v[184:187], v[114:117], v[2:5]
	v_mfma_f32_16x16x32_bf16 v[140:143], v[164:167], v[122:125], v[26:29]
	v_mfma_f32_16x16x32_bf16 v[154:157], v[172:175], v[122:125], v[18:21]
	v_mfma_f32_16x16x32_bf16 v[158:161], v[180:183], v[122:125], v[10:13]
	v_mfma_f32_16x16x32_bf16 v[162:165], v[188:191], v[122:125], v[2:5]
	s_barrier
	s_nop 1
	ds_read_b128 v[2:5], v135
	ds_read_b128 v[166:169], v135 offset:1024
	ds_read_b128 v[170:173], v135 offset:2048
	ds_read_b128 v[174:177], v135 offset:3072
	ds_read_b128 v[10:13], v133 offset:32768
	ds_read_b128 v[18:21], v133 offset:33792
	ds_read_b128 v[26:29], v132 offset:32768
	ds_read_b128 v[38:41], v132 offset:33792
	ds_read_b128 v[46:49], v131 offset:32768
	ds_read_b128 v[178:181], v131 offset:33792
	ds_read_b128 v[182:185], v130 offset:32768
	ds_read_b128 v[186:189], v130 offset:33792
	s_waitcnt vmcnt(2)
	s_barrier
	s_waitcnt lgkmcnt(0)
	v_mfma_f32_16x16x32_bf16 v[34:37], v[10:13], v[2:5], v[126:129]
	v_mfma_f32_16x16x32_bf16 v[122:125], v[18:21], v[166:169], v[34:37]
	v_mfma_f32_16x16x32_bf16 v[34:37], v[10:13], v[170:173], v[146:149]
	v_mfma_f32_16x16x32_bf16 v[58:61], v[18:21], v[174:177], v[34:37]
	v_mfma_f32_16x16x32_bf16 v[34:37], v[26:29], v[2:5], v[118:121]
	v_mfma_f32_16x16x32_bf16 v[114:117], v[38:41], v[166:169], v[34:37]
	v_mfma_f32_16x16x32_bf16 v[34:37], v[26:29], v[170:173], v[196:199]
	v_mfma_f32_16x16x32_bf16 v[50:53], v[38:41], v[174:177], v[34:37]
	v_mfma_f32_16x16x32_bf16 v[34:37], v[46:49], v[2:5], v[110:113]
	v_mfma_f32_16x16x32_bf16 v[106:109], v[178:181], v[166:169], v[34:37]
	v_mfma_f32_16x16x32_bf16 v[34:37], v[46:49], v[170:173], v[200:203]
	v_mfma_f32_16x16x32_bf16 v[42:45], v[178:181], v[174:177], v[34:37]
	v_mfma_f32_16x16x32_bf16 v[34:37], v[182:185], v[2:5], v[102:105]
	v_mfma_f32_16x16x32_bf16 v[98:101], v[186:189], v[166:169], v[34:37]
	v_mfma_f32_16x16x32_bf16 v[34:37], v[182:185], v[170:173], v[204:207]
	v_mfma_f32_16x16x32_bf16 v[34:37], v[186:189], v[174:177], v[34:37]
	s_barrier
; #define WAIT_V(n) asm volatile("s_waitcnt vmcnt(" #n ")" ::: "memory")
; #define WAIT_L(n) asm volatile("s_waitcnt lgkmcnt(" #n ")" ::: "memory")
; #define BAR __builtin_amdgcn_s_barrier()
; __device__ __forceinline__ void mainloop_8phase(const u16* __restrict__ A, const u16* __restrict__ Bt, int K,
;                                                 f32x4 (&acc)[2][2][4][2], int wid_s, int ld) {
;     ...
;   { LDB(B0, 1, 0); LDA(At, 1, 0); WAIT_V(2); BAR; WAIT_L(0); MMA(0, 0, At, B0); BAR;
;     LDB(B1, 1, 1); WAIT_V(0); BAR; WAIT_L(0); MMA(0, 1, At, B1); BAR;
;     LDA(At, 1, 1); BAR; WAIT_L(0); MMA(1, 0, At, B0); MMA(1, 1, At, B1); BAR; }
;   if (wr == 0) BAR;
	ds_read_b128 v[144:147], v134
	ds_read_b128 v[196:199], v134 offset:1024
	ds_read_b128 v[200:203], v134 offset:2048
	ds_read_b128 v[204:207], v134 offset:3072
	s_waitcnt vmcnt(0)
	s_barrier
	s_waitcnt lgkmcnt(0)
	v_mfma_f32_16x16x32_bf16 v[54:57], v[10:13], v[144:147], v[94:97]
	v_mfma_f32_16x16x32_bf16 v[10:13], v[10:13], v[200:203], v[90:93]
	v_mfma_f32_16x16x32_bf16 v[62:65], v[18:21], v[204:207], v[10:13]
	v_mfma_f32_16x16x32_bf16 v[10:13], v[26:29], v[144:147], v[86:89]
	v_mfma_f32_16x16x32_bf16 v[118:121], v[38:41], v[196:199], v[10:13]
	v_mfma_f32_16x16x32_bf16 v[10:13], v[26:29], v[200:203], v[82:85]
	v_mfma_f32_16x16x32_bf16 v[126:129], v[18:21], v[196:199], v[54:57]
	v_mfma_f32_16x16x32_bf16 v[54:57], v[38:41], v[204:207], v[10:13]
	v_mfma_f32_16x16x32_bf16 v[10:13], v[46:49], v[144:147], v[78:81]
	v_mfma_f32_16x16x32_bf16 v[110:113], v[178:181], v[196:199], v[10:13]
	v_mfma_f32_16x16x32_bf16 v[10:13], v[46:49], v[200:203], v[74:77]
	v_mfma_f32_16x16x32_bf16 v[46:49], v[178:181], v[204:207], v[10:13]
	v_mfma_f32_16x16x32_bf16 v[10:13], v[182:185], v[144:147], v[70:73]
	v_mfma_f32_16x16x32_bf16 v[102:105], v[186:189], v[196:199], v[10:13]
	v_mfma_f32_16x16x32_bf16 v[10:13], v[182:185], v[200:203], v[66:69]
	v_mfma_f32_16x16x32_bf16 v[38:41], v[186:189], v[204:207], v[10:13]
	s_barrier
	ds_read_b128 v[70:73], v133 offset:49152
	ds_read_b128 v[78:81], v133 offset:50176
	ds_read_b128 v[178:181], v132 offset:49152
	ds_read_b128 v[132:135], v132 offset:50176
	ds_read_b128 v[182:185], v131 offset:49152
	ds_read_b128 v[186:189], v131 offset:50176
	ds_read_b128 v[228:231], v130 offset:49152
	ds_read_b128 v[232:235], v130 offset:50176
	s_barrier
	s_waitcnt lgkmcnt(0)
	v_mfma_f32_16x16x32_bf16 v[10:13], v[70:73], v[2:5], v[192:195]
	v_mfma_f32_16x16x32_bf16 v[90:93], v[78:81], v[166:169], v[10:13]
	v_mfma_f32_16x16x32_bf16 v[10:13], v[70:73], v[170:173], v[208:211]
	v_mfma_f32_16x16x32_bf16 v[26:29], v[78:81], v[174:177], v[10:13]
	v_mfma_f32_16x16x32_bf16 v[10:13], v[178:181], v[2:5], v[212:215]
	v_mfma_f32_16x16x32_bf16 v[82:85], v[132:135], v[166:169], v[10:13]
	v_mfma_f32_16x16x32_bf16 v[10:13], v[178:181], v[170:173], v[216:219]
	v_mfma_f32_16x16x32_bf16 v[18:21], v[132:135], v[174:177], v[10:13]
	v_mfma_f32_16x16x32_bf16 v[10:13], v[182:185], v[2:5], v[220:223]
	v_mfma_f32_16x16x32_bf16 v[2:5], v[228:231], v[2:5], v[136:139]
	v_mfma_f32_16x16x32_bf16 v[74:77], v[186:189], v[166:169], v[10:13]
	v_mfma_f32_16x16x32_bf16 v[10:13], v[182:185], v[170:173], v[224:227]
	v_mfma_f32_16x16x32_bf16 v[66:69], v[232:235], v[166:169], v[2:5]
	v_mfma_f32_16x16x32_bf16 v[2:5], v[228:231], v[170:173], v[150:153]
	v_mfma_f32_16x16x32_bf16 v[10:13], v[186:189], v[174:177], v[10:13]
	v_mfma_f32_16x16x32_bf16 v[2:5], v[232:235], v[174:177], v[2:5]
	v_mfma_f32_16x16x32_bf16 v[30:33], v[70:73], v[144:147], v[30:33]
	v_mfma_f32_16x16x32_bf16 v[94:97], v[78:81], v[196:199], v[30:33]
	v_mfma_f32_16x16x32_bf16 v[30:33], v[70:73], v[200:203], v[140:143]
	v_mfma_f32_16x16x32_bf16 v[22:25], v[178:181], v[144:147], v[22:25]
	v_mfma_f32_16x16x32_bf16 v[14:17], v[182:185], v[144:147], v[14:17]
	v_mfma_f32_16x16x32_bf16 v[6:9], v[228:231], v[144:147], v[6:9]
	v_mfma_f32_16x16x32_bf16 v[30:33], v[78:81], v[204:207], v[30:33]
	v_mfma_f32_16x16x32_bf16 v[86:89], v[132:135], v[196:199], v[22:25]
	v_mfma_f32_16x16x32_bf16 v[22:25], v[178:181], v[200:203], v[154:157]
	v_mfma_f32_16x16x32_bf16 v[78:81], v[186:189], v[196:199], v[14:17]
	v_mfma_f32_16x16x32_bf16 v[14:17], v[182:185], v[200:203], v[158:161]
	v_mfma_f32_16x16x32_bf16 v[70:73], v[232:235], v[196:199], v[6:9]
	v_mfma_f32_16x16x32_bf16 v[6:9], v[228:231], v[200:203], v[162:165]
	v_mfma_f32_16x16x32_bf16 v[22:25], v[132:135], v[204:207], v[22:25]
	v_mfma_f32_16x16x32_bf16 v[14:17], v[186:189], v[204:207], v[14:17]
	v_mfma_f32_16x16x32_bf16 v[6:9], v[232:235], v[204:207], v[6:9]
	s_movk_i32 s2, 0x100
	v_cmp_gt_u32_e32 vcc, s2, v0
	s_barrier
	s_and_saveexec_b64 s[2:3], vcc
	s_cbranch_execz .LBB0_165
	s_barrier

; #define WAIT_V(n) asm volatile("s_waitcnt vmcnt(" #n ")" ::: "memory")
; #define WAIT_L(n) asm volatile("s_waitcnt lgkmcnt(" #n ")" ::: "memory")
; #define BAR __builtin_amdgcn_s_barrier()
; #define SCHED __builtin_amdgcn_sched_barrier(0)
; __device__ __forceinline__ void mainloop_8phase(const u16* __restrict__ A, const u16* __restrict__ Bt, int K,
;                                                 f32x4 (&acc)[2][2][4][2], int wid_s, int ld) {
;     ...
;     LDB(B0, 0, 0); SCHED; LDA(At, 0, 0); STAGE(SA(1, 1), A, brow + G_HALF, t + 1);
;     WAIT_L(8); BAR; WAIT_L(0); MMA(0, 0, At, B0); BAR; SCHED;
;     LDB(B1, 0, 1); STAGE(SB(0, 0), Bt, bcol, t + 2);
;     BAR; WAIT_L(0); MMA(0, 1, At, B1); BAR;
;     LDA(At, 0, 1); STAGE(SA(0, 0), A, brow, t + 2);
;     BAR; WAIT_L(0); MMA(1, 0, At, B0); BAR; SCHED;
;     STAGE(SB(0, 1), Bt, bcol + G_HALF, t + 2);
;     WAIT_V(6); BAR; MMA(1, 1, At, B1); BAR;
.LBB0_247:
	ds_read_b128 v[156:159], v155
	ds_read_b128 v[160:163], v155 offset:1024
	ds_read_b128 v[164:167], v155 offset:2048
	ds_read_b128 v[168:171], v155 offset:3072
	s_add_i32 s3, s1, 0xffffff00
	s_add_i32 m0, s100, 0xc000
	ds_read_b128 v[172:175], v133
	ds_read_b128 v[176:179], v133 offset:1024
	ds_read_b128 v[180:183], v132
	ds_read_b128 v[184:187], v132 offset:1024
	ds_read_b128 v[188:191], v131
	ds_read_b128 v[192:195], v131 offset:1024
	ds_read_b128 v[196:199], v130
	buffer_load_dwordx4 v137, s[88:91], s3 offen lds
	s_add_i32 m0, s100, 0xe000
	ds_read_b128 v[200:203], v130 offset:1024
	buffer_load_dwordx4 v136, s[88:91], s3 offen lds
	s_waitcnt lgkmcnt(8)
	s_barrier
	s_waitcnt lgkmcnt(1)
	v_mfma_f32_16x16x32_bf16 v[126:129], v[172:175], v[156:159], v[126:129]
	v_mfma_f32_16x16x32_bf16 v[122:125], v[172:175], v[164:167], v[122:125]
	v_mfma_f32_16x16x32_bf16 v[118:121], v[180:183], v[156:159], v[118:121]
	v_mfma_f32_16x16x32_bf16 v[114:117], v[180:183], v[164:167], v[114:117]
	v_mfma_f32_16x16x32_bf16 v[110:113], v[188:191], v[156:159], v[110:113]
	v_mfma_f32_16x16x32_bf16 v[106:109], v[188:191], v[164:167], v[106:109]
	v_mfma_f32_16x16x32_bf16 v[102:105], v[196:199], v[156:159], v[102:105]
	v_mfma_f32_16x16x32_bf16 v[98:101], v[196:199], v[164:167], v[98:101]
	v_mfma_f32_16x16x32_bf16 v[126:129], v[176:179], v[160:163], v[126:129]
	v_mfma_f32_16x16x32_bf16 v[122:125], v[176:179], v[168:171], v[122:125]
	v_mfma_f32_16x16x32_bf16 v[118:121], v[184:187], v[160:163], v[118:121]
	v_mfma_f32_16x16x32_bf16 v[114:117], v[184:187], v[168:171], v[114:117]
	v_mfma_f32_16x16x32_bf16 v[110:113], v[192:195], v[160:163], v[110:113]
	v_mfma_f32_16x16x32_bf16 v[106:109], v[192:195], v[168:171], v[106:109]
	s_waitcnt lgkmcnt(0)
	v_mfma_f32_16x16x32_bf16 v[102:105], v[200:203], v[160:163], v[102:105]
	v_mfma_f32_16x16x32_bf16 v[98:101], v[200:203], v[168:171], v[98:101]
	s_barrier
	s_add_i32 s3, s1, 0xfff7ff80
	s_add_i32 m0, s100, 0x10000
	ds_read_b128 v[204:207], v147
	ds_read_b128 v[208:211], v147 offset:1024
	ds_read_b128 v[212:215], v147 offset:2048
	buffer_load_dwordx4 v137, s[4:7], s3 offen lds
	s_add_i32 m0, s100, 0x12000
	ds_read_b128 v[216:219], v147 offset:3072
	buffer_load_dwordx4 v136, s[4:7], s3 offen lds
	s_barrier
	s_waitcnt lgkmcnt(1)
	v_mfma_f32_16x16x32_bf16 v[94:97], v[172:175], v[204:207], v[94:97]
	v_mfma_f32_16x16x32_bf16 v[90:93], v[172:175], v[212:215], v[90:93]
	v_mfma_f32_16x16x32_bf16 v[86:89], v[180:183], v[204:207], v[86:89]
	v_mfma_f32_16x16x32_bf16 v[82:85], v[180:183], v[212:215], v[82:85]
	v_mfma_f32_16x16x32_bf16 v[78:81], v[188:191], v[204:207], v[78:81]
	v_mfma_f32_16x16x32_bf16 v[74:77], v[188:191], v[212:215], v[74:77]
	v_mfma_f32_16x16x32_bf16 v[70:73], v[196:199], v[204:207], v[70:73]
	v_mfma_f32_16x16x32_bf16 v[66:69], v[196:199], v[212:215], v[66:69]
	v_mfma_f32_16x16x32_bf16 v[94:97], v[176:179], v[208:211], v[94:97]
	s_waitcnt lgkmcnt(0)
	v_mfma_f32_16x16x32_bf16 v[90:93], v[176:179], v[216:219], v[90:93]
	v_mfma_f32_16x16x32_bf16 v[86:89], v[184:187], v[208:211], v[86:89]
	v_mfma_f32_16x16x32_bf16 v[82:85], v[184:187], v[216:219], v[82:85]
	v_mfma_f32_16x16x32_bf16 v[78:81], v[192:195], v[208:211], v[78:81]
	v_mfma_f32_16x16x32_bf16 v[74:77], v[192:195], v[216:219], v[74:77]
	v_mfma_f32_16x16x32_bf16 v[70:73], v[200:203], v[208:211], v[70:73]
	v_mfma_f32_16x16x32_bf16 v[66:69], v[200:203], v[216:219], v[66:69]
	s_mov_b32 m0, s100
	s_barrier
	ds_read_b128 v[172:175], v133 offset:16384
	ds_read_b128 v[176:179], v133 offset:17408
	ds_read_b128 v[180:183], v132 offset:16384
	ds_read_b128 v[184:187], v132 offset:17408
	ds_read_b128 v[188:191], v131 offset:16384
	ds_read_b128 v[192:195], v131 offset:17408
	ds_read_b128 v[196:199], v130 offset:16384
	buffer_load_dwordx4 v137, s[88:91], s3 offen lds
	s_add_i32 m0, s100, 0x2000
	ds_read_b128 v[200:203], v130 offset:17408
	buffer_load_dwordx4 v136, s[88:91], s3 offen lds
	s_barrier
	s_waitcnt lgkmcnt(1)
	v_mfma_f32_16x16x32_bf16 v[62:65], v[172:175], v[156:159], v[62:65]
	v_mfma_f32_16x16x32_bf16 v[58:61], v[172:175], v[164:167], v[58:61]
	v_mfma_f32_16x16x32_bf16 v[54:57], v[180:183], v[156:159], v[54:57]
	v_mfma_f32_16x16x32_bf16 v[50:53], v[180:183], v[164:167], v[50:53]
	v_mfma_f32_16x16x32_bf16 v[46:49], v[188:191], v[156:159], v[46:49]
	v_mfma_f32_16x16x32_bf16 v[42:45], v[188:191], v[164:167], v[42:45]
	v_mfma_f32_16x16x32_bf16 v[38:41], v[196:199], v[156:159], v[38:41]
	v_mfma_f32_16x16x32_bf16 v[34:37], v[196:199], v[164:167], v[34:37]
	v_mfma_f32_16x16x32_bf16 v[62:65], v[176:179], v[160:163], v[62:65]
	v_mfma_f32_16x16x32_bf16 v[58:61], v[176:179], v[168:171], v[58:61]
	v_mfma_f32_16x16x32_bf16 v[54:57], v[184:187], v[160:163], v[54:57]
	v_mfma_f32_16x16x32_bf16 v[50:53], v[184:187], v[168:171], v[50:53]
	v_mfma_f32_16x16x32_bf16 v[46:49], v[192:195], v[160:163], v[46:49]
	v_mfma_f32_16x16x32_bf16 v[42:45], v[192:195], v[168:171], v[42:45]
	s_waitcnt lgkmcnt(0)
	v_mfma_f32_16x16x32_bf16 v[38:41], v[200:203], v[160:163], v[38:41]
	v_mfma_f32_16x16x32_bf16 v[34:37], v[200:203], v[168:171], v[34:37]
	s_barrier
	s_add_i32 s3, s1, 0xffffff80
	s_add_i32 m0, s100, 0x14000
	buffer_load_dwordx4 v137, s[4:7], s3 offen lds
	s_add_i32 m0, s100, 0x16000
	s_nop 0
	buffer_load_dwordx4 v136, s[4:7], s3 offen lds
	s_waitcnt vmcnt(6)
	s_barrier
; #define WAIT_V(n) asm volatile("s_waitcnt vmcnt(" #n ")" ::: "memory")
; #define WAIT_L(n) asm volatile("s_waitcnt lgkmcnt(" #n ")" ::: "memory")
; #define BAR __builtin_amdgcn_s_barrier()
; #define SCHED __builtin_amdgcn_sched_barrier(0)
; __device__ __forceinline__ void mainloop_8phase(const u16* __restrict__ A, const u16* __restrict__ Bt, int K,
;                                                 f32x4 (&acc)[2][2][4][2], int wid_s, int ld) {
;     ...
;     LDB(B0, 1, 0); SCHED; LDA(At, 1, 0); STAGE(SA(0, 1), A, brow + G_HALF, t + 2);
;     WAIT_L(8); BAR; WAIT_L(0); MMA(0, 0, At, B0); BAR; SCHED;
;     LDB(B1, 1, 1); STAGE(SB(1, 0), Bt, bcol, t + 3);
;     BAR; WAIT_L(0); MMA(0, 1, At, B1); BAR;
;     LDA(At, 1, 1); STAGE(SA(1, 0), A, brow, t + 3);
;     BAR; WAIT_L(0); MMA(1, 0, At, B0); BAR; SCHED;
;     STAGE(SB(1, 1), Bt, bcol + G_HALF, t + 3);
;     WAIT_V(6); BAR; MMA(1, 1, At, B1); BAR;
	v_mfma_f32_16x16x32_bf16 v[30:33], v[172:175], v[204:207], v[30:33]
	v_mfma_f32_16x16x32_bf16 v[26:29], v[172:175], v[212:215], v[26:29]
	v_mfma_f32_16x16x32_bf16 v[22:25], v[180:183], v[204:207], v[22:25]
	v_mfma_f32_16x16x32_bf16 v[18:21], v[180:183], v[212:215], v[18:21]
	v_mfma_f32_16x16x32_bf16 v[14:17], v[188:191], v[204:207], v[14:17]
	v_mfma_f32_16x16x32_bf16 v[10:13], v[188:191], v[212:215], v[10:13]
	v_mfma_f32_16x16x32_bf16 v[6:9], v[196:199], v[204:207], v[6:9]
	v_mfma_f32_16x16x32_bf16 v[2:5], v[196:199], v[212:215], v[2:5]
	v_mfma_f32_16x16x32_bf16 v[30:33], v[176:179], v[208:211], v[30:33]
	v_mfma_f32_16x16x32_bf16 v[26:29], v[176:179], v[216:219], v[26:29]
	v_mfma_f32_16x16x32_bf16 v[22:25], v[184:187], v[208:211], v[22:25]
	v_mfma_f32_16x16x32_bf16 v[18:21], v[184:187], v[216:219], v[18:21]
	v_mfma_f32_16x16x32_bf16 v[14:17], v[192:195], v[208:211], v[14:17]
	v_mfma_f32_16x16x32_bf16 v[10:13], v[192:195], v[216:219], v[10:13]
	v_mfma_f32_16x16x32_bf16 v[6:9], v[200:203], v[208:211], v[6:9]
	v_mfma_f32_16x16x32_bf16 v[2:5], v[200:203], v[216:219], v[2:5]
	s_barrier
	ds_read_b128 v[156:159], v135
	ds_read_b128 v[160:163], v135 offset:1024
	ds_read_b128 v[164:167], v135 offset:2048
	ds_read_b128 v[168:171], v135 offset:3072
	s_add_i32 m0, s100, 0x4000
	ds_read_b128 v[172:175], v133 offset:32768
	ds_read_b128 v[176:179], v133 offset:33792
	ds_read_b128 v[180:183], v132 offset:32768
	ds_read_b128 v[184:187], v132 offset:33792
	ds_read_b128 v[188:191], v131 offset:32768
	ds_read_b128 v[192:195], v131 offset:33792
	ds_read_b128 v[196:199], v130 offset:32768
	buffer_load_dwordx4 v137, s[88:91], s3 offen lds
	s_add_i32 m0, s100, 0x6000
	ds_read_b128 v[200:203], v130 offset:33792
	buffer_load_dwordx4 v136, s[88:91], s3 offen lds
	s_waitcnt lgkmcnt(8)
	s_barrier
	s_waitcnt lgkmcnt(1)
	v_mfma_f32_16x16x32_bf16 v[126:129], v[172:175], v[156:159], v[126:129]
	v_mfma_f32_16x16x32_bf16 v[122:125], v[172:175], v[164:167], v[122:125]
	v_mfma_f32_16x16x32_bf16 v[118:121], v[180:183], v[156:159], v[118:121]
	v_mfma_f32_16x16x32_bf16 v[114:117], v[180:183], v[164:167], v[114:117]
	v_mfma_f32_16x16x32_bf16 v[110:113], v[188:191], v[156:159], v[110:113]
	v_mfma_f32_16x16x32_bf16 v[106:109], v[188:191], v[164:167], v[106:109]
	v_mfma_f32_16x16x32_bf16 v[102:105], v[196:199], v[156:159], v[102:105]
	v_mfma_f32_16x16x32_bf16 v[98:101], v[196:199], v[164:167], v[98:101]
	v_mfma_f32_16x16x32_bf16 v[126:129], v[176:179], v[160:163], v[126:129]
	v_mfma_f32_16x16x32_bf16 v[122:125], v[176:179], v[168:171], v[122:125]
	v_mfma_f32_16x16x32_bf16 v[118:121], v[184:187], v[160:163], v[118:121]
	v_mfma_f32_16x16x32_bf16 v[114:117], v[184:187], v[168:171], v[114:117]
	v_mfma_f32_16x16x32_bf16 v[110:113], v[192:195], v[160:163], v[110:113]
	v_mfma_f32_16x16x32_bf16 v[106:109], v[192:195], v[168:171], v[106:109]
	s_waitcnt lgkmcnt(0)
	v_mfma_f32_16x16x32_bf16 v[102:105], v[200:203], v[160:163], v[102:105]
	v_mfma_f32_16x16x32_bf16 v[98:101], v[200:203], v[168:171], v[98:101]
	s_barrier
	s_add_i32 s3, s1, 0xfff80000
	s_add_i32 m0, s100, 0x18000
	ds_read_b128 v[204:207], v134
	ds_read_b128 v[208:211], v134 offset:1024
	ds_read_b128 v[212:215], v134 offset:2048
	buffer_load_dwordx4 v137, s[4:7], s3 offen lds
	s_add_i32 m0, s100, 0x1a000
	ds_read_b128 v[216:219], v134 offset:3072
	buffer_load_dwordx4 v136, s[4:7], s3 offen lds
	s_barrier
	s_waitcnt lgkmcnt(1)
	v_mfma_f32_16x16x32_bf16 v[94:97], v[172:175], v[204:207], v[94:97]
	v_mfma_f32_16x16x32_bf16 v[90:93], v[172:175], v[212:215], v[90:93]
	v_mfma_f32_16x16x32_bf16 v[86:89], v[180:183], v[204:207], v[86:89]
	v_mfma_f32_16x16x32_bf16 v[82:85], v[180:183], v[212:215], v[82:85]
	v_mfma_f32_16x16x32_bf16 v[78:81], v[188:191], v[204:207], v[78:81]
	v_mfma_f32_16x16x32_bf16 v[74:77], v[188:191], v[212:215], v[74:77]
	v_mfma_f32_16x16x32_bf16 v[70:73], v[196:199], v[204:207], v[70:73]
	v_mfma_f32_16x16x32_bf16 v[66:69], v[196:199], v[212:215], v[66:69]
	v_mfma_f32_16x16x32_bf16 v[94:97], v[176:179], v[208:211], v[94:97]
	s_waitcnt lgkmcnt(0)
	v_mfma_f32_16x16x32_bf16 v[90:93], v[176:179], v[216:219], v[90:93]
	v_mfma_f32_16x16x32_bf16 v[86:89], v[184:187], v[208:211], v[86:89]
	v_mfma_f32_16x16x32_bf16 v[82:85], v[184:187], v[216:219], v[82:85]
	v_mfma_f32_16x16x32_bf16 v[78:81], v[192:195], v[208:211], v[78:81]
	v_mfma_f32_16x16x32_bf16 v[74:77], v[192:195], v[216:219], v[74:77]
	v_mfma_f32_16x16x32_bf16 v[70:73], v[200:203], v[208:211], v[70:73]
	v_mfma_f32_16x16x32_bf16 v[66:69], v[200:203], v[216:219], v[66:69]
	s_add_i32 m0, s100, 0x8000
	s_barrier
	ds_read_b128 v[172:175], v133 offset:49152
	ds_read_b128 v[176:179], v133 offset:50176
	ds_read_b128 v[180:183], v132 offset:49152
	ds_read_b128 v[184:187], v132 offset:50176
	ds_read_b128 v[188:191], v131 offset:49152
	ds_read_b128 v[192:195], v131 offset:50176
	ds_read_b128 v[196:199], v130 offset:49152
	buffer_load_dwordx4 v137, s[88:91], s3 offen lds
	s_add_i32 m0, s100, 0xa000
	ds_read_b128 v[200:203], v130 offset:50176
	buffer_load_dwordx4 v136, s[88:91], s3 offen lds
	s_barrier
	s_waitcnt lgkmcnt(1)
	v_mfma_f32_16x16x32_bf16 v[62:65], v[172:175], v[156:159], v[62:65]
	v_mfma_f32_16x16x32_bf16 v[58:61], v[172:175], v[164:167], v[58:61]
	v_mfma_f32_16x16x32_bf16 v[54:57], v[180:183], v[156:159], v[54:57]
	v_mfma_f32_16x16x32_bf16 v[50:53], v[180:183], v[164:167], v[50:53]
	v_mfma_f32_16x16x32_bf16 v[46:49], v[188:191], v[156:159], v[46:49]
	v_mfma_f32_16x16x32_bf16 v[42:45], v[188:191], v[164:167], v[42:45]
	v_mfma_f32_16x16x32_bf16 v[38:41], v[196:199], v[156:159], v[38:41]
	v_mfma_f32_16x16x32_bf16 v[34:37], v[196:199], v[164:167], v[34:37]
	v_mfma_f32_16x16x32_bf16 v[62:65], v[176:179], v[160:163], v[62:65]
	v_mfma_f32_16x16x32_bf16 v[58:61], v[176:179], v[168:171], v[58:61]
	v_mfma_f32_16x16x32_bf16 v[54:57], v[184:187], v[160:163], v[54:57]
	v_mfma_f32_16x16x32_bf16 v[50:53], v[184:187], v[168:171], v[50:53]
	v_mfma_f32_16x16x32_bf16 v[46:49], v[192:195], v[160:163], v[46:49]
	v_mfma_f32_16x16x32_bf16 v[42:45], v[192:195], v[168:171], v[42:45]
	s_waitcnt lgkmcnt(0)
	v_mfma_f32_16x16x32_bf16 v[38:41], v[200:203], v[160:163], v[38:41]
	v_mfma_f32_16x16x32_bf16 v[34:37], v[200:203], v[168:171], v[34:37]
	s_barrier
; #define WAIT_V(n) asm volatile("s_waitcnt vmcnt(" #n ")" ::: "memory")
; #define WAIT_L(n) asm volatile("s_waitcnt lgkmcnt(" #n ")" ::: "memory")
; #define BAR __builtin_amdgcn_s_barrier()
; __device__ __forceinline__ void mainloop_8phase(const u16* __restrict__ A, const u16* __restrict__ Bt, int K,
;                                                 f32x4 (&acc)[2][2][4][2], int wid_s, int ld) {
;     ...
;     WAIT_V(6); BAR; MMA(1, 1, At, B1); BAR;
;   }
;   { LDB(B0, 0, 0); LDA(At, 0, 0); STAGE(SA(1, 1), A, brow + G_HALF, nt - 1);
;     BAR; WAIT_L(0); MMA(0, 0, At, B0); BAR;
;     LDB(B1, 0, 1); BAR; WAIT_L(0); MMA(0, 1, At, B1); BAR;
;     LDA(At, 0, 1); WAIT_V(4); BAR; WAIT_L(0); MMA(1, 0, At, B0); MMA(1, 1, At, B1); BAR; }
	s_add_i32 m0, s100, 0x1c000
	buffer_load_dwordx4 v137, s[4:7], s1 offen lds
	s_add_i32 m0, s100, 0x1e000
	s_nop 0
	buffer_load_dwordx4 v136, s[4:7], s1 offen lds
	s_waitcnt vmcnt(6)
	s_barrier
	v_mfma_f32_16x16x32_bf16 v[30:33], v[172:175], v[204:207], v[30:33]
	v_mfma_f32_16x16x32_bf16 v[26:29], v[172:175], v[212:215], v[26:29]
	v_mfma_f32_16x16x32_bf16 v[22:25], v[180:183], v[204:207], v[22:25]
	v_mfma_f32_16x16x32_bf16 v[18:21], v[180:183], v[212:215], v[18:21]
	v_mfma_f32_16x16x32_bf16 v[14:17], v[188:191], v[204:207], v[14:17]
	v_mfma_f32_16x16x32_bf16 v[10:13], v[188:191], v[212:215], v[10:13]
	v_mfma_f32_16x16x32_bf16 v[6:9], v[196:199], v[204:207], v[6:9]
	v_mfma_f32_16x16x32_bf16 v[2:5], v[196:199], v[212:215], v[2:5]
	v_mfma_f32_16x16x32_bf16 v[30:33], v[176:179], v[208:211], v[30:33]
	v_mfma_f32_16x16x32_bf16 v[26:29], v[176:179], v[216:219], v[26:29]
	v_mfma_f32_16x16x32_bf16 v[22:25], v[184:187], v[208:211], v[22:25]
	v_mfma_f32_16x16x32_bf16 v[18:21], v[184:187], v[216:219], v[18:21]
	v_mfma_f32_16x16x32_bf16 v[14:17], v[192:195], v[208:211], v[14:17]
	v_mfma_f32_16x16x32_bf16 v[10:13], v[192:195], v[216:219], v[10:13]
	v_mfma_f32_16x16x32_bf16 v[6:9], v[200:203], v[208:211], v[6:9]
	v_mfma_f32_16x16x32_bf16 v[2:5], v[200:203], v[216:219], v[2:5]
	s_add_i32 s0, s0, 2
	s_addk_i32 s1, 0x100
	s_cmp_lt_u32 s0, 28
	s_barrier
	s_cbranch_scc1 .LBB0_247
	v_readfirstlane_b32 s0, v145
	s_mov_b32 m0, s0
	s_mov_b32 s1, 0x80f80
	v_readfirstlane_b32 s0, v144
	ds_read_b128 v[138:141], v155
	ds_read_b128 v[148:151], v155 offset:1024
	ds_read_b128 v[156:159], v155 offset:2048
	ds_read_b128 v[152:155], v155 offset:3072
	ds_read_b128 v[160:163], v133
	ds_read_b128 v[164:167], v133 offset:1024
	ds_read_b128 v[168:171], v132
	ds_read_b128 v[172:175], v132 offset:1024
	ds_read_b128 v[176:179], v131
	ds_read_b128 v[180:183], v131 offset:1024
	ds_read_b128 v[184:187], v130
	ds_read_b128 v[188:191], v130 offset:1024
	buffer_load_dwordx4 v137, s[88:91], s1 offen lds
	s_mov_b32 m0, s0
	s_nop 0
	buffer_load_dwordx4 v136, s[88:91], s1 offen lds
	s_barrier
	s_waitcnt lgkmcnt(0)
	v_mfma_f32_16x16x32_bf16 v[126:129], v[160:163], v[138:141], v[126:129]
	v_mfma_f32_16x16x32_bf16 v[118:121], v[168:171], v[138:141], v[118:121]
	v_mfma_f32_16x16x32_bf16 v[110:113], v[176:179], v[138:141], v[110:113]
	v_mfma_f32_16x16x32_bf16 v[102:105], v[184:187], v[138:141], v[102:105]
	v_mfma_f32_16x16x32_bf16 v[126:129], v[164:167], v[148:151], v[126:129]
	v_mfma_f32_16x16x32_bf16 v[122:125], v[160:163], v[156:159], v[122:125]
	v_mfma_f32_16x16x32_bf16 v[118:121], v[172:175], v[148:151], v[118:121]
	v_mfma_f32_16x16x32_bf16 v[114:117], v[168:171], v[156:159], v[114:117]
	v_mfma_f32_16x16x32_bf16 v[110:113], v[180:183], v[148:151], v[110:113]
	v_mfma_f32_16x16x32_bf16 v[106:109], v[176:179], v[156:159], v[106:109]
	v_mfma_f32_16x16x32_bf16 v[102:105], v[188:191], v[148:151], v[102:105]
	v_mfma_f32_16x16x32_bf16 v[98:101], v[184:187], v[156:159], v[98:101]
	v_mfma_f32_16x16x32_bf16 v[142:145], v[164:167], v[152:155], v[122:125]
	v_mfma_f32_16x16x32_bf16 v[192:195], v[172:175], v[152:155], v[114:117]
	v_mfma_f32_16x16x32_bf16 v[196:199], v[180:183], v[152:155], v[106:109]
	v_mfma_f32_16x16x32_bf16 v[200:203], v[188:191], v[152:155], v[98:101]
	s_barrier
	s_nop 1
	ds_read_b128 v[98:101], v147
	ds_read_b128 v[106:109], v147 offset:1024
	ds_read_b128 v[114:117], v147 offset:2048
	ds_read_b128 v[122:125], v147 offset:3072
	s_barrier
	s_waitcnt lgkmcnt(0)
	v_mfma_f32_16x16x32_bf16 v[94:97], v[160:163], v[98:101], v[94:97]
	v_mfma_f32_16x16x32_bf16 v[90:93], v[160:163], v[114:117], v[90:93]
	v_mfma_f32_16x16x32_bf16 v[86:89], v[168:171], v[98:101], v[86:89]
	v_mfma_f32_16x16x32_bf16 v[82:85], v[168:171], v[114:117], v[82:85]
	v_mfma_f32_16x16x32_bf16 v[78:81], v[176:179], v[98:101], v[78:81]
	v_mfma_f32_16x16x32_bf16 v[74:77], v[176:179], v[114:117], v[74:77]
	v_mfma_f32_16x16x32_bf16 v[70:73], v[184:187], v[98:101], v[70:73]
	v_mfma_f32_16x16x32_bf16 v[66:69], v[184:187], v[114:117], v[66:69]
	v_mfma_f32_16x16x32_bf16 v[94:97], v[164:167], v[106:109], v[94:97]
	v_mfma_f32_16x16x32_bf16 v[90:93], v[164:167], v[122:125], v[90:93]
	v_mfma_f32_16x16x32_bf16 v[86:89], v[172:175], v[106:109], v[86:89]
	v_mfma_f32_16x16x32_bf16 v[82:85], v[172:175], v[122:125], v[82:85]
	v_mfma_f32_16x16x32_bf16 v[78:81], v[180:183], v[106:109], v[78:81]
	v_mfma_f32_16x16x32_bf16 v[74:77], v[180:183], v[122:125], v[74:77]
	v_mfma_f32_16x16x32_bf16 v[70:73], v[188:191], v[106:109], v[70:73]
	v_mfma_f32_16x16x32_bf16 v[66:69], v[188:191], v[122:125], v[66:69]
	s_barrier
	ds_read_b128 v[160:163], v133 offset:16384
	ds_read_b128 v[164:167], v133 offset:17408
	ds_read_b128 v[168:171], v132 offset:16384
	ds_read_b128 v[172:175], v132 offset:17408
	ds_read_b128 v[176:179], v131 offset:16384
	ds_read_b128 v[180:183], v131 offset:17408
	ds_read_b128 v[184:187], v130 offset:16384
	ds_read_b128 v[188:191], v130 offset:17408
	s_waitcnt vmcnt(4)
	s_barrier
; #define WAIT_V(n) asm volatile("s_waitcnt vmcnt(" #n ")" ::: "memory")
; #define WAIT_L(n) asm volatile("s_waitcnt lgkmcnt(" #n ")" ::: "memory")
; #define BAR __builtin_amdgcn_s_barrier()
; __device__ __forceinline__ void mainloop_8phase(const u16* __restrict__ A, const u16* __restrict__ Bt, int K,
;                                                 f32x4 (&acc)[2][2][4][2], int wid_s, int ld) {
;     ...
;     LDA(At, 0, 1); WAIT_V(4); BAR; WAIT_L(0); MMA(1, 0, At, B0); MMA(1, 1, At, B1); BAR; }
;   { LDB(B0, 1, 0); LDA(At, 1, 0); WAIT_V(2); BAR; WAIT_L(0); MMA(0, 0, At, B0); BAR;
	s_waitcnt lgkmcnt(0)
	v_mfma_f32_16x16x32_bf16 v[62:65], v[160:163], v[138:141], v[62:65]
	v_mfma_f32_16x16x32_bf16 v[58:61], v[160:163], v[156:159], v[58:61]
	v_mfma_f32_16x16x32_bf16 v[54:57], v[168:171], v[138:141], v[54:57]
	v_mfma_f32_16x16x32_bf16 v[50:53], v[168:171], v[156:159], v[50:53]
	v_mfma_f32_16x16x32_bf16 v[46:49], v[176:179], v[138:141], v[46:49]
	v_mfma_f32_16x16x32_bf16 v[42:45], v[176:179], v[156:159], v[42:45]
	v_mfma_f32_16x16x32_bf16 v[38:41], v[184:187], v[138:141], v[38:41]
	v_mfma_f32_16x16x32_bf16 v[34:37], v[184:187], v[156:159], v[34:37]
	v_mfma_f32_16x16x32_bf16 v[204:207], v[164:167], v[148:151], v[62:65]
	v_mfma_f32_16x16x32_bf16 v[208:211], v[164:167], v[152:155], v[58:61]
	v_mfma_f32_16x16x32_bf16 v[212:215], v[172:175], v[148:151], v[54:57]
	v_mfma_f32_16x16x32_bf16 v[216:219], v[172:175], v[152:155], v[50:53]
	v_mfma_f32_16x16x32_bf16 v[220:223], v[180:183], v[148:151], v[46:49]
	v_mfma_f32_16x16x32_bf16 v[224:227], v[180:183], v[152:155], v[42:45]
	v_mfma_f32_16x16x32_bf16 v[136:139], v[188:191], v[148:151], v[38:41]
	v_mfma_f32_16x16x32_bf16 v[146:149], v[188:191], v[152:155], v[34:37]
	v_mfma_f32_16x16x32_bf16 v[30:33], v[160:163], v[98:101], v[30:33]
	v_mfma_f32_16x16x32_bf16 v[22:25], v[168:171], v[98:101], v[22:25]
	v_mfma_f32_16x16x32_bf16 v[14:17], v[176:179], v[98:101], v[14:17]
	v_mfma_f32_16x16x32_bf16 v[6:9], v[184:187], v[98:101], v[6:9]
	v_mfma_f32_16x16x32_bf16 v[30:33], v[164:167], v[106:109], v[30:33]
	v_mfma_f32_16x16x32_bf16 v[26:29], v[160:163], v[114:117], v[26:29]
	v_mfma_f32_16x16x32_bf16 v[22:25], v[172:175], v[106:109], v[22:25]
	v_mfma_f32_16x16x32_bf16 v[18:21], v[168:171], v[114:117], v[18:21]
	v_mfma_f32_16x16x32_bf16 v[14:17], v[180:183], v[106:109], v[14:17]
	v_mfma_f32_16x16x32_bf16 v[10:13], v[176:179], v[114:117], v[10:13]
	v_mfma_f32_16x16x32_bf16 v[6:9], v[188:191], v[106:109], v[6:9]
	v_mfma_f32_16x16x32_bf16 v[2:5], v[184:187], v[114:117], v[2:5]
	v_mfma_f32_16x16x32_bf16 v[150:153], v[164:167], v[122:125], v[26:29]
	v_mfma_f32_16x16x32_bf16 v[154:157], v[172:175], v[122:125], v[18:21]
	v_mfma_f32_16x16x32_bf16 v[158:161], v[180:183], v[122:125], v[10:13]
	v_mfma_f32_16x16x32_bf16 v[162:165], v[188:191], v[122:125], v[2:5]
	s_barrier
	s_nop 1
	ds_read_b128 v[2:5], v135
	ds_read_b128 v[10:13], v135 offset:1024
	ds_read_b128 v[18:21], v135 offset:2048
	ds_read_b128 v[26:29], v135 offset:3072
	ds_read_b128 v[34:37], v133 offset:32768
	ds_read_b128 v[38:41], v133 offset:33792
	ds_read_b128 v[42:45], v132 offset:32768
	ds_read_b128 v[46:49], v132 offset:33792
	ds_read_b128 v[166:169], v131 offset:32768
	ds_read_b128 v[170:173], v131 offset:33792
	ds_read_b128 v[174:177], v130 offset:32768
	ds_read_b128 v[178:181], v130 offset:33792
	s_waitcnt vmcnt(2)
	s_barrier
	s_waitcnt lgkmcnt(0)
	v_mfma_f32_16x16x32_bf16 v[50:53], v[34:37], v[2:5], v[126:129]
	v_mfma_f32_16x16x32_bf16 v[122:125], v[38:41], v[10:13], v[50:53]
	v_mfma_f32_16x16x32_bf16 v[50:53], v[34:37], v[18:21], v[142:145]
	v_mfma_f32_16x16x32_bf16 v[126:129], v[38:41], v[26:29], v[50:53]
	v_mfma_f32_16x16x32_bf16 v[50:53], v[42:45], v[2:5], v[118:121]
	v_mfma_f32_16x16x32_bf16 v[114:117], v[46:49], v[10:13], v[50:53]
	v_mfma_f32_16x16x32_bf16 v[50:53], v[42:45], v[18:21], v[192:195]
	v_mfma_f32_16x16x32_bf16 v[118:121], v[46:49], v[26:29], v[50:53]
	v_mfma_f32_16x16x32_bf16 v[50:53], v[166:169], v[2:5], v[110:113]
	v_mfma_f32_16x16x32_bf16 v[106:109], v[170:173], v[10:13], v[50:53]
	v_mfma_f32_16x16x32_bf16 v[50:53], v[166:169], v[18:21], v[196:199]
	v_mfma_f32_16x16x32_bf16 v[110:113], v[170:173], v[26:29], v[50:53]
	v_mfma_f32_16x16x32_bf16 v[50:53], v[174:177], v[2:5], v[102:105]
	v_mfma_f32_16x16x32_bf16 v[98:101], v[178:181], v[10:13], v[50:53]
	v_mfma_f32_16x16x32_bf16 v[50:53], v[174:177], v[18:21], v[200:203]
	v_mfma_f32_16x16x32_bf16 v[102:105], v[178:181], v[26:29], v[50:53]
	s_barrier
; #define WAIT_V(n) asm volatile("s_waitcnt vmcnt(" #n ")" ::: "memory")
; #define WAIT_L(n) asm volatile("s_waitcnt lgkmcnt(" #n ")" ::: "memory")
; #define BAR __builtin_amdgcn_s_barrier()
; __device__ __forceinline__ void mainloop_8phase(const u16* __restrict__ A, const u16* __restrict__ Bt, int K,
;                                                 f32x4 (&acc)[2][2][4][2], int wid_s, int ld) {
;     ...
;   { LDB(B0, 1, 0); LDA(At, 1, 0); WAIT_V(2); BAR; WAIT_L(0); MMA(0, 0, At, B0); BAR;
;     LDB(B1, 1, 1); WAIT_V(0); BAR; WAIT_L(0); MMA(0, 1, At, B1); BAR;
;     LDA(At, 1, 1); BAR; WAIT_L(0); MMA(1, 0, At, B0); MMA(1, 1, At, B1); BAR; }
;   if (wr == 0) BAR;
	ds_read_b128 v[140:143], v134
	ds_read_b128 v[182:185], v134 offset:1024
	ds_read_b128 v[186:189], v134 offset:2048
	ds_read_b128 v[190:193], v134 offset:3072
	s_waitcnt vmcnt(0)
	s_barrier
	s_waitcnt lgkmcnt(0)
	v_mfma_f32_16x16x32_bf16 v[50:53], v[34:37], v[140:143], v[94:97]
	v_mfma_f32_16x16x32_bf16 v[34:37], v[34:37], v[186:189], v[90:93]
	v_mfma_f32_16x16x32_bf16 v[62:65], v[38:41], v[190:193], v[34:37]
	v_mfma_f32_16x16x32_bf16 v[34:37], v[42:45], v[140:143], v[86:89]
	v_mfma_f32_16x16x32_bf16 v[58:61], v[38:41], v[182:185], v[50:53]
	v_mfma_f32_16x16x32_bf16 v[50:53], v[46:49], v[182:185], v[34:37]
	v_mfma_f32_16x16x32_bf16 v[34:37], v[42:45], v[186:189], v[82:85]
	v_mfma_f32_16x16x32_bf16 v[54:57], v[46:49], v[190:193], v[34:37]
	v_mfma_f32_16x16x32_bf16 v[34:37], v[166:169], v[140:143], v[78:81]
	v_mfma_f32_16x16x32_bf16 v[42:45], v[170:173], v[182:185], v[34:37]
	v_mfma_f32_16x16x32_bf16 v[34:37], v[166:169], v[186:189], v[74:77]
	v_mfma_f32_16x16x32_bf16 v[46:49], v[170:173], v[190:193], v[34:37]
	v_mfma_f32_16x16x32_bf16 v[34:37], v[174:177], v[140:143], v[70:73]
	v_mfma_f32_16x16x32_bf16 v[38:41], v[174:177], v[186:189], v[66:69]
	v_mfma_f32_16x16x32_bf16 v[34:37], v[178:181], v[182:185], v[34:37]
	v_mfma_f32_16x16x32_bf16 v[38:41], v[178:181], v[190:193], v[38:41]
	s_barrier
	ds_read_b128 v[166:169], v133 offset:49152
	ds_read_b128 v[170:173], v133 offset:50176
	ds_read_b128 v[174:177], v132 offset:49152
	ds_read_b128 v[132:135], v132 offset:50176
	ds_read_b128 v[178:181], v131 offset:49152
	ds_read_b128 v[194:197], v131 offset:50176
	ds_read_b128 v[198:201], v130 offset:49152
	ds_read_b128 v[228:231], v130 offset:50176
	s_barrier
	s_waitcnt lgkmcnt(0)
	v_mfma_f32_16x16x32_bf16 v[66:69], v[166:169], v[2:5], v[204:207]
	v_mfma_f32_16x16x32_bf16 v[90:93], v[170:173], v[10:13], v[66:69]
	v_mfma_f32_16x16x32_bf16 v[66:69], v[166:169], v[18:21], v[208:211]
	v_mfma_f32_16x16x32_bf16 v[94:97], v[170:173], v[26:29], v[66:69]
	v_mfma_f32_16x16x32_bf16 v[66:69], v[174:177], v[2:5], v[212:215]
	v_mfma_f32_16x16x32_bf16 v[82:85], v[132:135], v[10:13], v[66:69]
	v_mfma_f32_16x16x32_bf16 v[66:69], v[174:177], v[18:21], v[216:219]
	v_mfma_f32_16x16x32_bf16 v[86:89], v[132:135], v[26:29], v[66:69]
	v_mfma_f32_16x16x32_bf16 v[66:69], v[178:181], v[2:5], v[220:223]
	v_mfma_f32_16x16x32_bf16 v[74:77], v[194:197], v[10:13], v[66:69]
	v_mfma_f32_16x16x32_bf16 v[66:69], v[178:181], v[18:21], v[224:227]
	v_mfma_f32_16x16x32_bf16 v[2:5], v[198:201], v[2:5], v[136:139]
	v_mfma_f32_16x16x32_bf16 v[78:81], v[194:197], v[26:29], v[66:69]
	v_mfma_f32_16x16x32_bf16 v[66:69], v[228:231], v[10:13], v[2:5]
	v_mfma_f32_16x16x32_bf16 v[2:5], v[198:201], v[18:21], v[146:149]
	v_mfma_f32_16x16x32_bf16 v[70:73], v[228:231], v[26:29], v[2:5]
	v_mfma_f32_16x16x32_bf16 v[2:5], v[166:169], v[140:143], v[30:33]
	v_mfma_f32_16x16x32_bf16 v[26:29], v[170:173], v[182:185], v[2:5]
	v_mfma_f32_16x16x32_bf16 v[2:5], v[166:169], v[186:189], v[150:153]
	v_mfma_f32_16x16x32_bf16 v[30:33], v[170:173], v[190:193], v[2:5]
	v_mfma_f32_16x16x32_bf16 v[2:5], v[174:177], v[140:143], v[22:25]
	v_mfma_f32_16x16x32_bf16 v[18:21], v[132:135], v[182:185], v[2:5]
	v_mfma_f32_16x16x32_bf16 v[2:5], v[174:177], v[186:189], v[154:157]
	v_mfma_f32_16x16x32_bf16 v[22:25], v[132:135], v[190:193], v[2:5]
	v_mfma_f32_16x16x32_bf16 v[2:5], v[178:181], v[140:143], v[14:17]
	v_mfma_f32_16x16x32_bf16 v[10:13], v[194:197], v[182:185], v[2:5]
	v_mfma_f32_16x16x32_bf16 v[2:5], v[178:181], v[186:189], v[158:161]
	v_mfma_f32_16x16x32_bf16 v[14:17], v[194:197], v[190:193], v[2:5]
	v_mfma_f32_16x16x32_bf16 v[2:5], v[198:201], v[140:143], v[6:9]
	v_mfma_f32_16x16x32_bf16 v[6:9], v[198:201], v[186:189], v[162:165]
	v_mfma_f32_16x16x32_bf16 v[2:5], v[228:231], v[182:185], v[2:5]
	v_mfma_f32_16x16x32_bf16 v[6:9], v[228:231], v[190:193], v[6:9]
	s_movk_i32 s0, 0x100
	v_cmp_gt_u32_e32 vcc, s0, v0
	s_barrier
	s_and_saveexec_b64 s[0:1], vcc
	s_cbranch_execz .LBB0_250
	s_barrier

; #define WAIT_V(n) asm volatile("s_waitcnt vmcnt(" #n ")" ::: "memory")
; #define WAIT_L(n) asm volatile("s_waitcnt lgkmcnt(" #n ")" ::: "memory")
; #define BAR __builtin_amdgcn_s_barrier()
; #define SCHED __builtin_amdgcn_sched_barrier(0)
; __device__ __forceinline__ void mainloop_8phase(const u16* __restrict__ A, const u16* __restrict__ Bt, int K,
;                                                 f32x4 (&acc)[2][2][4][2], int wid_s, int ld) {
;     ...
;     LDB(B0, 0, 0); SCHED; LDA(At, 0, 0); STAGE(SA(1, 1), A, brow + G_HALF, t + 1);
;     WAIT_L(8); BAR; WAIT_L(0); MMA(0, 0, At, B0); BAR; SCHED;
;     LDB(B1, 0, 1); STAGE(SB(0, 0), Bt, bcol, t + 2);
;     BAR; WAIT_L(0); MMA(0, 1, At, B1); BAR;
;     LDA(At, 0, 1); STAGE(SA(0, 0), A, brow, t + 2);
;     BAR; WAIT_L(0); MMA(1, 0, At, B0); BAR; SCHED;
;     STAGE(SB(0, 1), Bt, bcol + G_HALF, t + 2);
;     WAIT_V(6); BAR; MMA(1, 1, At, B1); BAR;
.LBB0_342:
	ds_read_b128 v[156:159], v155
	ds_read_b128 v[160:163], v155 offset:1024
	ds_read_b128 v[164:167], v155 offset:2048
	ds_read_b128 v[168:171], v155 offset:3072
	s_add_i32 s3, s2, 0xffffff00
	s_add_i32 m0, s100, 0xc000
	ds_read_b128 v[172:175], v133
	ds_read_b128 v[176:179], v133 offset:1024
	ds_read_b128 v[180:183], v132
	ds_read_b128 v[184:187], v132 offset:1024
	ds_read_b128 v[188:191], v131
	ds_read_b128 v[192:195], v131 offset:1024
	ds_read_b128 v[196:199], v130
	buffer_load_dwordx4 v136, s[88:91], s3 offen lds
	s_add_i32 m0, s100, 0xe000
	ds_read_b128 v[200:203], v130 offset:1024
	buffer_load_dwordx4 v135, s[88:91], s3 offen lds
	s_waitcnt lgkmcnt(8)
	s_barrier
	s_waitcnt lgkmcnt(1)
	v_mfma_f32_16x16x32_bf16 v[126:129], v[172:175], v[156:159], v[126:129]
	v_mfma_f32_16x16x32_bf16 v[122:125], v[172:175], v[164:167], v[122:125]
	v_mfma_f32_16x16x32_bf16 v[118:121], v[180:183], v[156:159], v[118:121]
	v_mfma_f32_16x16x32_bf16 v[114:117], v[180:183], v[164:167], v[114:117]
	v_mfma_f32_16x16x32_bf16 v[110:113], v[188:191], v[156:159], v[110:113]
	v_mfma_f32_16x16x32_bf16 v[106:109], v[188:191], v[164:167], v[106:109]
	v_mfma_f32_16x16x32_bf16 v[102:105], v[196:199], v[156:159], v[102:105]
	v_mfma_f32_16x16x32_bf16 v[98:101], v[196:199], v[164:167], v[98:101]
	v_mfma_f32_16x16x32_bf16 v[126:129], v[176:179], v[160:163], v[126:129]
	v_mfma_f32_16x16x32_bf16 v[122:125], v[176:179], v[168:171], v[122:125]
	v_mfma_f32_16x16x32_bf16 v[118:121], v[184:187], v[160:163], v[118:121]
	v_mfma_f32_16x16x32_bf16 v[114:117], v[184:187], v[168:171], v[114:117]
	v_mfma_f32_16x16x32_bf16 v[110:113], v[192:195], v[160:163], v[110:113]
	v_mfma_f32_16x16x32_bf16 v[106:109], v[192:195], v[168:171], v[106:109]
	s_waitcnt lgkmcnt(0)
	v_mfma_f32_16x16x32_bf16 v[102:105], v[200:203], v[160:163], v[102:105]
	v_mfma_f32_16x16x32_bf16 v[98:101], v[200:203], v[168:171], v[98:101]
	s_barrier
	s_add_i32 s3, s2, 0xfff7ff80
	s_add_i32 m0, s100, 0x10000
	ds_read_b128 v[204:207], v147
	ds_read_b128 v[208:211], v147 offset:1024
	ds_read_b128 v[212:215], v147 offset:2048
	buffer_load_dwordx4 v136, s[4:7], s3 offen lds
	s_add_i32 m0, s100, 0x12000
	ds_read_b128 v[216:219], v147 offset:3072
	buffer_load_dwordx4 v135, s[4:7], s3 offen lds
	s_barrier
	s_waitcnt lgkmcnt(1)
	v_mfma_f32_16x16x32_bf16 v[94:97], v[172:175], v[204:207], v[94:97]
	v_mfma_f32_16x16x32_bf16 v[90:93], v[172:175], v[212:215], v[90:93]
	v_mfma_f32_16x16x32_bf16 v[86:89], v[180:183], v[204:207], v[86:89]
	v_mfma_f32_16x16x32_bf16 v[82:85], v[180:183], v[212:215], v[82:85]
	v_mfma_f32_16x16x32_bf16 v[78:81], v[188:191], v[204:207], v[78:81]
	v_mfma_f32_16x16x32_bf16 v[74:77], v[188:191], v[212:215], v[74:77]
	v_mfma_f32_16x16x32_bf16 v[70:73], v[196:199], v[204:207], v[70:73]
	v_mfma_f32_16x16x32_bf16 v[66:69], v[196:199], v[212:215], v[66:69]
	v_mfma_f32_16x16x32_bf16 v[94:97], v[176:179], v[208:211], v[94:97]
	s_waitcnt lgkmcnt(0)
	v_mfma_f32_16x16x32_bf16 v[90:93], v[176:179], v[216:219], v[90:93]
	v_mfma_f32_16x16x32_bf16 v[86:89], v[184:187], v[208:211], v[86:89]
	v_mfma_f32_16x16x32_bf16 v[82:85], v[184:187], v[216:219], v[82:85]
	v_mfma_f32_16x16x32_bf16 v[78:81], v[192:195], v[208:211], v[78:81]
	v_mfma_f32_16x16x32_bf16 v[74:77], v[192:195], v[216:219], v[74:77]
	v_mfma_f32_16x16x32_bf16 v[70:73], v[200:203], v[208:211], v[70:73]
	v_mfma_f32_16x16x32_bf16 v[66:69], v[200:203], v[216:219], v[66:69]
	s_mov_b32 m0, s100
	s_barrier
	ds_read_b128 v[172:175], v133 offset:16384
	ds_read_b128 v[176:179], v133 offset:17408
	ds_read_b128 v[180:183], v132 offset:16384
	ds_read_b128 v[184:187], v132 offset:17408
	ds_read_b128 v[188:191], v131 offset:16384
	ds_read_b128 v[192:195], v131 offset:17408
	ds_read_b128 v[196:199], v130 offset:16384
	buffer_load_dwordx4 v136, s[88:91], s3 offen lds
	s_add_i32 m0, s100, 0x2000
	ds_read_b128 v[200:203], v130 offset:17408
	buffer_load_dwordx4 v135, s[88:91], s3 offen lds
	s_barrier
	s_waitcnt lgkmcnt(1)
	v_mfma_f32_16x16x32_bf16 v[62:65], v[172:175], v[156:159], v[62:65]
	v_mfma_f32_16x16x32_bf16 v[58:61], v[172:175], v[164:167], v[58:61]
	v_mfma_f32_16x16x32_bf16 v[54:57], v[180:183], v[156:159], v[54:57]
	v_mfma_f32_16x16x32_bf16 v[50:53], v[180:183], v[164:167], v[50:53]
	v_mfma_f32_16x16x32_bf16 v[46:49], v[188:191], v[156:159], v[46:49]
	v_mfma_f32_16x16x32_bf16 v[42:45], v[188:191], v[164:167], v[42:45]
	v_mfma_f32_16x16x32_bf16 v[38:41], v[196:199], v[156:159], v[38:41]
	v_mfma_f32_16x16x32_bf16 v[34:37], v[196:199], v[164:167], v[34:37]
	v_mfma_f32_16x16x32_bf16 v[62:65], v[176:179], v[160:163], v[62:65]
	v_mfma_f32_16x16x32_bf16 v[58:61], v[176:179], v[168:171], v[58:61]
	v_mfma_f32_16x16x32_bf16 v[54:57], v[184:187], v[160:163], v[54:57]
	v_mfma_f32_16x16x32_bf16 v[50:53], v[184:187], v[168:171], v[50:53]
	v_mfma_f32_16x16x32_bf16 v[46:49], v[192:195], v[160:163], v[46:49]
	v_mfma_f32_16x16x32_bf16 v[42:45], v[192:195], v[168:171], v[42:45]
	s_waitcnt lgkmcnt(0)
	v_mfma_f32_16x16x32_bf16 v[38:41], v[200:203], v[160:163], v[38:41]
	v_mfma_f32_16x16x32_bf16 v[34:37], v[200:203], v[168:171], v[34:37]
	s_barrier
	s_add_i32 s3, s2, 0xffffff80
	s_add_i32 m0, s100, 0x14000
	buffer_load_dwordx4 v136, s[4:7], s3 offen lds
	s_add_i32 m0, s100, 0x16000
	s_nop 0
	buffer_load_dwordx4 v135, s[4:7], s3 offen lds
	s_waitcnt vmcnt(6)
	s_barrier
; #define WAIT_V(n) asm volatile("s_waitcnt vmcnt(" #n ")" ::: "memory")
; #define WAIT_L(n) asm volatile("s_waitcnt lgkmcnt(" #n ")" ::: "memory")
; #define BAR __builtin_amdgcn_s_barrier()
; #define SCHED __builtin_amdgcn_sched_barrier(0)
; __device__ __forceinline__ void mainloop_8phase(const u16* __restrict__ A, const u16* __restrict__ Bt, int K,
;                                                 f32x4 (&acc)[2][2][4][2], int wid_s, int ld) {
;     ...
;     LDB(B0, 1, 0); SCHED; LDA(At, 1, 0); STAGE(SA(0, 1), A, brow + G_HALF, t + 2);
;     WAIT_L(8); BAR; WAIT_L(0); MMA(0, 0, At, B0); BAR; SCHED;
;     LDB(B1, 1, 1); STAGE(SB(1, 0), Bt, bcol, t + 3);
;     BAR; WAIT_L(0); MMA(0, 1, At, B1); BAR;
;     LDA(At, 1, 1); STAGE(SA(1, 0), A, brow, t + 3);
;     BAR; WAIT_L(0); MMA(1, 0, At, B0); BAR; SCHED;
;     STAGE(SB(1, 1), Bt, bcol + G_HALF, t + 3);
;     WAIT_V(6); BAR; MMA(1, 1, At, B1); BAR;
	v_mfma_f32_16x16x32_bf16 v[30:33], v[172:175], v[204:207], v[30:33]
	v_mfma_f32_16x16x32_bf16 v[26:29], v[172:175], v[212:215], v[26:29]
	v_mfma_f32_16x16x32_bf16 v[22:25], v[180:183], v[204:207], v[22:25]
	v_mfma_f32_16x16x32_bf16 v[18:21], v[180:183], v[212:215], v[18:21]
	v_mfma_f32_16x16x32_bf16 v[14:17], v[188:191], v[204:207], v[14:17]
	v_mfma_f32_16x16x32_bf16 v[10:13], v[188:191], v[212:215], v[10:13]
	v_mfma_f32_16x16x32_bf16 v[6:9], v[196:199], v[204:207], v[6:9]
	v_mfma_f32_16x16x32_bf16 v[2:5], v[196:199], v[212:215], v[2:5]
	v_mfma_f32_16x16x32_bf16 v[30:33], v[176:179], v[208:211], v[30:33]
	v_mfma_f32_16x16x32_bf16 v[26:29], v[176:179], v[216:219], v[26:29]
	v_mfma_f32_16x16x32_bf16 v[22:25], v[184:187], v[208:211], v[22:25]
	v_mfma_f32_16x16x32_bf16 v[18:21], v[184:187], v[216:219], v[18:21]
	v_mfma_f32_16x16x32_bf16 v[14:17], v[192:195], v[208:211], v[14:17]
	v_mfma_f32_16x16x32_bf16 v[10:13], v[192:195], v[216:219], v[10:13]
	v_mfma_f32_16x16x32_bf16 v[6:9], v[200:203], v[208:211], v[6:9]
	v_mfma_f32_16x16x32_bf16 v[2:5], v[200:203], v[216:219], v[2:5]
	s_barrier
	ds_read_b128 v[156:159], v137
	ds_read_b128 v[160:163], v137 offset:1024
	ds_read_b128 v[164:167], v137 offset:2048
	ds_read_b128 v[168:171], v137 offset:3072
	s_add_i32 m0, s100, 0x4000
	ds_read_b128 v[172:175], v133 offset:32768
	ds_read_b128 v[176:179], v133 offset:33792
	ds_read_b128 v[180:183], v132 offset:32768
	ds_read_b128 v[184:187], v132 offset:33792
	ds_read_b128 v[188:191], v131 offset:32768
	ds_read_b128 v[192:195], v131 offset:33792
	ds_read_b128 v[196:199], v130 offset:32768
	buffer_load_dwordx4 v136, s[88:91], s3 offen lds
	s_add_i32 m0, s100, 0x6000
	ds_read_b128 v[200:203], v130 offset:33792
	buffer_load_dwordx4 v135, s[88:91], s3 offen lds
	s_waitcnt lgkmcnt(8)
	s_barrier
	s_waitcnt lgkmcnt(1)
	v_mfma_f32_16x16x32_bf16 v[126:129], v[172:175], v[156:159], v[126:129]
	v_mfma_f32_16x16x32_bf16 v[122:125], v[172:175], v[164:167], v[122:125]
	v_mfma_f32_16x16x32_bf16 v[118:121], v[180:183], v[156:159], v[118:121]
	v_mfma_f32_16x16x32_bf16 v[114:117], v[180:183], v[164:167], v[114:117]
	v_mfma_f32_16x16x32_bf16 v[110:113], v[188:191], v[156:159], v[110:113]
	v_mfma_f32_16x16x32_bf16 v[106:109], v[188:191], v[164:167], v[106:109]
	v_mfma_f32_16x16x32_bf16 v[102:105], v[196:199], v[156:159], v[102:105]
	v_mfma_f32_16x16x32_bf16 v[98:101], v[196:199], v[164:167], v[98:101]
	v_mfma_f32_16x16x32_bf16 v[126:129], v[176:179], v[160:163], v[126:129]
	v_mfma_f32_16x16x32_bf16 v[122:125], v[176:179], v[168:171], v[122:125]
	v_mfma_f32_16x16x32_bf16 v[118:121], v[184:187], v[160:163], v[118:121]
	v_mfma_f32_16x16x32_bf16 v[114:117], v[184:187], v[168:171], v[114:117]
	v_mfma_f32_16x16x32_bf16 v[110:113], v[192:195], v[160:163], v[110:113]
	v_mfma_f32_16x16x32_bf16 v[106:109], v[192:195], v[168:171], v[106:109]
	s_waitcnt lgkmcnt(0)
	v_mfma_f32_16x16x32_bf16 v[102:105], v[200:203], v[160:163], v[102:105]
	v_mfma_f32_16x16x32_bf16 v[98:101], v[200:203], v[168:171], v[98:101]
	s_barrier
	s_add_i32 s3, s2, 0xfff80000
	s_add_i32 m0, s100, 0x18000
	ds_read_b128 v[204:207], v134
	ds_read_b128 v[208:211], v134 offset:1024
	ds_read_b128 v[212:215], v134 offset:2048
	buffer_load_dwordx4 v136, s[4:7], s3 offen lds
	s_add_i32 m0, s100, 0x1a000
	ds_read_b128 v[216:219], v134 offset:3072
	buffer_load_dwordx4 v135, s[4:7], s3 offen lds
	s_barrier
	s_waitcnt lgkmcnt(1)
	v_mfma_f32_16x16x32_bf16 v[94:97], v[172:175], v[204:207], v[94:97]
	v_mfma_f32_16x16x32_bf16 v[90:93], v[172:175], v[212:215], v[90:93]
	v_mfma_f32_16x16x32_bf16 v[86:89], v[180:183], v[204:207], v[86:89]
	v_mfma_f32_16x16x32_bf16 v[82:85], v[180:183], v[212:215], v[82:85]
	v_mfma_f32_16x16x32_bf16 v[78:81], v[188:191], v[204:207], v[78:81]
	v_mfma_f32_16x16x32_bf16 v[74:77], v[188:191], v[212:215], v[74:77]
	v_mfma_f32_16x16x32_bf16 v[70:73], v[196:199], v[204:207], v[70:73]
	v_mfma_f32_16x16x32_bf16 v[66:69], v[196:199], v[212:215], v[66:69]
	v_mfma_f32_16x16x32_bf16 v[94:97], v[176:179], v[208:211], v[94:97]
	s_waitcnt lgkmcnt(0)
	v_mfma_f32_16x16x32_bf16 v[90:93], v[176:179], v[216:219], v[90:93]
	v_mfma_f32_16x16x32_bf16 v[86:89], v[184:187], v[208:211], v[86:89]
	v_mfma_f32_16x16x32_bf16 v[82:85], v[184:187], v[216:219], v[82:85]
	v_mfma_f32_16x16x32_bf16 v[78:81], v[192:195], v[208:211], v[78:81]
	v_mfma_f32_16x16x32_bf16 v[74:77], v[192:195], v[216:219], v[74:77]
	v_mfma_f32_16x16x32_bf16 v[70:73], v[200:203], v[208:211], v[70:73]
	v_mfma_f32_16x16x32_bf16 v[66:69], v[200:203], v[216:219], v[66:69]
	s_add_i32 m0, s100, 0x8000
	s_barrier
	ds_read_b128 v[172:175], v133 offset:49152
	ds_read_b128 v[176:179], v133 offset:50176
	ds_read_b128 v[180:183], v132 offset:49152
	ds_read_b128 v[184:187], v132 offset:50176
	ds_read_b128 v[188:191], v131 offset:49152
	ds_read_b128 v[192:195], v131 offset:50176
	ds_read_b128 v[196:199], v130 offset:49152
	buffer_load_dwordx4 v136, s[88:91], s3 offen lds
	s_add_i32 m0, s100, 0xa000
	ds_read_b128 v[200:203], v130 offset:50176
	buffer_load_dwordx4 v135, s[88:91], s3 offen lds
	s_barrier
	s_waitcnt lgkmcnt(1)
	v_mfma_f32_16x16x32_bf16 v[62:65], v[172:175], v[156:159], v[62:65]
	v_mfma_f32_16x16x32_bf16 v[58:61], v[172:175], v[164:167], v[58:61]
	v_mfma_f32_16x16x32_bf16 v[54:57], v[180:183], v[156:159], v[54:57]
	v_mfma_f32_16x16x32_bf16 v[50:53], v[180:183], v[164:167], v[50:53]
	v_mfma_f32_16x16x32_bf16 v[46:49], v[188:191], v[156:159], v[46:49]
	v_mfma_f32_16x16x32_bf16 v[42:45], v[188:191], v[164:167], v[42:45]
	v_mfma_f32_16x16x32_bf16 v[38:41], v[196:199], v[156:159], v[38:41]
	v_mfma_f32_16x16x32_bf16 v[34:37], v[196:199], v[164:167], v[34:37]
	v_mfma_f32_16x16x32_bf16 v[62:65], v[176:179], v[160:163], v[62:65]
	v_mfma_f32_16x16x32_bf16 v[58:61], v[176:179], v[168:171], v[58:61]
	v_mfma_f32_16x16x32_bf16 v[54:57], v[184:187], v[160:163], v[54:57]
	v_mfma_f32_16x16x32_bf16 v[50:53], v[184:187], v[168:171], v[50:53]
	v_mfma_f32_16x16x32_bf16 v[46:49], v[192:195], v[160:163], v[46:49]
	v_mfma_f32_16x16x32_bf16 v[42:45], v[192:195], v[168:171], v[42:45]
	s_waitcnt lgkmcnt(0)
	v_mfma_f32_16x16x32_bf16 v[38:41], v[200:203], v[160:163], v[38:41]
	v_mfma_f32_16x16x32_bf16 v[34:37], v[200:203], v[168:171], v[34:37]
	s_barrier
; #define WAIT_V(n) asm volatile("s_waitcnt vmcnt(" #n ")" ::: "memory")
; #define WAIT_L(n) asm volatile("s_waitcnt lgkmcnt(" #n ")" ::: "memory")
; #define BAR __builtin_amdgcn_s_barrier()
; __device__ __forceinline__ void mainloop_8phase(const u16* __restrict__ A, const u16* __restrict__ Bt, int K,
;                                                 f32x4 (&acc)[2][2][4][2], int wid_s, int ld) {
;     ...
;     WAIT_V(6); BAR; MMA(1, 1, At, B1); BAR;
;   }
;   { LDB(B0, 0, 0); LDA(At, 0, 0); STAGE(SA(1, 1), A, brow + G_HALF, nt - 1);
;     BAR; WAIT_L(0); MMA(0, 0, At, B0); BAR;
;     LDB(B1, 0, 1); BAR; WAIT_L(0); MMA(0, 1, At, B1); BAR;
;     LDA(At, 0, 1); WAIT_V(4); BAR; WAIT_L(0); MMA(1, 0, At, B0); MMA(1, 1, At, B1); BAR; }
	s_add_i32 m0, s100, 0x1c000
	buffer_load_dwordx4 v136, s[4:7], s2 offen lds
	s_add_i32 m0, s100, 0x1e000
	s_nop 0
	buffer_load_dwordx4 v135, s[4:7], s2 offen lds
	s_waitcnt vmcnt(6)
	s_barrier
	v_mfma_f32_16x16x32_bf16 v[30:33], v[172:175], v[204:207], v[30:33]
	v_mfma_f32_16x16x32_bf16 v[26:29], v[172:175], v[212:215], v[26:29]
	v_mfma_f32_16x16x32_bf16 v[22:25], v[180:183], v[204:207], v[22:25]
	v_mfma_f32_16x16x32_bf16 v[18:21], v[180:183], v[212:215], v[18:21]
	v_mfma_f32_16x16x32_bf16 v[14:17], v[188:191], v[204:207], v[14:17]
	v_mfma_f32_16x16x32_bf16 v[10:13], v[188:191], v[212:215], v[10:13]
	v_mfma_f32_16x16x32_bf16 v[6:9], v[196:199], v[204:207], v[6:9]
	v_mfma_f32_16x16x32_bf16 v[2:5], v[196:199], v[212:215], v[2:5]
	v_mfma_f32_16x16x32_bf16 v[30:33], v[176:179], v[208:211], v[30:33]
	v_mfma_f32_16x16x32_bf16 v[26:29], v[176:179], v[216:219], v[26:29]
	v_mfma_f32_16x16x32_bf16 v[22:25], v[184:187], v[208:211], v[22:25]
	v_mfma_f32_16x16x32_bf16 v[18:21], v[184:187], v[216:219], v[18:21]
	v_mfma_f32_16x16x32_bf16 v[14:17], v[192:195], v[208:211], v[14:17]
	v_mfma_f32_16x16x32_bf16 v[10:13], v[192:195], v[216:219], v[10:13]
	v_mfma_f32_16x16x32_bf16 v[6:9], v[200:203], v[208:211], v[6:9]
	v_mfma_f32_16x16x32_bf16 v[2:5], v[200:203], v[216:219], v[2:5]
	s_add_i32 s1, s1, 2
	s_addk_i32 s2, 0x100
	s_cmp_lt_u32 s1, 28
	s_barrier
	s_cbranch_scc1 .LBB0_342
	v_readfirstlane_b32 s1, v145
	s_mov_b32 m0, s1
	s_mov_b32 s2, 0x80f80
	v_readfirstlane_b32 s1, v144
	ds_read_b128 v[138:141], v155
	ds_read_b128 v[148:151], v155 offset:1024
	ds_read_b128 v[156:159], v155 offset:2048
	ds_read_b128 v[152:155], v155 offset:3072
	ds_read_b128 v[160:163], v133
	ds_read_b128 v[164:167], v133 offset:1024
	ds_read_b128 v[168:171], v132
	ds_read_b128 v[172:175], v132 offset:1024
	ds_read_b128 v[176:179], v131
	ds_read_b128 v[180:183], v131 offset:1024
	ds_read_b128 v[184:187], v130
	ds_read_b128 v[188:191], v130 offset:1024
	buffer_load_dwordx4 v136, s[88:91], s2 offen lds
	s_mov_b32 m0, s1
	s_nop 0
	buffer_load_dwordx4 v135, s[88:91], s2 offen lds
	s_barrier
	s_waitcnt lgkmcnt(0)
	v_mfma_f32_16x16x32_bf16 v[126:129], v[160:163], v[138:141], v[126:129]
	v_mfma_f32_16x16x32_bf16 v[118:121], v[168:171], v[138:141], v[118:121]
	v_mfma_f32_16x16x32_bf16 v[110:113], v[176:179], v[138:141], v[110:113]
	v_mfma_f32_16x16x32_bf16 v[102:105], v[184:187], v[138:141], v[102:105]
	v_mfma_f32_16x16x32_bf16 v[126:129], v[164:167], v[148:151], v[126:129]
	v_mfma_f32_16x16x32_bf16 v[122:125], v[160:163], v[156:159], v[122:125]
	v_mfma_f32_16x16x32_bf16 v[118:121], v[172:175], v[148:151], v[118:121]
	v_mfma_f32_16x16x32_bf16 v[114:117], v[168:171], v[156:159], v[114:117]
	v_mfma_f32_16x16x32_bf16 v[110:113], v[180:183], v[148:151], v[110:113]
	v_mfma_f32_16x16x32_bf16 v[106:109], v[176:179], v[156:159], v[106:109]
	v_mfma_f32_16x16x32_bf16 v[102:105], v[188:191], v[148:151], v[102:105]
	v_mfma_f32_16x16x32_bf16 v[98:101], v[184:187], v[156:159], v[98:101]
	v_mfma_f32_16x16x32_bf16 v[142:145], v[164:167], v[152:155], v[122:125]
	v_mfma_f32_16x16x32_bf16 v[192:195], v[172:175], v[152:155], v[114:117]
	v_mfma_f32_16x16x32_bf16 v[196:199], v[180:183], v[152:155], v[106:109]
	v_mfma_f32_16x16x32_bf16 v[200:203], v[188:191], v[152:155], v[98:101]
	s_barrier
	s_nop 1
	ds_read_b128 v[98:101], v147
	ds_read_b128 v[106:109], v147 offset:1024
	ds_read_b128 v[114:117], v147 offset:2048
	ds_read_b128 v[122:125], v147 offset:3072
	s_barrier
	s_waitcnt lgkmcnt(0)
	v_mfma_f32_16x16x32_bf16 v[94:97], v[160:163], v[98:101], v[94:97]
	v_mfma_f32_16x16x32_bf16 v[90:93], v[160:163], v[114:117], v[90:93]
	v_mfma_f32_16x16x32_bf16 v[86:89], v[168:171], v[98:101], v[86:89]
	v_mfma_f32_16x16x32_bf16 v[82:85], v[168:171], v[114:117], v[82:85]
	v_mfma_f32_16x16x32_bf16 v[78:81], v[176:179], v[98:101], v[78:81]
	v_mfma_f32_16x16x32_bf16 v[74:77], v[176:179], v[114:117], v[74:77]
	v_mfma_f32_16x16x32_bf16 v[70:73], v[184:187], v[98:101], v[70:73]
	v_mfma_f32_16x16x32_bf16 v[66:69], v[184:187], v[114:117], v[66:69]
	v_mfma_f32_16x16x32_bf16 v[94:97], v[164:167], v[106:109], v[94:97]
	v_mfma_f32_16x16x32_bf16 v[90:93], v[164:167], v[122:125], v[90:93]
	v_mfma_f32_16x16x32_bf16 v[86:89], v[172:175], v[106:109], v[86:89]
	v_mfma_f32_16x16x32_bf16 v[82:85], v[172:175], v[122:125], v[82:85]
	v_mfma_f32_16x16x32_bf16 v[78:81], v[180:183], v[106:109], v[78:81]
	v_mfma_f32_16x16x32_bf16 v[74:77], v[180:183], v[122:125], v[74:77]
	v_mfma_f32_16x16x32_bf16 v[70:73], v[188:191], v[106:109], v[70:73]
	v_mfma_f32_16x16x32_bf16 v[66:69], v[188:191], v[122:125], v[66:69]
	s_barrier
	ds_read_b128 v[160:163], v133 offset:16384
	ds_read_b128 v[164:167], v133 offset:17408
	ds_read_b128 v[168:171], v132 offset:16384
	ds_read_b128 v[172:175], v132 offset:17408
	ds_read_b128 v[176:179], v131 offset:16384
	ds_read_b128 v[180:183], v131 offset:17408
	ds_read_b128 v[184:187], v130 offset:16384
	ds_read_b128 v[188:191], v130 offset:17408
	s_waitcnt vmcnt(4)
	s_barrier
; #define WAIT_V(n) asm volatile("s_waitcnt vmcnt(" #n ")" ::: "memory")
; #define WAIT_L(n) asm volatile("s_waitcnt lgkmcnt(" #n ")" ::: "memory")
; #define BAR __builtin_amdgcn_s_barrier()
; __device__ __forceinline__ void mainloop_8phase(const u16* __restrict__ A, const u16* __restrict__ Bt, int K,
;                                                 f32x4 (&acc)[2][2][4][2], int wid_s, int ld) {
;     ...
;     LDA(At, 0, 1); WAIT_V(4); BAR; WAIT_L(0); MMA(1, 0, At, B0); MMA(1, 1, At, B1); BAR; }
;   { LDB(B0, 1, 0); LDA(At, 1, 0); WAIT_V(2); BAR; WAIT_L(0); MMA(0, 0, At, B0); BAR;
	s_waitcnt lgkmcnt(0)
	v_mfma_f32_16x16x32_bf16 v[62:65], v[160:163], v[138:141], v[62:65]
	v_mfma_f32_16x16x32_bf16 v[58:61], v[160:163], v[156:159], v[58:61]
	v_mfma_f32_16x16x32_bf16 v[54:57], v[168:171], v[138:141], v[54:57]
	v_mfma_f32_16x16x32_bf16 v[50:53], v[168:171], v[156:159], v[50:53]
	v_mfma_f32_16x16x32_bf16 v[46:49], v[176:179], v[138:141], v[46:49]
	v_mfma_f32_16x16x32_bf16 v[42:45], v[176:179], v[156:159], v[42:45]
	v_mfma_f32_16x16x32_bf16 v[38:41], v[184:187], v[138:141], v[38:41]
	v_mfma_f32_16x16x32_bf16 v[34:37], v[184:187], v[156:159], v[34:37]
	v_mfma_f32_16x16x32_bf16 v[204:207], v[164:167], v[148:151], v[62:65]
	v_mfma_f32_16x16x32_bf16 v[208:211], v[164:167], v[152:155], v[58:61]
	v_mfma_f32_16x16x32_bf16 v[212:215], v[172:175], v[148:151], v[54:57]
	v_mfma_f32_16x16x32_bf16 v[216:219], v[172:175], v[152:155], v[50:53]
	v_mfma_f32_16x16x32_bf16 v[220:223], v[180:183], v[148:151], v[46:49]
	v_mfma_f32_16x16x32_bf16 v[224:227], v[180:183], v[152:155], v[42:45]
	v_mfma_f32_16x16x32_bf16 v[138:141], v[188:191], v[148:151], v[38:41]
	v_mfma_f32_16x16x32_bf16 v[146:149], v[188:191], v[152:155], v[34:37]
	v_mfma_f32_16x16x32_bf16 v[30:33], v[160:163], v[98:101], v[30:33]
	v_mfma_f32_16x16x32_bf16 v[22:25], v[168:171], v[98:101], v[22:25]
	v_mfma_f32_16x16x32_bf16 v[14:17], v[176:179], v[98:101], v[14:17]
	v_mfma_f32_16x16x32_bf16 v[6:9], v[184:187], v[98:101], v[6:9]
	v_mfma_f32_16x16x32_bf16 v[30:33], v[164:167], v[106:109], v[30:33]
	v_mfma_f32_16x16x32_bf16 v[26:29], v[160:163], v[114:117], v[26:29]
	v_mfma_f32_16x16x32_bf16 v[22:25], v[172:175], v[106:109], v[22:25]
	v_mfma_f32_16x16x32_bf16 v[18:21], v[168:171], v[114:117], v[18:21]
	v_mfma_f32_16x16x32_bf16 v[14:17], v[180:183], v[106:109], v[14:17]
	v_mfma_f32_16x16x32_bf16 v[10:13], v[176:179], v[114:117], v[10:13]
	v_mfma_f32_16x16x32_bf16 v[6:9], v[188:191], v[106:109], v[6:9]
	v_mfma_f32_16x16x32_bf16 v[2:5], v[184:187], v[114:117], v[2:5]
	v_mfma_f32_16x16x32_bf16 v[150:153], v[164:167], v[122:125], v[26:29]
	v_mfma_f32_16x16x32_bf16 v[154:157], v[172:175], v[122:125], v[18:21]
	v_mfma_f32_16x16x32_bf16 v[158:161], v[180:183], v[122:125], v[10:13]
	v_mfma_f32_16x16x32_bf16 v[162:165], v[188:191], v[122:125], v[2:5]
	s_barrier
	s_nop 1
	ds_read_b128 v[2:5], v137
	ds_read_b128 v[166:169], v137 offset:1024
	ds_read_b128 v[170:173], v137 offset:2048
	ds_read_b128 v[174:177], v137 offset:3072
	ds_read_b128 v[10:13], v133 offset:32768
	ds_read_b128 v[18:21], v133 offset:33792
	ds_read_b128 v[26:29], v132 offset:32768
	ds_read_b128 v[38:41], v132 offset:33792
	ds_read_b128 v[46:49], v131 offset:32768
	ds_read_b128 v[178:181], v131 offset:33792
	ds_read_b128 v[182:185], v130 offset:32768
	ds_read_b128 v[186:189], v130 offset:33792
	s_waitcnt vmcnt(2)
	s_barrier
	s_waitcnt lgkmcnt(0)
	v_mfma_f32_16x16x32_bf16 v[34:37], v[10:13], v[2:5], v[126:129]
	v_mfma_f32_16x16x32_bf16 v[122:125], v[18:21], v[166:169], v[34:37]
	v_mfma_f32_16x16x32_bf16 v[34:37], v[10:13], v[170:173], v[142:145]
	v_mfma_f32_16x16x32_bf16 v[58:61], v[18:21], v[174:177], v[34:37]
	v_mfma_f32_16x16x32_bf16 v[34:37], v[26:29], v[2:5], v[118:121]
	v_mfma_f32_16x16x32_bf16 v[114:117], v[38:41], v[166:169], v[34:37]
	v_mfma_f32_16x16x32_bf16 v[34:37], v[26:29], v[170:173], v[192:195]
	v_mfma_f32_16x16x32_bf16 v[50:53], v[38:41], v[174:177], v[34:37]
	v_mfma_f32_16x16x32_bf16 v[34:37], v[46:49], v[2:5], v[110:113]
	v_mfma_f32_16x16x32_bf16 v[106:109], v[178:181], v[166:169], v[34:37]
	v_mfma_f32_16x16x32_bf16 v[34:37], v[46:49], v[170:173], v[196:199]
	v_mfma_f32_16x16x32_bf16 v[42:45], v[178:181], v[174:177], v[34:37]
	v_mfma_f32_16x16x32_bf16 v[34:37], v[182:185], v[2:5], v[102:105]
	v_mfma_f32_16x16x32_bf16 v[98:101], v[186:189], v[166:169], v[34:37]
	v_mfma_f32_16x16x32_bf16 v[34:37], v[182:185], v[170:173], v[200:203]
	v_mfma_f32_16x16x32_bf16 v[34:37], v[186:189], v[174:177], v[34:37]
	s_barrier
; #define WAIT_V(n) asm volatile("s_waitcnt vmcnt(" #n ")" ::: "memory")
; #define WAIT_L(n) asm volatile("s_waitcnt lgkmcnt(" #n ")" ::: "memory")
; #define BAR __builtin_amdgcn_s_barrier()
; __device__ __forceinline__ void mainloop_8phase(const u16* __restrict__ A, const u16* __restrict__ Bt, int K,
;                                                 f32x4 (&acc)[2][2][4][2], int wid_s, int ld) {
;     ...
;   { LDB(B0, 1, 0); LDA(At, 1, 0); WAIT_V(2); BAR; WAIT_L(0); MMA(0, 0, At, B0); BAR;
;     LDB(B1, 1, 1); WAIT_V(0); BAR; WAIT_L(0); MMA(0, 1, At, B1); BAR;
;     LDA(At, 1, 1); BAR; WAIT_L(0); MMA(1, 0, At, B0); MMA(1, 1, At, B1); BAR; }
;   if (wr == 0) BAR;
	ds_read_b128 v[142:145], v134
	ds_read_b128 v[190:193], v134 offset:1024
	ds_read_b128 v[194:197], v134 offset:2048
	ds_read_b128 v[134:137], v134 offset:3072
	s_waitcnt vmcnt(0)
	s_barrier
	s_waitcnt lgkmcnt(0)
	v_mfma_f32_16x16x32_bf16 v[54:57], v[10:13], v[142:145], v[94:97]
	v_mfma_f32_16x16x32_bf16 v[10:13], v[10:13], v[194:197], v[90:93]
	v_mfma_f32_16x16x32_bf16 v[62:65], v[18:21], v[134:137], v[10:13]
	v_mfma_f32_16x16x32_bf16 v[10:13], v[26:29], v[142:145], v[86:89]
	v_mfma_f32_16x16x32_bf16 v[118:121], v[38:41], v[190:193], v[10:13]
	v_mfma_f32_16x16x32_bf16 v[10:13], v[26:29], v[194:197], v[82:85]
	v_mfma_f32_16x16x32_bf16 v[126:129], v[18:21], v[190:193], v[54:57]
	v_mfma_f32_16x16x32_bf16 v[54:57], v[38:41], v[134:137], v[10:13]
	v_mfma_f32_16x16x32_bf16 v[10:13], v[46:49], v[142:145], v[78:81]
	v_mfma_f32_16x16x32_bf16 v[110:113], v[178:181], v[190:193], v[10:13]
	v_mfma_f32_16x16x32_bf16 v[10:13], v[46:49], v[194:197], v[74:77]
	v_mfma_f32_16x16x32_bf16 v[46:49], v[178:181], v[134:137], v[10:13]
	v_mfma_f32_16x16x32_bf16 v[10:13], v[182:185], v[142:145], v[70:73]
	v_mfma_f32_16x16x32_bf16 v[102:105], v[186:189], v[190:193], v[10:13]
	v_mfma_f32_16x16x32_bf16 v[10:13], v[182:185], v[194:197], v[66:69]
	v_mfma_f32_16x16x32_bf16 v[38:41], v[186:189], v[134:137], v[10:13]
	s_barrier
	ds_read_b128 v[66:69], v133 offset:49152
	ds_read_b128 v[78:81], v133 offset:50176
	ds_read_b128 v[178:181], v132 offset:49152
	ds_read_b128 v[182:185], v132 offset:50176
	ds_read_b128 v[186:189], v131 offset:49152
	ds_read_b128 v[198:201], v131 offset:50176
	ds_read_b128 v[228:231], v130 offset:49152
	ds_read_b128 v[130:133], v130 offset:50176
	s_barrier
	s_waitcnt lgkmcnt(0)
	v_mfma_f32_16x16x32_bf16 v[10:13], v[66:69], v[2:5], v[204:207]
	v_mfma_f32_16x16x32_bf16 v[90:93], v[78:81], v[166:169], v[10:13]
	v_mfma_f32_16x16x32_bf16 v[10:13], v[66:69], v[170:173], v[208:211]
	v_mfma_f32_16x16x32_bf16 v[26:29], v[78:81], v[174:177], v[10:13]
	v_mfma_f32_16x16x32_bf16 v[10:13], v[178:181], v[2:5], v[212:215]
	v_mfma_f32_16x16x32_bf16 v[82:85], v[182:185], v[166:169], v[10:13]
	v_mfma_f32_16x16x32_bf16 v[10:13], v[178:181], v[170:173], v[216:219]
	v_mfma_f32_16x16x32_bf16 v[18:21], v[182:185], v[174:177], v[10:13]
	v_mfma_f32_16x16x32_bf16 v[10:13], v[186:189], v[2:5], v[220:223]
	v_mfma_f32_16x16x32_bf16 v[2:5], v[228:231], v[2:5], v[138:141]
	v_mfma_f32_16x16x32_bf16 v[74:77], v[198:201], v[166:169], v[10:13]
	v_mfma_f32_16x16x32_bf16 v[10:13], v[186:189], v[170:173], v[224:227]
	v_mfma_f32_16x16x32_bf16 v[70:73], v[130:133], v[166:169], v[2:5]
	v_mfma_f32_16x16x32_bf16 v[2:5], v[228:231], v[170:173], v[146:149]
	v_mfma_f32_16x16x32_bf16 v[10:13], v[198:201], v[174:177], v[10:13]
	v_mfma_f32_16x16x32_bf16 v[2:5], v[130:133], v[174:177], v[2:5]
	v_mfma_f32_16x16x32_bf16 v[30:33], v[66:69], v[142:145], v[30:33]
	v_mfma_f32_16x16x32_bf16 v[94:97], v[78:81], v[190:193], v[30:33]
	v_mfma_f32_16x16x32_bf16 v[30:33], v[66:69], v[194:197], v[150:153]
	v_mfma_f32_16x16x32_bf16 v[22:25], v[178:181], v[142:145], v[22:25]
	v_mfma_f32_16x16x32_bf16 v[14:17], v[186:189], v[142:145], v[14:17]
	v_mfma_f32_16x16x32_bf16 v[6:9], v[228:231], v[142:145], v[6:9]
	v_mfma_f32_16x16x32_bf16 v[30:33], v[78:81], v[134:137], v[30:33]
	v_mfma_f32_16x16x32_bf16 v[86:89], v[182:185], v[190:193], v[22:25]
	v_mfma_f32_16x16x32_bf16 v[22:25], v[178:181], v[194:197], v[154:157]
	v_mfma_f32_16x16x32_bf16 v[78:81], v[198:201], v[190:193], v[14:17]
	v_mfma_f32_16x16x32_bf16 v[14:17], v[186:189], v[194:197], v[158:161]
	v_mfma_f32_16x16x32_bf16 v[66:69], v[130:133], v[190:193], v[6:9]
	v_mfma_f32_16x16x32_bf16 v[6:9], v[228:231], v[194:197], v[162:165]
	v_mfma_f32_16x16x32_bf16 v[22:25], v[182:185], v[134:137], v[22:25]
	v_mfma_f32_16x16x32_bf16 v[14:17], v[198:201], v[134:137], v[14:17]
	v_mfma_f32_16x16x32_bf16 v[6:9], v[130:133], v[134:137], v[6:9]
	s_movk_i32 s1, 0x100
	v_cmp_gt_u32_e32 vcc, s1, v0
	s_barrier
	s_and_saveexec_b64 s[2:3], vcc
	s_cbranch_execz .LBB0_345
	s_barrier

; #define WAIT_V(n) asm volatile("s_waitcnt vmcnt(" #n ")" ::: "memory")
; #define WAIT_L(n) asm volatile("s_waitcnt lgkmcnt(" #n ")" ::: "memory")
; #define BAR __builtin_amdgcn_s_barrier()
; #define SCHED __builtin_amdgcn_sched_barrier(0)
; __device__ __forceinline__ void mainloop_8phase(const u16* __restrict__ A, const u16* __restrict__ Bt, int K,
;                                                 f32x4 (&acc)[2][2][4][2], int wid_s, int ld) {
;     ...
;     LDB(B0, 0, 0); SCHED; LDA(At, 0, 0); STAGE(SA(1, 1), A, brow + G_HALF, t + 1);
;     WAIT_L(8); BAR; WAIT_L(0); MMA(0, 0, At, B0); BAR; SCHED;
;     LDB(B1, 0, 1); STAGE(SB(0, 0), Bt, bcol, t + 2);
;     BAR; WAIT_L(0); MMA(0, 1, At, B1); BAR;
;     LDA(At, 0, 1); STAGE(SA(0, 0), A, brow, t + 2);
;     BAR; WAIT_L(0); MMA(1, 0, At, B0); BAR; SCHED;
;     STAGE(SB(0, 1), Bt, bcol + G_HALF, t + 2);
;     WAIT_V(6); BAR; MMA(1, 1, At, B1); BAR;
.LBB0_565:
	ds_read_b128 v[158:161], v156
	ds_read_b128 v[162:165], v156 offset:1024
	ds_read_b128 v[166:169], v156 offset:2048
	ds_read_b128 v[170:173], v156 offset:3072
	s_add_i32 s15, s27, s3
	s_add_i32 s6, s15, 0x80
	s_add_i32 m0, s100, 0xc000
	ds_read_b128 v[174:177], v134
	ds_read_b128 v[178:181], v134 offset:1024
	ds_read_b128 v[182:185], v133
	ds_read_b128 v[186:189], v133 offset:1024
	ds_read_b128 v[190:193], v132
	ds_read_b128 v[194:197], v132 offset:1024
	ds_read_b128 v[198:201], v131
	buffer_load_dwordx4 v137, s[76:79], s6 offen lds
	s_add_i32 m0, s100, 0xe000
	ds_read_b128 v[202:205], v131 offset:1024
	buffer_load_dwordx4 v138, s[76:79], s6 offen lds
	s_waitcnt lgkmcnt(8)
	s_barrier
	s_waitcnt lgkmcnt(1)
	v_mfma_f32_16x16x32_bf16 v[126:129], v[174:177], v[158:161], v[126:129]
	v_mfma_f32_16x16x32_bf16 v[122:125], v[174:177], v[166:169], v[122:125]
	v_mfma_f32_16x16x32_bf16 v[118:121], v[182:185], v[158:161], v[118:121]
	v_mfma_f32_16x16x32_bf16 v[114:117], v[182:185], v[166:169], v[114:117]
	v_mfma_f32_16x16x32_bf16 v[110:113], v[190:193], v[158:161], v[110:113]
	v_mfma_f32_16x16x32_bf16 v[106:109], v[190:193], v[166:169], v[106:109]
	v_mfma_f32_16x16x32_bf16 v[102:105], v[198:201], v[158:161], v[102:105]
	v_mfma_f32_16x16x32_bf16 v[98:101], v[198:201], v[166:169], v[98:101]
	v_mfma_f32_16x16x32_bf16 v[126:129], v[178:181], v[162:165], v[126:129]
	v_mfma_f32_16x16x32_bf16 v[122:125], v[178:181], v[170:173], v[122:125]
	v_mfma_f32_16x16x32_bf16 v[118:121], v[186:189], v[162:165], v[118:121]
	v_mfma_f32_16x16x32_bf16 v[114:117], v[186:189], v[170:173], v[114:117]
	v_mfma_f32_16x16x32_bf16 v[110:113], v[194:197], v[162:165], v[110:113]
	v_mfma_f32_16x16x32_bf16 v[106:109], v[194:197], v[170:173], v[106:109]
	s_waitcnt lgkmcnt(0)
	v_mfma_f32_16x16x32_bf16 v[102:105], v[202:205], v[162:165], v[102:105]
	v_mfma_f32_16x16x32_bf16 v[98:101], v[202:205], v[170:173], v[98:101]
	s_barrier
	s_add_i32 s14, s3, 0x100
	s_mov_b32 s6, s78
	s_mov_b32 s7, s79
	s_add_i32 m0, s100, 0x10000
	ds_read_b128 v[206:209], v148
	ds_read_b128 v[210:213], v148 offset:1024
	ds_read_b128 v[214:217], v148 offset:2048
	ds_read_b128 v[218:221], v148 offset:3072
	buffer_load_dwordx4 v137, s[4:7], s14 offen lds
	s_add_i32 m0, s100, 0x12000
	s_add_i32 s2, s2, 2
	buffer_load_dwordx4 v138, s[4:7], s14 offen lds
	s_barrier
	s_waitcnt lgkmcnt(0)
	v_mfma_f32_16x16x32_bf16 v[94:97], v[174:177], v[206:209], v[94:97]
	v_mfma_f32_16x16x32_bf16 v[90:93], v[174:177], v[214:217], v[90:93]
	v_mfma_f32_16x16x32_bf16 v[86:89], v[182:185], v[206:209], v[86:89]
	v_mfma_f32_16x16x32_bf16 v[82:85], v[182:185], v[214:217], v[82:85]
	v_mfma_f32_16x16x32_bf16 v[78:81], v[190:193], v[206:209], v[78:81]
	v_mfma_f32_16x16x32_bf16 v[74:77], v[190:193], v[214:217], v[74:77]
	v_mfma_f32_16x16x32_bf16 v[70:73], v[198:201], v[206:209], v[70:73]
	v_mfma_f32_16x16x32_bf16 v[66:69], v[198:201], v[214:217], v[66:69]
	v_mfma_f32_16x16x32_bf16 v[94:97], v[178:181], v[210:213], v[94:97]
	v_mfma_f32_16x16x32_bf16 v[90:93], v[178:181], v[218:221], v[90:93]
	v_mfma_f32_16x16x32_bf16 v[86:89], v[186:189], v[210:213], v[86:89]
	v_mfma_f32_16x16x32_bf16 v[82:85], v[186:189], v[218:221], v[82:85]
	v_mfma_f32_16x16x32_bf16 v[78:81], v[194:197], v[210:213], v[78:81]
	v_mfma_f32_16x16x32_bf16 v[74:77], v[194:197], v[218:221], v[74:77]
	v_mfma_f32_16x16x32_bf16 v[70:73], v[202:205], v[210:213], v[70:73]
	v_mfma_f32_16x16x32_bf16 v[66:69], v[202:205], v[218:221], v[66:69]
	s_mov_b32 m0, s100
	s_barrier
	ds_read_b128 v[174:177], v134 offset:16384
	ds_read_b128 v[178:181], v134 offset:17408
	ds_read_b128 v[182:185], v133 offset:16384
	ds_read_b128 v[186:189], v133 offset:17408
	ds_read_b128 v[190:193], v132 offset:16384
	ds_read_b128 v[194:197], v132 offset:17408
	ds_read_b128 v[198:201], v131 offset:16384
	buffer_load_dwordx4 v137, s[76:79], s14 offen lds
	s_add_i32 m0, s100, 0x2000
	ds_read_b128 v[202:205], v131 offset:17408
	buffer_load_dwordx4 v138, s[76:79], s14 offen lds
	s_barrier
	s_waitcnt lgkmcnt(1)
	v_mfma_f32_16x16x32_bf16 v[62:65], v[174:177], v[158:161], v[62:65]
	v_mfma_f32_16x16x32_bf16 v[58:61], v[174:177], v[166:169], v[58:61]
	v_mfma_f32_16x16x32_bf16 v[54:57], v[182:185], v[158:161], v[54:57]
	v_mfma_f32_16x16x32_bf16 v[50:53], v[182:185], v[166:169], v[50:53]
	v_mfma_f32_16x16x32_bf16 v[46:49], v[190:193], v[158:161], v[46:49]
	v_mfma_f32_16x16x32_bf16 v[42:45], v[190:193], v[166:169], v[42:45]
	v_mfma_f32_16x16x32_bf16 v[38:41], v[198:201], v[158:161], v[38:41]
	v_mfma_f32_16x16x32_bf16 v[34:37], v[198:201], v[166:169], v[34:37]
	v_mfma_f32_16x16x32_bf16 v[62:65], v[178:181], v[162:165], v[62:65]
	v_mfma_f32_16x16x32_bf16 v[58:61], v[178:181], v[170:173], v[58:61]
	v_mfma_f32_16x16x32_bf16 v[54:57], v[186:189], v[162:165], v[54:57]
	v_mfma_f32_16x16x32_bf16 v[50:53], v[186:189], v[170:173], v[50:53]
	v_mfma_f32_16x16x32_bf16 v[46:49], v[194:197], v[162:165], v[46:49]
	v_mfma_f32_16x16x32_bf16 v[42:45], v[194:197], v[170:173], v[42:45]
	s_waitcnt lgkmcnt(0)
	v_mfma_f32_16x16x32_bf16 v[38:41], v[202:205], v[162:165], v[38:41]
	v_mfma_f32_16x16x32_bf16 v[34:37], v[202:205], v[170:173], v[34:37]
	s_barrier
	s_add_i32 s34, s15, 0x100
	s_add_i32 m0, s100, 0x14000
	buffer_load_dwordx4 v137, s[4:7], s34 offen lds
	s_add_i32 m0, s100, 0x16000
	s_nop 0
	buffer_load_dwordx4 v138, s[4:7], s34 offen lds
	s_waitcnt vmcnt(6)
	s_barrier
; #define WAIT_V(n) asm volatile("s_waitcnt vmcnt(" #n ")" ::: "memory")
; #define WAIT_L(n) asm volatile("s_waitcnt lgkmcnt(" #n ")" ::: "memory")
; #define BAR __builtin_amdgcn_s_barrier()
; #define SCHED __builtin_amdgcn_sched_barrier(0)
; __device__ __forceinline__ void mainloop_8phase(const u16* __restrict__ A, const u16* __restrict__ Bt, int K,
;                                                 f32x4 (&acc)[2][2][4][2], int wid_s, int ld) {
;     ...
;     LDB(B0, 1, 0); SCHED; LDA(At, 1, 0); STAGE(SA(0, 1), A, brow + G_HALF, t + 2);
;     WAIT_L(8); BAR; WAIT_L(0); MMA(0, 0, At, B0); BAR; SCHED;
;     LDB(B1, 1, 1); STAGE(SB(1, 0), Bt, bcol, t + 3);
;     BAR; WAIT_L(0); MMA(0, 1, At, B1); BAR;
;     LDA(At, 1, 1); STAGE(SA(1, 0), A, brow, t + 3);
;     BAR; WAIT_L(0); MMA(1, 0, At, B0); BAR; SCHED;
;     STAGE(SB(1, 1), Bt, bcol + G_HALF, t + 3);
;     WAIT_V(6); BAR; MMA(1, 1, At, B1); BAR;
	v_mfma_f32_16x16x32_bf16 v[30:33], v[174:177], v[206:209], v[30:33]
	v_mfma_f32_16x16x32_bf16 v[26:29], v[174:177], v[214:217], v[26:29]
	v_mfma_f32_16x16x32_bf16 v[22:25], v[182:185], v[206:209], v[22:25]
	v_mfma_f32_16x16x32_bf16 v[18:21], v[182:185], v[214:217], v[18:21]
	v_mfma_f32_16x16x32_bf16 v[14:17], v[190:193], v[206:209], v[14:17]
	v_mfma_f32_16x16x32_bf16 v[10:13], v[190:193], v[214:217], v[10:13]
	v_mfma_f32_16x16x32_bf16 v[6:9], v[198:201], v[206:209], v[6:9]
	v_mfma_f32_16x16x32_bf16 v[2:5], v[198:201], v[214:217], v[2:5]
	v_mfma_f32_16x16x32_bf16 v[30:33], v[178:181], v[210:213], v[30:33]
	v_mfma_f32_16x16x32_bf16 v[26:29], v[178:181], v[218:221], v[26:29]
	v_mfma_f32_16x16x32_bf16 v[22:25], v[186:189], v[210:213], v[22:25]
	v_mfma_f32_16x16x32_bf16 v[18:21], v[186:189], v[218:221], v[18:21]
	v_mfma_f32_16x16x32_bf16 v[14:17], v[194:197], v[210:213], v[14:17]
	v_mfma_f32_16x16x32_bf16 v[10:13], v[194:197], v[218:221], v[10:13]
	v_mfma_f32_16x16x32_bf16 v[6:9], v[202:205], v[210:213], v[6:9]
	v_mfma_f32_16x16x32_bf16 v[2:5], v[202:205], v[218:221], v[2:5]
	s_barrier
	ds_read_b128 v[158:161], v136
	ds_read_b128 v[162:165], v136 offset:1024
	ds_read_b128 v[166:169], v136 offset:2048
	ds_read_b128 v[170:173], v136 offset:3072
	s_add_i32 m0, s100, 0x4000
	ds_read_b128 v[174:177], v134 offset:32768
	ds_read_b128 v[178:181], v134 offset:33792
	ds_read_b128 v[182:185], v133 offset:32768
	ds_read_b128 v[186:189], v133 offset:33792
	ds_read_b128 v[190:193], v132 offset:32768
	ds_read_b128 v[194:197], v132 offset:33792
	ds_read_b128 v[198:201], v131 offset:32768
	buffer_load_dwordx4 v137, s[76:79], s34 offen lds
	s_add_i32 m0, s100, 0x6000
	ds_read_b128 v[202:205], v131 offset:33792
	buffer_load_dwordx4 v138, s[76:79], s34 offen lds
	s_waitcnt lgkmcnt(8)
	s_barrier
	s_waitcnt lgkmcnt(1)
	v_mfma_f32_16x16x32_bf16 v[126:129], v[174:177], v[158:161], v[126:129]
	v_mfma_f32_16x16x32_bf16 v[122:125], v[174:177], v[166:169], v[122:125]
	v_mfma_f32_16x16x32_bf16 v[118:121], v[182:185], v[158:161], v[118:121]
	v_mfma_f32_16x16x32_bf16 v[114:117], v[182:185], v[166:169], v[114:117]
	v_mfma_f32_16x16x32_bf16 v[110:113], v[190:193], v[158:161], v[110:113]
	v_mfma_f32_16x16x32_bf16 v[106:109], v[190:193], v[166:169], v[106:109]
	v_mfma_f32_16x16x32_bf16 v[102:105], v[198:201], v[158:161], v[102:105]
	v_mfma_f32_16x16x32_bf16 v[98:101], v[198:201], v[166:169], v[98:101]
	v_mfma_f32_16x16x32_bf16 v[126:129], v[178:181], v[162:165], v[126:129]
	v_mfma_f32_16x16x32_bf16 v[122:125], v[178:181], v[170:173], v[122:125]
	v_mfma_f32_16x16x32_bf16 v[118:121], v[186:189], v[162:165], v[118:121]
	v_mfma_f32_16x16x32_bf16 v[114:117], v[186:189], v[170:173], v[114:117]
	v_mfma_f32_16x16x32_bf16 v[110:113], v[194:197], v[162:165], v[110:113]
	v_mfma_f32_16x16x32_bf16 v[106:109], v[194:197], v[170:173], v[106:109]
	s_waitcnt lgkmcnt(0)
	v_mfma_f32_16x16x32_bf16 v[102:105], v[202:205], v[162:165], v[102:105]
	v_mfma_f32_16x16x32_bf16 v[98:101], v[202:205], v[170:173], v[98:101]
	s_barrier
	s_addk_i32 s3, 0x180
	s_add_i32 m0, s100, 0x18000
	ds_read_b128 v[206:209], v135
	ds_read_b128 v[210:213], v135 offset:1024
	ds_read_b128 v[214:217], v135 offset:2048
	buffer_load_dwordx4 v137, s[4:7], s3 offen lds
	s_add_i32 m0, s100, 0x1a000
	ds_read_b128 v[218:221], v135 offset:3072
	buffer_load_dwordx4 v138, s[4:7], s3 offen lds
	s_barrier
	s_waitcnt lgkmcnt(1)
	v_mfma_f32_16x16x32_bf16 v[94:97], v[174:177], v[206:209], v[94:97]
	v_mfma_f32_16x16x32_bf16 v[90:93], v[174:177], v[214:217], v[90:93]
	v_mfma_f32_16x16x32_bf16 v[86:89], v[182:185], v[206:209], v[86:89]
	v_mfma_f32_16x16x32_bf16 v[82:85], v[182:185], v[214:217], v[82:85]
	v_mfma_f32_16x16x32_bf16 v[78:81], v[190:193], v[206:209], v[78:81]
	v_mfma_f32_16x16x32_bf16 v[74:77], v[190:193], v[214:217], v[74:77]
	v_mfma_f32_16x16x32_bf16 v[70:73], v[198:201], v[206:209], v[70:73]
	v_mfma_f32_16x16x32_bf16 v[66:69], v[198:201], v[214:217], v[66:69]
	v_mfma_f32_16x16x32_bf16 v[94:97], v[178:181], v[210:213], v[94:97]
	s_waitcnt lgkmcnt(0)
	v_mfma_f32_16x16x32_bf16 v[90:93], v[178:181], v[218:221], v[90:93]
	v_mfma_f32_16x16x32_bf16 v[86:89], v[186:189], v[210:213], v[86:89]
	v_mfma_f32_16x16x32_bf16 v[82:85], v[186:189], v[218:221], v[82:85]
	v_mfma_f32_16x16x32_bf16 v[78:81], v[194:197], v[210:213], v[78:81]
	v_mfma_f32_16x16x32_bf16 v[74:77], v[194:197], v[218:221], v[74:77]
	v_mfma_f32_16x16x32_bf16 v[70:73], v[202:205], v[210:213], v[70:73]
	v_mfma_f32_16x16x32_bf16 v[66:69], v[202:205], v[218:221], v[66:69]
	s_add_i32 m0, s100, 0x8000
	s_barrier
	ds_read_b128 v[174:177], v134 offset:49152
	ds_read_b128 v[178:181], v134 offset:50176
	ds_read_b128 v[182:185], v133 offset:49152
	ds_read_b128 v[186:189], v133 offset:50176
	ds_read_b128 v[190:193], v132 offset:49152
	ds_read_b128 v[194:197], v132 offset:50176
	ds_read_b128 v[198:201], v131 offset:49152
	buffer_load_dwordx4 v137, s[76:79], s3 offen lds
	s_add_i32 m0, s100, 0xa000
	ds_read_b128 v[202:205], v131 offset:50176
	buffer_load_dwordx4 v138, s[76:79], s3 offen lds
	s_barrier
	s_waitcnt lgkmcnt(1)
	v_mfma_f32_16x16x32_bf16 v[62:65], v[174:177], v[158:161], v[62:65]
	v_mfma_f32_16x16x32_bf16 v[58:61], v[174:177], v[166:169], v[58:61]
	v_mfma_f32_16x16x32_bf16 v[54:57], v[182:185], v[158:161], v[54:57]
	v_mfma_f32_16x16x32_bf16 v[50:53], v[182:185], v[166:169], v[50:53]
	v_mfma_f32_16x16x32_bf16 v[46:49], v[190:193], v[158:161], v[46:49]
	v_mfma_f32_16x16x32_bf16 v[42:45], v[190:193], v[166:169], v[42:45]
	v_mfma_f32_16x16x32_bf16 v[38:41], v[198:201], v[158:161], v[38:41]
	v_mfma_f32_16x16x32_bf16 v[34:37], v[198:201], v[166:169], v[34:37]
	v_mfma_f32_16x16x32_bf16 v[62:65], v[178:181], v[162:165], v[62:65]
	v_mfma_f32_16x16x32_bf16 v[58:61], v[178:181], v[170:173], v[58:61]
	v_mfma_f32_16x16x32_bf16 v[54:57], v[186:189], v[162:165], v[54:57]
	v_mfma_f32_16x16x32_bf16 v[50:53], v[186:189], v[170:173], v[50:53]
	v_mfma_f32_16x16x32_bf16 v[46:49], v[194:197], v[162:165], v[46:49]
	v_mfma_f32_16x16x32_bf16 v[42:45], v[194:197], v[170:173], v[42:45]
	s_waitcnt lgkmcnt(0)
	v_mfma_f32_16x16x32_bf16 v[38:41], v[202:205], v[162:165], v[38:41]
	v_mfma_f32_16x16x32_bf16 v[34:37], v[202:205], v[170:173], v[34:37]
	s_barrier
; #define WAIT_V(n) asm volatile("s_waitcnt vmcnt(" #n ")" ::: "memory")
; #define WAIT_L(n) asm volatile("s_waitcnt lgkmcnt(" #n ")" ::: "memory")
; #define BAR __builtin_amdgcn_s_barrier()
; __device__ __forceinline__ void mainloop_8phase(const u16* __restrict__ A, const u16* __restrict__ Bt, int K,
;                                                 f32x4 (&acc)[2][2][4][2], int wid_s, int ld) {
;     ...
;     WAIT_V(6); BAR; MMA(1, 1, At, B1); BAR;
;   }
;   { LDB(B0, 0, 0); LDA(At, 0, 0); STAGE(SA(1, 1), A, brow + G_HALF, nt - 1);
;     BAR; WAIT_L(0); MMA(0, 0, At, B0); BAR;
;     LDB(B1, 0, 1); BAR; WAIT_L(0); MMA(0, 1, At, B1); BAR;
;     LDA(At, 0, 1); WAIT_V(4); BAR; WAIT_L(0); MMA(1, 0, At, B0); MMA(1, 1, At, B1); BAR; }
	s_addk_i32 s15, 0x180
	s_add_i32 m0, s100, 0x1c000
	buffer_load_dwordx4 v137, s[4:7], s15 offen lds
	s_add_i32 m0, s100, 0x1e000
	s_nop 0
	buffer_load_dwordx4 v138, s[4:7], s15 offen lds
	s_waitcnt vmcnt(6)
	s_barrier
	v_mfma_f32_16x16x32_bf16 v[30:33], v[174:177], v[206:209], v[30:33]
	v_mfma_f32_16x16x32_bf16 v[26:29], v[174:177], v[214:217], v[26:29]
	v_mfma_f32_16x16x32_bf16 v[22:25], v[182:185], v[206:209], v[22:25]
	v_mfma_f32_16x16x32_bf16 v[18:21], v[182:185], v[214:217], v[18:21]
	v_mfma_f32_16x16x32_bf16 v[14:17], v[190:193], v[206:209], v[14:17]
	v_mfma_f32_16x16x32_bf16 v[10:13], v[190:193], v[214:217], v[10:13]
	v_mfma_f32_16x16x32_bf16 v[6:9], v[198:201], v[206:209], v[6:9]
	v_mfma_f32_16x16x32_bf16 v[2:5], v[198:201], v[214:217], v[2:5]
	v_mfma_f32_16x16x32_bf16 v[30:33], v[178:181], v[210:213], v[30:33]
	v_mfma_f32_16x16x32_bf16 v[26:29], v[178:181], v[218:221], v[26:29]
	v_mfma_f32_16x16x32_bf16 v[22:25], v[186:189], v[210:213], v[22:25]
	v_mfma_f32_16x16x32_bf16 v[18:21], v[186:189], v[218:221], v[18:21]
	v_mfma_f32_16x16x32_bf16 v[14:17], v[194:197], v[210:213], v[14:17]
	v_mfma_f32_16x16x32_bf16 v[10:13], v[194:197], v[218:221], v[10:13]
	v_mfma_f32_16x16x32_bf16 v[6:9], v[202:205], v[210:213], v[6:9]
	v_mfma_f32_16x16x32_bf16 v[2:5], v[202:205], v[218:221], v[2:5]
	s_cmp_lt_u32 s2, s29
	s_mov_b32 s3, s14
	s_barrier
	s_cbranch_scc1 .LBB0_565
	v_readfirstlane_b32 s2, v146
	s_mov_b32 m0, s2
	v_readfirstlane_b32 s2, v145
	ds_read_b128 v[140:143], v156
	ds_read_b128 v[150:153], v156 offset:1024
	ds_read_b128 v[158:161], v156 offset:2048
	ds_read_b128 v[154:157], v156 offset:3072
	ds_read_b128 v[162:165], v134
	ds_read_b128 v[166:169], v134 offset:1024
	ds_read_b128 v[170:173], v133
	ds_read_b128 v[174:177], v133 offset:1024
	ds_read_b128 v[178:181], v132
	ds_read_b128 v[182:185], v132 offset:1024
	ds_read_b128 v[186:189], v131
	ds_read_b128 v[190:193], v131 offset:1024
	buffer_load_dwordx4 v137, s[76:79], s30 offen lds
	s_mov_b32 m0, s2
	s_nop 0
	buffer_load_dwordx4 v138, s[76:79], s30 offen lds
	s_barrier
	s_waitcnt lgkmcnt(0)
	v_mfma_f32_16x16x32_bf16 v[126:129], v[162:165], v[140:143], v[126:129]
	v_mfma_f32_16x16x32_bf16 v[118:121], v[170:173], v[140:143], v[118:121]
	v_mfma_f32_16x16x32_bf16 v[110:113], v[178:181], v[140:143], v[110:113]
	v_mfma_f32_16x16x32_bf16 v[102:105], v[186:189], v[140:143], v[102:105]
	v_mfma_f32_16x16x32_bf16 v[126:129], v[166:169], v[150:153], v[126:129]
	v_mfma_f32_16x16x32_bf16 v[122:125], v[162:165], v[158:161], v[122:125]
	v_mfma_f32_16x16x32_bf16 v[118:121], v[174:177], v[150:153], v[118:121]
	v_mfma_f32_16x16x32_bf16 v[114:117], v[170:173], v[158:161], v[114:117]
	v_mfma_f32_16x16x32_bf16 v[110:113], v[182:185], v[150:153], v[110:113]
	v_mfma_f32_16x16x32_bf16 v[106:109], v[178:181], v[158:161], v[106:109]
	v_mfma_f32_16x16x32_bf16 v[102:105], v[190:193], v[150:153], v[102:105]
	v_mfma_f32_16x16x32_bf16 v[98:101], v[186:189], v[158:161], v[98:101]
	v_mfma_f32_16x16x32_bf16 v[144:147], v[166:169], v[154:157], v[122:125]
	v_mfma_f32_16x16x32_bf16 v[194:197], v[174:177], v[154:157], v[114:117]
	v_mfma_f32_16x16x32_bf16 v[198:201], v[182:185], v[154:157], v[106:109]
	v_mfma_f32_16x16x32_bf16 v[202:205], v[190:193], v[154:157], v[98:101]
	s_barrier
	s_nop 1
	ds_read_b128 v[98:101], v148
	ds_read_b128 v[106:109], v148 offset:1024
	ds_read_b128 v[114:117], v148 offset:2048
	ds_read_b128 v[122:125], v148 offset:3072
	s_barrier
	s_waitcnt lgkmcnt(0)
	v_mfma_f32_16x16x32_bf16 v[94:97], v[162:165], v[98:101], v[94:97]
	v_mfma_f32_16x16x32_bf16 v[86:89], v[170:173], v[98:101], v[86:89]
	v_mfma_f32_16x16x32_bf16 v[78:81], v[178:181], v[98:101], v[78:81]
	v_mfma_f32_16x16x32_bf16 v[70:73], v[186:189], v[98:101], v[70:73]
	v_mfma_f32_16x16x32_bf16 v[94:97], v[166:169], v[106:109], v[94:97]
	v_mfma_f32_16x16x32_bf16 v[90:93], v[162:165], v[114:117], v[90:93]
	v_mfma_f32_16x16x32_bf16 v[86:89], v[174:177], v[106:109], v[86:89]
	v_mfma_f32_16x16x32_bf16 v[82:85], v[170:173], v[114:117], v[82:85]
	v_mfma_f32_16x16x32_bf16 v[78:81], v[182:185], v[106:109], v[78:81]
	v_mfma_f32_16x16x32_bf16 v[74:77], v[178:181], v[114:117], v[74:77]
	v_mfma_f32_16x16x32_bf16 v[70:73], v[190:193], v[106:109], v[70:73]
	v_mfma_f32_16x16x32_bf16 v[66:69], v[186:189], v[114:117], v[66:69]
	v_mfma_f32_16x16x32_bf16 v[162:165], v[166:169], v[122:125], v[90:93]
	v_mfma_f32_16x16x32_bf16 v[166:169], v[174:177], v[122:125], v[82:85]
	v_mfma_f32_16x16x32_bf16 v[170:173], v[182:185], v[122:125], v[74:77]
	v_mfma_f32_16x16x32_bf16 v[174:177], v[190:193], v[122:125], v[66:69]
	s_barrier
	s_nop 0
	ds_read_b128 v[66:69], v134 offset:16384
	ds_read_b128 v[74:77], v134 offset:17408
	ds_read_b128 v[82:85], v133 offset:16384
	ds_read_b128 v[90:93], v133 offset:17408
	ds_read_b128 v[178:181], v132 offset:16384
	ds_read_b128 v[182:185], v132 offset:17408
	ds_read_b128 v[186:189], v131 offset:16384
	ds_read_b128 v[190:193], v131 offset:17408
	s_waitcnt vmcnt(4)
	s_barrier
; #define WAIT_V(n) asm volatile("s_waitcnt vmcnt(" #n ")" ::: "memory")
; #define WAIT_L(n) asm volatile("s_waitcnt lgkmcnt(" #n ")" ::: "memory")
; #define BAR __builtin_amdgcn_s_barrier()
; __device__ __forceinline__ void mainloop_8phase(const u16* __restrict__ A, const u16* __restrict__ Bt, int K,
;                                                 f32x4 (&acc)[2][2][4][2], int wid_s, int ld) {
;     ...
;     LDA(At, 0, 1); WAIT_V(4); BAR; WAIT_L(0); MMA(1, 0, At, B0); MMA(1, 1, At, B1); BAR; }
;   { LDB(B0, 1, 0); LDA(At, 1, 0); WAIT_V(2); BAR; WAIT_L(0); MMA(0, 0, At, B0); BAR;
	s_waitcnt lgkmcnt(0)
	v_mfma_f32_16x16x32_bf16 v[62:65], v[66:69], v[140:143], v[62:65]
	v_mfma_f32_16x16x32_bf16 v[54:57], v[82:85], v[140:143], v[54:57]
	v_mfma_f32_16x16x32_bf16 v[46:49], v[178:181], v[140:143], v[46:49]
	v_mfma_f32_16x16x32_bf16 v[38:41], v[186:189], v[140:143], v[38:41]
	v_mfma_f32_16x16x32_bf16 v[62:65], v[74:77], v[150:153], v[62:65]
	v_mfma_f32_16x16x32_bf16 v[58:61], v[66:69], v[158:161], v[58:61]
	v_mfma_f32_16x16x32_bf16 v[54:57], v[90:93], v[150:153], v[54:57]
	v_mfma_f32_16x16x32_bf16 v[50:53], v[82:85], v[158:161], v[50:53]
	v_mfma_f32_16x16x32_bf16 v[46:49], v[182:185], v[150:153], v[46:49]
	v_mfma_f32_16x16x32_bf16 v[42:45], v[178:181], v[158:161], v[42:45]
	v_mfma_f32_16x16x32_bf16 v[38:41], v[190:193], v[150:153], v[38:41]
	v_mfma_f32_16x16x32_bf16 v[34:37], v[186:189], v[158:161], v[34:37]
	v_mfma_f32_16x16x32_bf16 v[206:209], v[74:77], v[154:157], v[58:61]
	v_mfma_f32_16x16x32_bf16 v[210:213], v[90:93], v[154:157], v[50:53]
	v_mfma_f32_16x16x32_bf16 v[214:217], v[182:185], v[154:157], v[42:45]
	v_mfma_f32_16x16x32_bf16 v[138:141], v[190:193], v[154:157], v[34:37]
	v_mfma_f32_16x16x32_bf16 v[30:33], v[66:69], v[98:101], v[30:33]
	v_mfma_f32_16x16x32_bf16 v[22:25], v[82:85], v[98:101], v[22:25]
	v_mfma_f32_16x16x32_bf16 v[14:17], v[178:181], v[98:101], v[14:17]
	v_mfma_f32_16x16x32_bf16 v[6:9], v[186:189], v[98:101], v[6:9]
	v_mfma_f32_16x16x32_bf16 v[30:33], v[74:77], v[106:109], v[30:33]
	v_mfma_f32_16x16x32_bf16 v[26:29], v[66:69], v[114:117], v[26:29]
	v_mfma_f32_16x16x32_bf16 v[22:25], v[90:93], v[106:109], v[22:25]
	v_mfma_f32_16x16x32_bf16 v[18:21], v[82:85], v[114:117], v[18:21]
	v_mfma_f32_16x16x32_bf16 v[14:17], v[182:185], v[106:109], v[14:17]
	v_mfma_f32_16x16x32_bf16 v[10:13], v[178:181], v[114:117], v[10:13]
	v_mfma_f32_16x16x32_bf16 v[6:9], v[190:193], v[106:109], v[6:9]
	v_mfma_f32_16x16x32_bf16 v[2:5], v[186:189], v[114:117], v[2:5]
	v_mfma_f32_16x16x32_bf16 v[148:151], v[74:77], v[122:125], v[26:29]
	v_mfma_f32_16x16x32_bf16 v[152:155], v[90:93], v[122:125], v[18:21]
	v_mfma_f32_16x16x32_bf16 v[156:159], v[182:185], v[122:125], v[10:13]
	v_mfma_f32_16x16x32_bf16 v[178:181], v[190:193], v[122:125], v[2:5]
	s_barrier
	s_nop 1
	ds_read_b128 v[2:5], v136
	ds_read_b128 v[10:13], v136 offset:1024
	ds_read_b128 v[18:21], v136 offset:2048
	ds_read_b128 v[26:29], v136 offset:3072
	ds_read_b128 v[34:37], v134 offset:32768
	ds_read_b128 v[42:45], v134 offset:33792
	ds_read_b128 v[50:53], v133 offset:32768
	ds_read_b128 v[58:61], v133 offset:33792
	ds_read_b128 v[66:69], v132 offset:32768
	ds_read_b128 v[182:185], v132 offset:33792
	ds_read_b128 v[186:189], v131 offset:32768
	ds_read_b128 v[190:193], v131 offset:33792
	s_waitcnt vmcnt(2)
	s_barrier
	s_waitcnt lgkmcnt(0)
	v_mfma_f32_16x16x32_bf16 v[74:77], v[34:37], v[2:5], v[126:129]
	v_mfma_f32_16x16x32_bf16 v[122:125], v[42:45], v[10:13], v[74:77]
	v_mfma_f32_16x16x32_bf16 v[74:77], v[34:37], v[18:21], v[144:147]
	v_mfma_f32_16x16x32_bf16 v[126:129], v[42:45], v[26:29], v[74:77]
	v_mfma_f32_16x16x32_bf16 v[74:77], v[50:53], v[2:5], v[118:121]
	v_mfma_f32_16x16x32_bf16 v[114:117], v[58:61], v[10:13], v[74:77]
	v_mfma_f32_16x16x32_bf16 v[74:77], v[50:53], v[18:21], v[194:197]
	v_mfma_f32_16x16x32_bf16 v[118:121], v[58:61], v[26:29], v[74:77]
	v_mfma_f32_16x16x32_bf16 v[74:77], v[66:69], v[2:5], v[110:113]
	v_mfma_f32_16x16x32_bf16 v[106:109], v[182:185], v[10:13], v[74:77]
	v_mfma_f32_16x16x32_bf16 v[74:77], v[66:69], v[18:21], v[198:201]
	v_mfma_f32_16x16x32_bf16 v[110:113], v[182:185], v[26:29], v[74:77]
	v_mfma_f32_16x16x32_bf16 v[74:77], v[186:189], v[2:5], v[102:105]
	v_mfma_f32_16x16x32_bf16 v[98:101], v[190:193], v[10:13], v[74:77]
	v_mfma_f32_16x16x32_bf16 v[74:77], v[186:189], v[18:21], v[202:205]
	v_mfma_f32_16x16x32_bf16 v[102:105], v[190:193], v[26:29], v[74:77]
	s_barrier
; #define WAIT_V(n) asm volatile("s_waitcnt vmcnt(" #n ")" ::: "memory")
; #define WAIT_L(n) asm volatile("s_waitcnt lgkmcnt(" #n ")" ::: "memory")
; #define BAR __builtin_amdgcn_s_barrier()
; __device__ __forceinline__ void mainloop_8phase(const u16* __restrict__ A, const u16* __restrict__ Bt, int K,
;                                                 f32x4 (&acc)[2][2][4][2], int wid_s, int ld) {
;     ...
;     LDB(B1, 1, 1); WAIT_V(0); BAR; WAIT_L(0); MMA(0, 1, At, B1); BAR;
;     LDA(At, 1, 1); BAR; WAIT_L(0); MMA(1, 0, At, B0); MMA(1, 1, At, B1); BAR; }
;   if (wr == 0) BAR;
	ds_read_b128 v[142:145], v135
	ds_read_b128 v[194:197], v135 offset:1024
	ds_read_b128 v[198:201], v135 offset:2048
	ds_read_b128 v[202:205], v135 offset:3072
	s_waitcnt vmcnt(0)
	s_barrier
	s_waitcnt lgkmcnt(0)
	v_mfma_f32_16x16x32_bf16 v[74:77], v[34:37], v[142:145], v[94:97]
	v_mfma_f32_16x16x32_bf16 v[34:37], v[34:37], v[198:201], v[162:165]
	v_mfma_f32_16x16x32_bf16 v[94:97], v[42:45], v[202:205], v[34:37]
	v_mfma_f32_16x16x32_bf16 v[34:37], v[50:53], v[142:145], v[86:89]
	v_mfma_f32_16x16x32_bf16 v[82:85], v[58:61], v[194:197], v[34:37]
	v_mfma_f32_16x16x32_bf16 v[34:37], v[50:53], v[198:201], v[166:169]
	v_mfma_f32_16x16x32_bf16 v[86:89], v[58:61], v[202:205], v[34:37]
	v_mfma_f32_16x16x32_bf16 v[34:37], v[66:69], v[142:145], v[78:81]
	v_mfma_f32_16x16x32_bf16 v[90:93], v[42:45], v[194:197], v[74:77]
	v_mfma_f32_16x16x32_bf16 v[74:77], v[182:185], v[194:197], v[34:37]
	v_mfma_f32_16x16x32_bf16 v[34:37], v[66:69], v[198:201], v[170:173]
	v_mfma_f32_16x16x32_bf16 v[78:81], v[182:185], v[202:205], v[34:37]
	v_mfma_f32_16x16x32_bf16 v[34:37], v[186:189], v[142:145], v[70:73]
	v_mfma_f32_16x16x32_bf16 v[66:69], v[190:193], v[194:197], v[34:37]
	v_mfma_f32_16x16x32_bf16 v[34:37], v[186:189], v[198:201], v[174:177]
	v_mfma_f32_16x16x32_bf16 v[70:73], v[190:193], v[202:205], v[34:37]
	s_barrier
	ds_read_b128 v[160:163], v134 offset:49152
	ds_read_b128 v[134:137], v134 offset:50176
	ds_read_b128 v[164:167], v133 offset:49152
	ds_read_b128 v[168:171], v133 offset:50176
	ds_read_b128 v[172:175], v132 offset:49152
	ds_read_b128 v[182:185], v132 offset:50176
	ds_read_b128 v[186:189], v131 offset:49152
	ds_read_b128 v[190:193], v131 offset:50176
	s_barrier
	s_waitcnt lgkmcnt(0)
	v_mfma_f32_16x16x32_bf16 v[34:37], v[160:163], v[2:5], v[62:65]
	v_mfma_f32_16x16x32_bf16 v[58:61], v[134:137], v[10:13], v[34:37]
	v_mfma_f32_16x16x32_bf16 v[34:37], v[160:163], v[18:21], v[206:209]
	v_mfma_f32_16x16x32_bf16 v[62:65], v[134:137], v[26:29], v[34:37]
	v_mfma_f32_16x16x32_bf16 v[34:37], v[164:167], v[2:5], v[54:57]
	v_mfma_f32_16x16x32_bf16 v[50:53], v[168:171], v[10:13], v[34:37]
	v_mfma_f32_16x16x32_bf16 v[34:37], v[164:167], v[18:21], v[210:213]
	v_mfma_f32_16x16x32_bf16 v[54:57], v[168:171], v[26:29], v[34:37]
	v_mfma_f32_16x16x32_bf16 v[34:37], v[172:175], v[2:5], v[46:49]
	v_mfma_f32_16x16x32_bf16 v[42:45], v[182:185], v[10:13], v[34:37]
	v_mfma_f32_16x16x32_bf16 v[34:37], v[172:175], v[18:21], v[214:217]
	v_mfma_f32_16x16x32_bf16 v[2:5], v[186:189], v[2:5], v[38:41]
	v_mfma_f32_16x16x32_bf16 v[46:49], v[182:185], v[26:29], v[34:37]
	v_mfma_f32_16x16x32_bf16 v[34:37], v[190:193], v[10:13], v[2:5]
	v_mfma_f32_16x16x32_bf16 v[2:5], v[186:189], v[18:21], v[138:141]
	v_mfma_f32_16x16x32_bf16 v[38:41], v[190:193], v[26:29], v[2:5]
	v_mfma_f32_16x16x32_bf16 v[2:5], v[160:163], v[142:145], v[30:33]
	v_mfma_f32_16x16x32_bf16 v[26:29], v[134:137], v[194:197], v[2:5]
	v_mfma_f32_16x16x32_bf16 v[2:5], v[160:163], v[198:201], v[148:151]
	v_mfma_f32_16x16x32_bf16 v[30:33], v[134:137], v[202:205], v[2:5]
	v_mfma_f32_16x16x32_bf16 v[2:5], v[164:167], v[142:145], v[22:25]
	v_mfma_f32_16x16x32_bf16 v[18:21], v[168:171], v[194:197], v[2:5]
	v_mfma_f32_16x16x32_bf16 v[2:5], v[164:167], v[198:201], v[152:155]
	v_mfma_f32_16x16x32_bf16 v[22:25], v[168:171], v[202:205], v[2:5]
	v_mfma_f32_16x16x32_bf16 v[2:5], v[172:175], v[142:145], v[14:17]
	v_mfma_f32_16x16x32_bf16 v[10:13], v[182:185], v[194:197], v[2:5]
	v_mfma_f32_16x16x32_bf16 v[2:5], v[172:175], v[198:201], v[156:159]
	v_mfma_f32_16x16x32_bf16 v[14:17], v[182:185], v[202:205], v[2:5]
	v_mfma_f32_16x16x32_bf16 v[2:5], v[186:189], v[142:145], v[6:9]
	v_mfma_f32_16x16x32_bf16 v[6:9], v[186:189], v[198:201], v[178:181]
	v_mfma_f32_16x16x32_bf16 v[2:5], v[190:193], v[194:197], v[2:5]
	v_mfma_f32_16x16x32_bf16 v[6:9], v[190:193], v[202:205], v[6:9]
	s_movk_i32 s2, 0x100
	v_cmp_gt_u32_e32 vcc, s2, v0
	s_barrier
	s_and_saveexec_b64 s[2:3], vcc
	s_cbranch_execz .LBB0_568
	s_barrier
